# hand-written GEMM phases (merge4, mlp1, mlp2, out-proj) with DMA burst after the barrier; S5 carry with batched prefetch
# speedup vs baseline: 1.0987x; 1.0510x over previous
; __device__ __forceinline__ int otid() { int t = threadIdx.x; asm volatile("" : "+v"(t)); return t; }
; __device__ void phase_s5_carry(CParams& p, int l, int item) {
;   int idx = item * 256 + otid();
;   int b = idx >> 11, dir = (idx >> 10) & 1, gp = idx & 1023;
;   float2 A = p.Apar[(l * 2 + dir) * 1024 + gp];
;   float ar = A.x, ai = A.y;
; #pragma unroll
;   for (int s = 0; s < 6; s++) { float nr = ar * ar - ai * ai, ni = 2.f * ar * ai; ar = nr; ai = ni; }
;   float hr = 0.f, hi = 0.f;
; #pragma unroll 4
;   for (int s = 0; s < 132; s++) {
;     int q;
;     if (dir == 0) q = s < 4 ? (256 + 4 * b + s) : (128 * b + (s - 4));
;     else q = s < 4 ? (256 + 4 * b + 3 - s) : (128 * b + 127 - (s - 4));
;     size_t o = ((size_t)q * 2 + dir) * 1024 + gp;
;     float2 e = p.E[o];
;     p.Hin[o] = make_float2(hr, hi);
;     float nr = ar * hr - ai * hi + e.x;
;     float ni = ar * hi + ai * hr + e.y;
;     hr = nr; hi = ni;
;   }
; }
.LBB0_546:
	s_andn2_b64 vcc, exec, s[26:27]
	s_cbranch_vccnz .LBB0_443
	v_lshl_add_u32 v1, s92, 8, v147
	v_and_b32_e32 v0, 0x7ff, v1
	v_or_b32_e32 v2, s13, v0
	v_lshlrev_b32_e32 v2, 3, v2
	global_load_dwordx2 v[4:5], v2, s[24:25]
	v_lshlrev_b32_e32 v7, 3, v0
	s_lshr_b32 s4, s92, 3
	s_lshr_b32 s10, s92, 2
	s_and_b32 s10, s10, 1
	s_cmp_eq_u32 s10, 0
	s_mov_b32 s12, 0xffffc000
	s_cselect_b32 s1, 0x4000, s12
	s_cselect_b32 s2, 0, -1
	s_lshl_b32 s12, s4, 2
	s_add_u32 s12, s12, 0x100
	s_cmp_eq_u32 s10, 0
	s_cselect_b32 s26, 0, 3
	s_add_u32 s12, s12, s26
	s_lshl_b32 s12, s12, 14
	s_add_u32 s6, s64, s12
	s_addc_u32 s7, s65, 0
	s_add_u32 s8, s66, s12
	s_addc_u32 s9, s67, 0
	s_lshl_b32 s12, s4, 7
	s_cmp_eq_u32 s10, 0
	s_cselect_b32 s26, 0, 127
	s_add_u32 s12, s12, s26
	s_lshl_b32 s26, s12, 14
	global_load_dwordx2 v[14:15], v7, s[6:7]
	s_add_u32 s6, s6, s1
	s_addc_u32 s7, s7, s2
	global_load_dwordx2 v[16:17], v7, s[6:7]
	s_add_u32 s6, s6, s1
	s_addc_u32 s7, s7, s2
	global_load_dwordx2 v[18:19], v7, s[6:7]
	s_add_u32 s6, s6, s1
	s_addc_u32 s7, s7, s2
	global_load_dwordx2 v[20:21], v7, s[6:7]
	s_add_u32 s6, s64, s26
	s_addc_u32 s7, s65, 0
	global_load_dwordx2 v[22:23], v7, s[6:7]
	s_add_u32 s6, s6, s1
	s_addc_u32 s7, s7, s2
	global_load_dwordx2 v[24:25], v7, s[6:7]
	s_add_u32 s6, s6, s1
	s_addc_u32 s7, s7, s2
	global_load_dwordx2 v[26:27], v7, s[6:7]
	s_add_u32 s6, s6, s1
	s_addc_u32 s7, s7, s2
	global_load_dwordx2 v[28:29], v7, s[6:7]
	s_add_u32 s6, s6, s1
	s_addc_u32 s7, s7, s2
	global_load_dwordx2 v[30:31], v7, s[6:7]
	s_add_u32 s6, s6, s1
	s_addc_u32 s7, s7, s2
	global_load_dwordx2 v[32:33], v7, s[6:7]
	s_add_u32 s6, s6, s1
	s_addc_u32 s7, s7, s2
	global_load_dwordx2 v[34:35], v7, s[6:7]
	s_add_u32 s6, s6, s1
	s_addc_u32 s7, s7, s2
	global_load_dwordx2 v[36:37], v7, s[6:7]
	s_add_u32 s6, s6, s1
	s_addc_u32 s7, s7, s2
	global_load_dwordx2 v[38:39], v7, s[6:7]
	s_add_u32 s6, s6, s1
	s_addc_u32 s7, s7, s2
	global_load_dwordx2 v[40:41], v7, s[6:7]
	s_add_u32 s6, s6, s1
	s_addc_u32 s7, s7, s2
	global_load_dwordx2 v[42:43], v7, s[6:7]
	s_add_u32 s6, s6, s1
	s_addc_u32 s7, s7, s2
	global_load_dwordx2 v[44:45], v7, s[6:7]
	s_add_u32 s6, s6, s1
	s_addc_u32 s7, s7, s2
	global_load_dwordx2 v[46:47], v7, s[6:7]
	s_add_u32 s6, s6, s1
	s_addc_u32 s7, s7, s2
	global_load_dwordx2 v[48:49], v7, s[6:7]
	s_add_u32 s6, s6, s1
	s_addc_u32 s7, s7, s2
	global_load_dwordx2 v[50:51], v7, s[6:7]
	s_add_u32 s6, s6, s1
	s_addc_u32 s7, s7, s2
	global_load_dwordx2 v[52:53], v7, s[6:7]
	s_add_u32 s6, s6, s1
	s_addc_u32 s7, s7, s2
	global_load_dwordx2 v[54:55], v7, s[6:7]
	s_add_u32 s6, s6, s1
	s_addc_u32 s7, s7, s2
	global_load_dwordx2 v[56:57], v7, s[6:7]
	s_add_u32 s6, s6, s1
	s_addc_u32 s7, s7, s2
	global_load_dwordx2 v[58:59], v7, s[6:7]
	s_add_u32 s6, s6, s1
	s_addc_u32 s7, s7, s2
	global_load_dwordx2 v[60:61], v7, s[6:7]
	s_add_u32 s6, s6, s1
	s_addc_u32 s7, s7, s2
	global_load_dwordx2 v[62:63], v7, s[6:7]
	s_add_u32 s6, s6, s1
	s_addc_u32 s7, s7, s2
	global_load_dwordx2 v[64:65], v7, s[6:7]
	s_add_u32 s6, s6, s1
	s_addc_u32 s7, s7, s2
	global_load_dwordx2 v[66:67], v7, s[6:7]
	s_add_u32 s6, s6, s1
	s_addc_u32 s7, s7, s2
	global_load_dwordx2 v[68:69], v7, s[6:7]
	s_add_u32 s6, s6, s1
	s_addc_u32 s7, s7, s2
	global_load_dwordx2 v[70:71], v7, s[6:7]
	s_add_u32 s6, s6, s1
	s_addc_u32 s7, s7, s2
	global_load_dwordx2 v[72:73], v7, s[6:7]
	s_add_u32 s6, s6, s1
	s_addc_u32 s7, s7, s2
	global_load_dwordx2 v[74:75], v7, s[6:7]
	s_add_u32 s6, s6, s1
	s_addc_u32 s7, s7, s2
	global_load_dwordx2 v[76:77], v7, s[6:7]
	s_add_u32 s6, s6, s1
	s_addc_u32 s7, s7, s2
	global_load_dwordx2 v[78:79], v7, s[6:7]
	s_add_u32 s6, s6, s1
	s_addc_u32 s7, s7, s2
	global_load_dwordx2 v[80:81], v7, s[6:7]
	s_add_u32 s6, s6, s1
	s_addc_u32 s7, s7, s2
	global_load_dwordx2 v[82:83], v7, s[6:7]
	s_add_u32 s6, s6, s1
	s_addc_u32 s7, s7, s2
	global_load_dwordx2 v[84:85], v7, s[6:7]
	s_add_u32 s6, s6, s1
	s_addc_u32 s7, s7, s2
	global_load_dwordx2 v[86:87], v7, s[6:7]
	s_add_u32 s6, s6, s1
	s_addc_u32 s7, s7, s2
	global_load_dwordx2 v[88:89], v7, s[6:7]
	s_add_u32 s6, s6, s1
	s_addc_u32 s7, s7, s2
	global_load_dwordx2 v[90:91], v7, s[6:7]
	s_add_u32 s6, s6, s1
	s_addc_u32 s7, s7, s2
	global_load_dwordx2 v[92:93], v7, s[6:7]
	s_add_u32 s6, s6, s1
	s_addc_u32 s7, s7, s2
	global_load_dwordx2 v[94:95], v7, s[6:7]
	s_add_u32 s6, s6, s1
	s_addc_u32 s7, s7, s2
	global_load_dwordx2 v[96:97], v7, s[6:7]
	s_add_u32 s6, s6, s1
	s_addc_u32 s7, s7, s2
	global_load_dwordx2 v[98:99], v7, s[6:7]
	s_add_u32 s6, s6, s1
	s_addc_u32 s7, s7, s2
	global_load_dwordx2 v[100:101], v7, s[6:7]
	s_add_u32 s6, s6, s1
	s_addc_u32 s7, s7, s2
	s_waitcnt vmcnt(44)
	v_mul_f32_e32 v10, v5, v5
	v_add_f32_e32 v11, v4, v4
	v_fma_f32 v4, v4, v4, -v10
	v_mul_f32_e32 v5, v5, v11
	v_mul_f32_e32 v10, v5, v5
	v_add_f32_e32 v11, v4, v4
	v_fma_f32 v4, v4, v4, -v10
	v_mul_f32_e32 v5, v5, v11
	v_mul_f32_e32 v10, v5, v5
	v_add_f32_e32 v11, v4, v4
	v_fma_f32 v4, v4, v4, -v10
	v_mul_f32_e32 v5, v5, v11
	v_mul_f32_e32 v10, v5, v5
	v_add_f32_e32 v11, v4, v4
	v_fma_f32 v4, v4, v4, -v10
	v_mul_f32_e32 v5, v5, v11
	v_mul_f32_e32 v10, v5, v5
	v_add_f32_e32 v11, v4, v4
	v_fma_f32 v4, v4, v4, -v10
	v_mul_f32_e32 v5, v5, v11
	v_mul_f32_e32 v10, v5, v5
	v_add_f32_e32 v11, v4, v4
	v_fma_f32 v4, v4, v4, -v10
	v_mul_f32_e32 v5, v5, v11
	v_mov_b32_e32 v8, 0
	v_mov_b32_e32 v9, 0
	s_waitcnt vmcnt(22)
; __device__ void phase_s5_carry(CParams& p, int l, int item) {
;     ...
;   for (int s = 0; s < 132; s++) {
;     int q;
;     if (dir == 0) q = s < 4 ? (256 + 4 * b + s) : (128 * b + (s - 4));
;     else q = s < 4 ? (256 + 4 * b + 3 - s) : (128 * b + 127 - (s - 4));
;     size_t o = ((size_t)q * 2 + dir) * 1024 + gp;
;     float2 e = p.E[o];
;     p.Hin[o] = make_float2(hr, hi);
;     float nr = ar * hr - ai * hi + e.x;
;     float ni = ar * hi + ai * hr + e.y;
;     hr = nr; hi = ni;
;   }
	global_store_dwordx2 v7, v[8:9], s[8:9]
	s_add_u32 s8, s8, s1
	s_addc_u32 s9, s9, s2
	v_mul_f32_e32 v10, v5, v9
	v_mul_f32_e32 v11, v5, v8
	v_fma_f32 v12, v4, v8, -v10
	v_fma_f32 v13, v4, v9, v11
	s_nop 0
	v_add_f32_e32 v8, v12, v14
	v_add_f32_e32 v9, v13, v15
	global_store_dwordx2 v7, v[8:9], s[8:9]
	s_add_u32 s8, s8, s1
	s_addc_u32 s9, s9, s2
	v_mul_f32_e32 v10, v5, v9
	v_mul_f32_e32 v11, v5, v8
	v_fma_f32 v12, v4, v8, -v10
	v_fma_f32 v13, v4, v9, v11
	s_nop 0
	v_add_f32_e32 v8, v12, v16
	v_add_f32_e32 v9, v13, v17
	global_store_dwordx2 v7, v[8:9], s[8:9]
	s_add_u32 s8, s8, s1
	s_addc_u32 s9, s9, s2
	v_mul_f32_e32 v10, v5, v9
	v_mul_f32_e32 v11, v5, v8
	v_fma_f32 v12, v4, v8, -v10
	v_fma_f32 v13, v4, v9, v11
	s_nop 0
	v_add_f32_e32 v8, v12, v18
	v_add_f32_e32 v9, v13, v19
	global_store_dwordx2 v7, v[8:9], s[8:9]
	s_add_u32 s8, s66, s26
	s_addc_u32 s9, s67, 0
	v_mul_f32_e32 v10, v5, v9
	v_mul_f32_e32 v11, v5, v8
	v_fma_f32 v12, v4, v8, -v10
	v_fma_f32 v13, v4, v9, v11
	s_nop 0
	v_add_f32_e32 v8, v12, v20
	v_add_f32_e32 v9, v13, v21
	global_store_dwordx2 v7, v[8:9], s[8:9]
	s_add_u32 s8, s8, s1
	s_addc_u32 s9, s9, s2
	v_mul_f32_e32 v10, v5, v9
	v_mul_f32_e32 v11, v5, v8
	v_fma_f32 v12, v4, v8, -v10
	v_fma_f32 v13, v4, v9, v11
	s_nop 0
	v_add_f32_e32 v8, v12, v22
	v_add_f32_e32 v9, v13, v23
	global_store_dwordx2 v7, v[8:9], s[8:9]
	s_add_u32 s8, s8, s1
	s_addc_u32 s9, s9, s2
	v_mul_f32_e32 v10, v5, v9
	v_mul_f32_e32 v11, v5, v8
	v_fma_f32 v12, v4, v8, -v10
	v_fma_f32 v13, v4, v9, v11
	s_nop 0
	v_add_f32_e32 v8, v12, v24
	v_add_f32_e32 v9, v13, v25
	global_store_dwordx2 v7, v[8:9], s[8:9]
	s_add_u32 s8, s8, s1
	s_addc_u32 s9, s9, s2
	v_mul_f32_e32 v10, v5, v9
	v_mul_f32_e32 v11, v5, v8
	v_fma_f32 v12, v4, v8, -v10
	v_fma_f32 v13, v4, v9, v11
	s_nop 0
	v_add_f32_e32 v8, v12, v26
	v_add_f32_e32 v9, v13, v27
	global_store_dwordx2 v7, v[8:9], s[8:9]
	s_add_u32 s8, s8, s1
	s_addc_u32 s9, s9, s2
	v_mul_f32_e32 v10, v5, v9
	v_mul_f32_e32 v11, v5, v8
	v_fma_f32 v12, v4, v8, -v10
	v_fma_f32 v13, v4, v9, v11
	s_nop 0
	v_add_f32_e32 v8, v12, v28
	v_add_f32_e32 v9, v13, v29
	global_store_dwordx2 v7, v[8:9], s[8:9]
	s_add_u32 s8, s8, s1
	s_addc_u32 s9, s9, s2
	v_mul_f32_e32 v10, v5, v9
	v_mul_f32_e32 v11, v5, v8
	v_fma_f32 v12, v4, v8, -v10
	v_fma_f32 v13, v4, v9, v11
	s_nop 0
	v_add_f32_e32 v8, v12, v30
	v_add_f32_e32 v9, v13, v31
	global_store_dwordx2 v7, v[8:9], s[8:9]
	s_add_u32 s8, s8, s1
	s_addc_u32 s9, s9, s2
	v_mul_f32_e32 v10, v5, v9
	v_mul_f32_e32 v11, v5, v8
	v_fma_f32 v12, v4, v8, -v10
	v_fma_f32 v13, v4, v9, v11
	s_nop 0
	v_add_f32_e32 v8, v12, v32
	v_add_f32_e32 v9, v13, v33
	global_store_dwordx2 v7, v[8:9], s[8:9]
	s_add_u32 s8, s8, s1
	s_addc_u32 s9, s9, s2
	v_mul_f32_e32 v10, v5, v9
	v_mul_f32_e32 v11, v5, v8
	v_fma_f32 v12, v4, v8, -v10
	v_fma_f32 v13, v4, v9, v11
	s_nop 0
	v_add_f32_e32 v8, v12, v34
	v_add_f32_e32 v9, v13, v35
	global_store_dwordx2 v7, v[8:9], s[8:9]
	s_add_u32 s8, s8, s1
	s_addc_u32 s9, s9, s2
	v_mul_f32_e32 v10, v5, v9
	v_mul_f32_e32 v11, v5, v8
	v_fma_f32 v12, v4, v8, -v10
	v_fma_f32 v13, v4, v9, v11
	s_nop 0
	v_add_f32_e32 v8, v12, v36
	v_add_f32_e32 v9, v13, v37
	global_store_dwordx2 v7, v[8:9], s[8:9]
	s_add_u32 s8, s8, s1
	s_addc_u32 s9, s9, s2
	v_mul_f32_e32 v10, v5, v9
	v_mul_f32_e32 v11, v5, v8
	v_fma_f32 v12, v4, v8, -v10
	v_fma_f32 v13, v4, v9, v11
	s_nop 0
	v_add_f32_e32 v8, v12, v38
	v_add_f32_e32 v9, v13, v39
	global_store_dwordx2 v7, v[8:9], s[8:9]
	s_add_u32 s8, s8, s1
	s_addc_u32 s9, s9, s2
	v_mul_f32_e32 v10, v5, v9
	v_mul_f32_e32 v11, v5, v8
	v_fma_f32 v12, v4, v8, -v10
	v_fma_f32 v13, v4, v9, v11
	s_nop 0
	v_add_f32_e32 v8, v12, v40
	v_add_f32_e32 v9, v13, v41
	global_store_dwordx2 v7, v[8:9], s[8:9]
	s_add_u32 s8, s8, s1
	s_addc_u32 s9, s9, s2
	v_mul_f32_e32 v10, v5, v9
	v_mul_f32_e32 v11, v5, v8
	v_fma_f32 v12, v4, v8, -v10
	v_fma_f32 v13, v4, v9, v11
	s_nop 0
	v_add_f32_e32 v8, v12, v42
	v_add_f32_e32 v9, v13, v43
	global_store_dwordx2 v7, v[8:9], s[8:9]
	s_add_u32 s8, s8, s1
	s_addc_u32 s9, s9, s2
	v_mul_f32_e32 v10, v5, v9
	v_mul_f32_e32 v11, v5, v8
	v_fma_f32 v12, v4, v8, -v10
	v_fma_f32 v13, v4, v9, v11
	s_nop 0
	v_add_f32_e32 v8, v12, v44
	v_add_f32_e32 v9, v13, v45
	global_store_dwordx2 v7, v[8:9], s[8:9]
	s_add_u32 s8, s8, s1
	s_addc_u32 s9, s9, s2
	v_mul_f32_e32 v10, v5, v9
	v_mul_f32_e32 v11, v5, v8
	v_fma_f32 v12, v4, v8, -v10
	v_fma_f32 v13, v4, v9, v11
	s_nop 0
	v_add_f32_e32 v8, v12, v46
	v_add_f32_e32 v9, v13, v47
	global_store_dwordx2 v7, v[8:9], s[8:9]
	s_add_u32 s8, s8, s1
	s_addc_u32 s9, s9, s2
	v_mul_f32_e32 v10, v5, v9
	v_mul_f32_e32 v11, v5, v8
	v_fma_f32 v12, v4, v8, -v10
	v_fma_f32 v13, v4, v9, v11
	s_nop 0
	v_add_f32_e32 v8, v12, v48
	v_add_f32_e32 v9, v13, v49
	global_store_dwordx2 v7, v[8:9], s[8:9]
	s_add_u32 s8, s8, s1
	s_addc_u32 s9, s9, s2
	v_mul_f32_e32 v10, v5, v9
	v_mul_f32_e32 v11, v5, v8
	v_fma_f32 v12, v4, v8, -v10
	v_fma_f32 v13, v4, v9, v11
	s_nop 0
	v_add_f32_e32 v8, v12, v50
	v_add_f32_e32 v9, v13, v51
	global_store_dwordx2 v7, v[8:9], s[8:9]
	s_add_u32 s8, s8, s1
	s_addc_u32 s9, s9, s2
	v_mul_f32_e32 v10, v5, v9
	v_mul_f32_e32 v11, v5, v8
	v_fma_f32 v12, v4, v8, -v10
	v_fma_f32 v13, v4, v9, v11
	s_nop 0
	v_add_f32_e32 v8, v12, v52
	v_add_f32_e32 v9, v13, v53
	global_store_dwordx2 v7, v[8:9], s[8:9]
	s_add_u32 s8, s8, s1
	s_addc_u32 s9, s9, s2
	v_mul_f32_e32 v10, v5, v9
	v_mul_f32_e32 v11, v5, v8
	v_fma_f32 v12, v4, v8, -v10
	v_fma_f32 v13, v4, v9, v11
	s_nop 0
	v_add_f32_e32 v8, v12, v54
	v_add_f32_e32 v9, v13, v55
	global_store_dwordx2 v7, v[8:9], s[8:9]
	s_add_u32 s8, s8, s1
	s_addc_u32 s9, s9, s2
	v_mul_f32_e32 v10, v5, v9
	v_mul_f32_e32 v11, v5, v8
; __device__ void phase_s5_carry(CParams& p, int l, int item) {
;     ...
;   for (int s = 0; s < 132; s++) {
;     int q;
;     if (dir == 0) q = s < 4 ? (256 + 4 * b + s) : (128 * b + (s - 4));
;     else q = s < 4 ? (256 + 4 * b + 3 - s) : (128 * b + 127 - (s - 4));
;     size_t o = ((size_t)q * 2 + dir) * 1024 + gp;
;     float2 e = p.E[o];
;     p.Hin[o] = make_float2(hr, hi);
;     float nr = ar * hr - ai * hi + e.x;
;     float ni = ar * hi + ai * hr + e.y;
;     hr = nr; hi = ni;
;   }
	v_fma_f32 v12, v4, v8, -v10
	v_fma_f32 v13, v4, v9, v11
	s_nop 0
	v_add_f32_e32 v8, v12, v56
	v_add_f32_e32 v9, v13, v57
	global_load_dwordx2 v[14:15], v7, s[6:7]
	s_add_u32 s6, s6, s1
	s_addc_u32 s7, s7, s2
	global_load_dwordx2 v[16:17], v7, s[6:7]
	s_add_u32 s6, s6, s1
	s_addc_u32 s7, s7, s2
	global_load_dwordx2 v[18:19], v7, s[6:7]
	s_add_u32 s6, s6, s1
	s_addc_u32 s7, s7, s2
	global_load_dwordx2 v[20:21], v7, s[6:7]
	s_add_u32 s6, s6, s1
	s_addc_u32 s7, s7, s2
	global_load_dwordx2 v[22:23], v7, s[6:7]
	s_add_u32 s6, s6, s1
	s_addc_u32 s7, s7, s2
	global_load_dwordx2 v[24:25], v7, s[6:7]
	s_add_u32 s6, s6, s1
	s_addc_u32 s7, s7, s2
	global_load_dwordx2 v[26:27], v7, s[6:7]
	s_add_u32 s6, s6, s1
	s_addc_u32 s7, s7, s2
	global_load_dwordx2 v[28:29], v7, s[6:7]
	s_add_u32 s6, s6, s1
	s_addc_u32 s7, s7, s2
	global_load_dwordx2 v[30:31], v7, s[6:7]
	s_add_u32 s6, s6, s1
	s_addc_u32 s7, s7, s2
	global_load_dwordx2 v[32:33], v7, s[6:7]
	s_add_u32 s6, s6, s1
	s_addc_u32 s7, s7, s2
	global_load_dwordx2 v[34:35], v7, s[6:7]
	s_add_u32 s6, s6, s1
	s_addc_u32 s7, s7, s2
	global_load_dwordx2 v[36:37], v7, s[6:7]
	s_add_u32 s6, s6, s1
	s_addc_u32 s7, s7, s2
	global_load_dwordx2 v[38:39], v7, s[6:7]
	s_add_u32 s6, s6, s1
	s_addc_u32 s7, s7, s2
	global_load_dwordx2 v[40:41], v7, s[6:7]
	s_add_u32 s6, s6, s1
	s_addc_u32 s7, s7, s2
	global_load_dwordx2 v[42:43], v7, s[6:7]
	s_add_u32 s6, s6, s1
	s_addc_u32 s7, s7, s2
	global_load_dwordx2 v[44:45], v7, s[6:7]
	s_add_u32 s6, s6, s1
	s_addc_u32 s7, s7, s2
	global_load_dwordx2 v[46:47], v7, s[6:7]
	s_add_u32 s6, s6, s1
	s_addc_u32 s7, s7, s2
	global_load_dwordx2 v[48:49], v7, s[6:7]
	s_add_u32 s6, s6, s1
	s_addc_u32 s7, s7, s2
	global_load_dwordx2 v[50:51], v7, s[6:7]
	s_add_u32 s6, s6, s1
	s_addc_u32 s7, s7, s2
	global_load_dwordx2 v[52:53], v7, s[6:7]
	s_add_u32 s6, s6, s1
	s_addc_u32 s7, s7, s2
	global_load_dwordx2 v[54:55], v7, s[6:7]
	s_add_u32 s6, s6, s1
	s_addc_u32 s7, s7, s2
	global_load_dwordx2 v[56:57], v7, s[6:7]
	s_add_u32 s6, s6, s1
	s_addc_u32 s7, s7, s2
	s_waitcnt vmcnt(22)
	global_store_dwordx2 v7, v[8:9], s[8:9]
	s_add_u32 s8, s8, s1
	s_addc_u32 s9, s9, s2
	v_mul_f32_e32 v10, v5, v9
	v_mul_f32_e32 v11, v5, v8
	v_fma_f32 v12, v4, v8, -v10
	v_fma_f32 v13, v4, v9, v11
	s_nop 0
	v_add_f32_e32 v8, v12, v58
	v_add_f32_e32 v9, v13, v59
	global_store_dwordx2 v7, v[8:9], s[8:9]
	s_add_u32 s8, s8, s1
	s_addc_u32 s9, s9, s2
	v_mul_f32_e32 v10, v5, v9
	v_mul_f32_e32 v11, v5, v8
	v_fma_f32 v12, v4, v8, -v10
	v_fma_f32 v13, v4, v9, v11
	s_nop 0
	v_add_f32_e32 v8, v12, v60
	v_add_f32_e32 v9, v13, v61
	global_store_dwordx2 v7, v[8:9], s[8:9]
	s_add_u32 s8, s8, s1
	s_addc_u32 s9, s9, s2
	v_mul_f32_e32 v10, v5, v9
	v_mul_f32_e32 v11, v5, v8
	v_fma_f32 v12, v4, v8, -v10
	v_fma_f32 v13, v4, v9, v11
	s_nop 0
	v_add_f32_e32 v8, v12, v62
	v_add_f32_e32 v9, v13, v63
	global_store_dwordx2 v7, v[8:9], s[8:9]
	s_add_u32 s8, s8, s1
	s_addc_u32 s9, s9, s2
	v_mul_f32_e32 v10, v5, v9
	v_mul_f32_e32 v11, v5, v8
	v_fma_f32 v12, v4, v8, -v10
	v_fma_f32 v13, v4, v9, v11
	s_nop 0
	v_add_f32_e32 v8, v12, v64
	v_add_f32_e32 v9, v13, v65
	global_store_dwordx2 v7, v[8:9], s[8:9]
	s_add_u32 s8, s8, s1
	s_addc_u32 s9, s9, s2
	v_mul_f32_e32 v10, v5, v9
	v_mul_f32_e32 v11, v5, v8
	v_fma_f32 v12, v4, v8, -v10
	v_fma_f32 v13, v4, v9, v11
	s_nop 0
	v_add_f32_e32 v8, v12, v66
	v_add_f32_e32 v9, v13, v67
	global_store_dwordx2 v7, v[8:9], s[8:9]
	s_add_u32 s8, s8, s1
	s_addc_u32 s9, s9, s2
	v_mul_f32_e32 v10, v5, v9
	v_mul_f32_e32 v11, v5, v8
	v_fma_f32 v12, v4, v8, -v10
	v_fma_f32 v13, v4, v9, v11
	s_nop 0
	v_add_f32_e32 v8, v12, v68
	v_add_f32_e32 v9, v13, v69
	global_store_dwordx2 v7, v[8:9], s[8:9]
	s_add_u32 s8, s8, s1
	s_addc_u32 s9, s9, s2
	v_mul_f32_e32 v10, v5, v9
	v_mul_f32_e32 v11, v5, v8
	v_fma_f32 v12, v4, v8, -v10
	v_fma_f32 v13, v4, v9, v11
	s_nop 0
	v_add_f32_e32 v8, v12, v70
	v_add_f32_e32 v9, v13, v71
	global_store_dwordx2 v7, v[8:9], s[8:9]
	s_add_u32 s8, s8, s1
	s_addc_u32 s9, s9, s2
	v_mul_f32_e32 v10, v5, v9
	v_mul_f32_e32 v11, v5, v8
	v_fma_f32 v12, v4, v8, -v10
	v_fma_f32 v13, v4, v9, v11
	s_nop 0
	v_add_f32_e32 v8, v12, v72
	v_add_f32_e32 v9, v13, v73
	global_store_dwordx2 v7, v[8:9], s[8:9]
	s_add_u32 s8, s8, s1
	s_addc_u32 s9, s9, s2
	v_mul_f32_e32 v10, v5, v9
	v_mul_f32_e32 v11, v5, v8
	v_fma_f32 v12, v4, v8, -v10
	v_fma_f32 v13, v4, v9, v11
	s_nop 0
	v_add_f32_e32 v8, v12, v74
	v_add_f32_e32 v9, v13, v75
	global_store_dwordx2 v7, v[8:9], s[8:9]
	s_add_u32 s8, s8, s1
	s_addc_u32 s9, s9, s2
	v_mul_f32_e32 v10, v5, v9
	v_mul_f32_e32 v11, v5, v8
	v_fma_f32 v12, v4, v8, -v10
	v_fma_f32 v13, v4, v9, v11
	s_nop 0
	v_add_f32_e32 v8, v12, v76
	v_add_f32_e32 v9, v13, v77
	global_store_dwordx2 v7, v[8:9], s[8:9]
	s_add_u32 s8, s8, s1
	s_addc_u32 s9, s9, s2
	v_mul_f32_e32 v10, v5, v9
	v_mul_f32_e32 v11, v5, v8
	v_fma_f32 v12, v4, v8, -v10
	v_fma_f32 v13, v4, v9, v11
	s_nop 0
	v_add_f32_e32 v8, v12, v78
	v_add_f32_e32 v9, v13, v79
	global_store_dwordx2 v7, v[8:9], s[8:9]
	s_add_u32 s8, s8, s1
	s_addc_u32 s9, s9, s2
	v_mul_f32_e32 v10, v5, v9
	v_mul_f32_e32 v11, v5, v8
	v_fma_f32 v12, v4, v8, -v10
	v_fma_f32 v13, v4, v9, v11
	s_nop 0
	v_add_f32_e32 v8, v12, v80
	v_add_f32_e32 v9, v13, v81
	global_store_dwordx2 v7, v[8:9], s[8:9]
	s_add_u32 s8, s8, s1
	s_addc_u32 s9, s9, s2
	v_mul_f32_e32 v10, v5, v9
	v_mul_f32_e32 v11, v5, v8
	v_fma_f32 v12, v4, v8, -v10
	v_fma_f32 v13, v4, v9, v11
	s_nop 0
	v_add_f32_e32 v8, v12, v82
	v_add_f32_e32 v9, v13, v83
	global_store_dwordx2 v7, v[8:9], s[8:9]
	s_add_u32 s8, s8, s1
	s_addc_u32 s9, s9, s2
	v_mul_f32_e32 v10, v5, v9
	v_mul_f32_e32 v11, v5, v8
	v_fma_f32 v12, v4, v8, -v10
; __device__ void phase_s5_carry(CParams& p, int l, int item) {
;     ...
;   for (int s = 0; s < 132; s++) {
;     int q;
;     if (dir == 0) q = s < 4 ? (256 + 4 * b + s) : (128 * b + (s - 4));
;     else q = s < 4 ? (256 + 4 * b + 3 - s) : (128 * b + 127 - (s - 4));
;     size_t o = ((size_t)q * 2 + dir) * 1024 + gp;
;     float2 e = p.E[o];
;     p.Hin[o] = make_float2(hr, hi);
;     float nr = ar * hr - ai * hi + e.x;
;     float ni = ar * hi + ai * hr + e.y;
;     hr = nr; hi = ni;
;   }
	v_fma_f32 v13, v4, v9, v11
	s_nop 0
	v_add_f32_e32 v8, v12, v84
	v_add_f32_e32 v9, v13, v85
	global_store_dwordx2 v7, v[8:9], s[8:9]
	s_add_u32 s8, s8, s1
	s_addc_u32 s9, s9, s2
	v_mul_f32_e32 v10, v5, v9
	v_mul_f32_e32 v11, v5, v8
	v_fma_f32 v12, v4, v8, -v10
	v_fma_f32 v13, v4, v9, v11
	s_nop 0
	v_add_f32_e32 v8, v12, v86
	v_add_f32_e32 v9, v13, v87
	global_store_dwordx2 v7, v[8:9], s[8:9]
	s_add_u32 s8, s8, s1
	s_addc_u32 s9, s9, s2
	v_mul_f32_e32 v10, v5, v9
	v_mul_f32_e32 v11, v5, v8
	v_fma_f32 v12, v4, v8, -v10
	v_fma_f32 v13, v4, v9, v11
	s_nop 0
	v_add_f32_e32 v8, v12, v88
	v_add_f32_e32 v9, v13, v89
	global_store_dwordx2 v7, v[8:9], s[8:9]
	s_add_u32 s8, s8, s1
	s_addc_u32 s9, s9, s2
	v_mul_f32_e32 v10, v5, v9
	v_mul_f32_e32 v11, v5, v8
	v_fma_f32 v12, v4, v8, -v10
	v_fma_f32 v13, v4, v9, v11
	s_nop 0
	v_add_f32_e32 v8, v12, v90
	v_add_f32_e32 v9, v13, v91
	global_store_dwordx2 v7, v[8:9], s[8:9]
	s_add_u32 s8, s8, s1
	s_addc_u32 s9, s9, s2
	v_mul_f32_e32 v10, v5, v9
	v_mul_f32_e32 v11, v5, v8
	v_fma_f32 v12, v4, v8, -v10
	v_fma_f32 v13, v4, v9, v11
	s_nop 0
	v_add_f32_e32 v8, v12, v92
	v_add_f32_e32 v9, v13, v93
	global_store_dwordx2 v7, v[8:9], s[8:9]
	s_add_u32 s8, s8, s1
	s_addc_u32 s9, s9, s2
	v_mul_f32_e32 v10, v5, v9
	v_mul_f32_e32 v11, v5, v8
	v_fma_f32 v12, v4, v8, -v10
	v_fma_f32 v13, v4, v9, v11
	s_nop 0
	v_add_f32_e32 v8, v12, v94
	v_add_f32_e32 v9, v13, v95
	global_store_dwordx2 v7, v[8:9], s[8:9]
	s_add_u32 s8, s8, s1
	s_addc_u32 s9, s9, s2
	v_mul_f32_e32 v10, v5, v9
	v_mul_f32_e32 v11, v5, v8
	v_fma_f32 v12, v4, v8, -v10
	v_fma_f32 v13, v4, v9, v11
	s_nop 0
	v_add_f32_e32 v8, v12, v96
	v_add_f32_e32 v9, v13, v97
	global_store_dwordx2 v7, v[8:9], s[8:9]
	s_add_u32 s8, s8, s1
	s_addc_u32 s9, s9, s2
	v_mul_f32_e32 v10, v5, v9
	v_mul_f32_e32 v11, v5, v8
	v_fma_f32 v12, v4, v8, -v10
	v_fma_f32 v13, v4, v9, v11
	s_nop 0
	v_add_f32_e32 v8, v12, v98
	v_add_f32_e32 v9, v13, v99
	global_store_dwordx2 v7, v[8:9], s[8:9]
	s_add_u32 s8, s8, s1
	s_addc_u32 s9, s9, s2
	v_mul_f32_e32 v10, v5, v9
	v_mul_f32_e32 v11, v5, v8
	v_fma_f32 v12, v4, v8, -v10
	v_fma_f32 v13, v4, v9, v11
	s_nop 0
	v_add_f32_e32 v8, v12, v100
	v_add_f32_e32 v9, v13, v101
	global_load_dwordx2 v[58:59], v7, s[6:7]
	s_add_u32 s6, s6, s1
	s_addc_u32 s7, s7, s2
	global_load_dwordx2 v[60:61], v7, s[6:7]
	s_add_u32 s6, s6, s1
	s_addc_u32 s7, s7, s2
	global_load_dwordx2 v[62:63], v7, s[6:7]
	s_add_u32 s6, s6, s1
	s_addc_u32 s7, s7, s2
	global_load_dwordx2 v[64:65], v7, s[6:7]
	s_add_u32 s6, s6, s1
	s_addc_u32 s7, s7, s2
	global_load_dwordx2 v[66:67], v7, s[6:7]
	s_add_u32 s6, s6, s1
	s_addc_u32 s7, s7, s2
	global_load_dwordx2 v[68:69], v7, s[6:7]
	s_add_u32 s6, s6, s1
	s_addc_u32 s7, s7, s2
	global_load_dwordx2 v[70:71], v7, s[6:7]
	s_add_u32 s6, s6, s1
	s_addc_u32 s7, s7, s2
	global_load_dwordx2 v[72:73], v7, s[6:7]
	s_add_u32 s6, s6, s1
	s_addc_u32 s7, s7, s2
	global_load_dwordx2 v[74:75], v7, s[6:7]
	s_add_u32 s6, s6, s1
	s_addc_u32 s7, s7, s2
	global_load_dwordx2 v[76:77], v7, s[6:7]
	s_add_u32 s6, s6, s1
	s_addc_u32 s7, s7, s2
	global_load_dwordx2 v[78:79], v7, s[6:7]
	s_add_u32 s6, s6, s1
	s_addc_u32 s7, s7, s2
	global_load_dwordx2 v[80:81], v7, s[6:7]
	s_add_u32 s6, s6, s1
	s_addc_u32 s7, s7, s2
	global_load_dwordx2 v[82:83], v7, s[6:7]
	s_add_u32 s6, s6, s1
	s_addc_u32 s7, s7, s2
	global_load_dwordx2 v[84:85], v7, s[6:7]
	s_add_u32 s6, s6, s1
	s_addc_u32 s7, s7, s2
	global_load_dwordx2 v[86:87], v7, s[6:7]
	s_add_u32 s6, s6, s1
	s_addc_u32 s7, s7, s2
	global_load_dwordx2 v[88:89], v7, s[6:7]
	s_add_u32 s6, s6, s1
	s_addc_u32 s7, s7, s2
	global_load_dwordx2 v[90:91], v7, s[6:7]
	s_add_u32 s6, s6, s1
	s_addc_u32 s7, s7, s2
	global_load_dwordx2 v[92:93], v7, s[6:7]
	s_add_u32 s6, s6, s1
	s_addc_u32 s7, s7, s2
	global_load_dwordx2 v[94:95], v7, s[6:7]
	s_add_u32 s6, s6, s1
	s_addc_u32 s7, s7, s2
	global_load_dwordx2 v[96:97], v7, s[6:7]
	s_add_u32 s6, s6, s1
	s_addc_u32 s7, s7, s2
	global_load_dwordx2 v[98:99], v7, s[6:7]
	s_add_u32 s6, s6, s1
	s_addc_u32 s7, s7, s2
	global_load_dwordx2 v[100:101], v7, s[6:7]
	s_add_u32 s6, s6, s1
	s_addc_u32 s7, s7, s2
	s_waitcnt vmcnt(22)
	global_store_dwordx2 v7, v[8:9], s[8:9]
	s_add_u32 s8, s8, s1
	s_addc_u32 s9, s9, s2
	v_mul_f32_e32 v10, v5, v9
	v_mul_f32_e32 v11, v5, v8
	v_fma_f32 v12, v4, v8, -v10
	v_fma_f32 v13, v4, v9, v11
	s_nop 0
	v_add_f32_e32 v8, v12, v14
	v_add_f32_e32 v9, v13, v15
	global_store_dwordx2 v7, v[8:9], s[8:9]
	s_add_u32 s8, s8, s1
	s_addc_u32 s9, s9, s2
	v_mul_f32_e32 v10, v5, v9
	v_mul_f32_e32 v11, v5, v8
	v_fma_f32 v12, v4, v8, -v10
	v_fma_f32 v13, v4, v9, v11
	s_nop 0
	v_add_f32_e32 v8, v12, v16
	v_add_f32_e32 v9, v13, v17
	global_store_dwordx2 v7, v[8:9], s[8:9]
	s_add_u32 s8, s8, s1
	s_addc_u32 s9, s9, s2
	v_mul_f32_e32 v10, v5, v9
	v_mul_f32_e32 v11, v5, v8
	v_fma_f32 v12, v4, v8, -v10
	v_fma_f32 v13, v4, v9, v11
	s_nop 0
	v_add_f32_e32 v8, v12, v18
	v_add_f32_e32 v9, v13, v19
	global_store_dwordx2 v7, v[8:9], s[8:9]
	s_add_u32 s8, s8, s1
	s_addc_u32 s9, s9, s2
	v_mul_f32_e32 v10, v5, v9
	v_mul_f32_e32 v11, v5, v8
	v_fma_f32 v12, v4, v8, -v10
	v_fma_f32 v13, v4, v9, v11
	s_nop 0
	v_add_f32_e32 v8, v12, v20
	v_add_f32_e32 v9, v13, v21
	global_store_dwordx2 v7, v[8:9], s[8:9]
	s_add_u32 s8, s8, s1
	s_addc_u32 s9, s9, s2
	v_mul_f32_e32 v10, v5, v9
	v_mul_f32_e32 v11, v5, v8
	v_fma_f32 v12, v4, v8, -v10
	v_fma_f32 v13, v4, v9, v11
	s_nop 0
	v_add_f32_e32 v8, v12, v22
	v_add_f32_e32 v9, v13, v23
	global_store_dwordx2 v7, v[8:9], s[8:9]
	s_add_u32 s8, s8, s1
	s_addc_u32 s9, s9, s2
	v_mul_f32_e32 v10, v5, v9
	v_mul_f32_e32 v11, v5, v8
	v_fma_f32 v12, v4, v8, -v10
	v_fma_f32 v13, v4, v9, v11
	s_nop 0
; __device__ void phase_s5_carry(CParams& p, int l, int item) {
;     ...
;   for (int s = 0; s < 132; s++) {
;     int q;
;     if (dir == 0) q = s < 4 ? (256 + 4 * b + s) : (128 * b + (s - 4));
;     else q = s < 4 ? (256 + 4 * b + 3 - s) : (128 * b + 127 - (s - 4));
;     size_t o = ((size_t)q * 2 + dir) * 1024 + gp;
;     float2 e = p.E[o];
;     p.Hin[o] = make_float2(hr, hi);
;     float nr = ar * hr - ai * hi + e.x;
;     float ni = ar * hi + ai * hr + e.y;
;     hr = nr; hi = ni;
;   }
	v_add_f32_e32 v8, v12, v24
	v_add_f32_e32 v9, v13, v25
	global_store_dwordx2 v7, v[8:9], s[8:9]
	s_add_u32 s8, s8, s1
	s_addc_u32 s9, s9, s2
	v_mul_f32_e32 v10, v5, v9
	v_mul_f32_e32 v11, v5, v8
	v_fma_f32 v12, v4, v8, -v10
	v_fma_f32 v13, v4, v9, v11
	s_nop 0
	v_add_f32_e32 v8, v12, v26
	v_add_f32_e32 v9, v13, v27
	global_store_dwordx2 v7, v[8:9], s[8:9]
	s_add_u32 s8, s8, s1
	s_addc_u32 s9, s9, s2
	v_mul_f32_e32 v10, v5, v9
	v_mul_f32_e32 v11, v5, v8
	v_fma_f32 v12, v4, v8, -v10
	v_fma_f32 v13, v4, v9, v11
	s_nop 0
	v_add_f32_e32 v8, v12, v28
	v_add_f32_e32 v9, v13, v29
	global_store_dwordx2 v7, v[8:9], s[8:9]
	s_add_u32 s8, s8, s1
	s_addc_u32 s9, s9, s2
	v_mul_f32_e32 v10, v5, v9
	v_mul_f32_e32 v11, v5, v8
	v_fma_f32 v12, v4, v8, -v10
	v_fma_f32 v13, v4, v9, v11
	s_nop 0
	v_add_f32_e32 v8, v12, v30
	v_add_f32_e32 v9, v13, v31
	global_store_dwordx2 v7, v[8:9], s[8:9]
	s_add_u32 s8, s8, s1
	s_addc_u32 s9, s9, s2
	v_mul_f32_e32 v10, v5, v9
	v_mul_f32_e32 v11, v5, v8
	v_fma_f32 v12, v4, v8, -v10
	v_fma_f32 v13, v4, v9, v11
	s_nop 0
	v_add_f32_e32 v8, v12, v32
	v_add_f32_e32 v9, v13, v33
	global_store_dwordx2 v7, v[8:9], s[8:9]
	s_add_u32 s8, s8, s1
	s_addc_u32 s9, s9, s2
	v_mul_f32_e32 v10, v5, v9
	v_mul_f32_e32 v11, v5, v8
	v_fma_f32 v12, v4, v8, -v10
	v_fma_f32 v13, v4, v9, v11
	s_nop 0
	v_add_f32_e32 v8, v12, v34
	v_add_f32_e32 v9, v13, v35
	global_store_dwordx2 v7, v[8:9], s[8:9]
	s_add_u32 s8, s8, s1
	s_addc_u32 s9, s9, s2
	v_mul_f32_e32 v10, v5, v9
	v_mul_f32_e32 v11, v5, v8
	v_fma_f32 v12, v4, v8, -v10
	v_fma_f32 v13, v4, v9, v11
	s_nop 0
	v_add_f32_e32 v8, v12, v36
	v_add_f32_e32 v9, v13, v37
	global_store_dwordx2 v7, v[8:9], s[8:9]
	s_add_u32 s8, s8, s1
	s_addc_u32 s9, s9, s2
	v_mul_f32_e32 v10, v5, v9
	v_mul_f32_e32 v11, v5, v8
	v_fma_f32 v12, v4, v8, -v10
	v_fma_f32 v13, v4, v9, v11
	s_nop 0
	v_add_f32_e32 v8, v12, v38
	v_add_f32_e32 v9, v13, v39
	global_store_dwordx2 v7, v[8:9], s[8:9]
	s_add_u32 s8, s8, s1
	s_addc_u32 s9, s9, s2
	v_mul_f32_e32 v10, v5, v9
	v_mul_f32_e32 v11, v5, v8
	v_fma_f32 v12, v4, v8, -v10
	v_fma_f32 v13, v4, v9, v11
	s_nop 0
	v_add_f32_e32 v8, v12, v40
	v_add_f32_e32 v9, v13, v41
	global_store_dwordx2 v7, v[8:9], s[8:9]
	s_add_u32 s8, s8, s1
	s_addc_u32 s9, s9, s2
	v_mul_f32_e32 v10, v5, v9
	v_mul_f32_e32 v11, v5, v8
	v_fma_f32 v12, v4, v8, -v10
	v_fma_f32 v13, v4, v9, v11
	s_nop 0
	v_add_f32_e32 v8, v12, v42
	v_add_f32_e32 v9, v13, v43
	global_store_dwordx2 v7, v[8:9], s[8:9]
	s_add_u32 s8, s8, s1
	s_addc_u32 s9, s9, s2
	v_mul_f32_e32 v10, v5, v9
	v_mul_f32_e32 v11, v5, v8
	v_fma_f32 v12, v4, v8, -v10
	v_fma_f32 v13, v4, v9, v11
	s_nop 0
	v_add_f32_e32 v8, v12, v44
	v_add_f32_e32 v9, v13, v45
	global_store_dwordx2 v7, v[8:9], s[8:9]
	s_add_u32 s8, s8, s1
	s_addc_u32 s9, s9, s2
	v_mul_f32_e32 v10, v5, v9
	v_mul_f32_e32 v11, v5, v8
	v_fma_f32 v12, v4, v8, -v10
	v_fma_f32 v13, v4, v9, v11
	s_nop 0
	v_add_f32_e32 v8, v12, v46
	v_add_f32_e32 v9, v13, v47
	global_store_dwordx2 v7, v[8:9], s[8:9]
	s_add_u32 s8, s8, s1
	s_addc_u32 s9, s9, s2
	v_mul_f32_e32 v10, v5, v9
	v_mul_f32_e32 v11, v5, v8
	v_fma_f32 v12, v4, v8, -v10
	v_fma_f32 v13, v4, v9, v11
	s_nop 0
	v_add_f32_e32 v8, v12, v48
	v_add_f32_e32 v9, v13, v49
	global_store_dwordx2 v7, v[8:9], s[8:9]
	s_add_u32 s8, s8, s1
	s_addc_u32 s9, s9, s2
	v_mul_f32_e32 v10, v5, v9
	v_mul_f32_e32 v11, v5, v8
	v_fma_f32 v12, v4, v8, -v10
	v_fma_f32 v13, v4, v9, v11
	s_nop 0
	v_add_f32_e32 v8, v12, v50
	v_add_f32_e32 v9, v13, v51
	global_store_dwordx2 v7, v[8:9], s[8:9]
	s_add_u32 s8, s8, s1
	s_addc_u32 s9, s9, s2
	v_mul_f32_e32 v10, v5, v9
	v_mul_f32_e32 v11, v5, v8
	v_fma_f32 v12, v4, v8, -v10
	v_fma_f32 v13, v4, v9, v11
	s_nop 0
	v_add_f32_e32 v8, v12, v52
	v_add_f32_e32 v9, v13, v53
	global_store_dwordx2 v7, v[8:9], s[8:9]
	s_add_u32 s8, s8, s1
	s_addc_u32 s9, s9, s2
	v_mul_f32_e32 v10, v5, v9
	v_mul_f32_e32 v11, v5, v8
	v_fma_f32 v12, v4, v8, -v10
	v_fma_f32 v13, v4, v9, v11
	s_nop 0
	v_add_f32_e32 v8, v12, v54
	v_add_f32_e32 v9, v13, v55
	global_store_dwordx2 v7, v[8:9], s[8:9]
	s_add_u32 s8, s8, s1
	s_addc_u32 s9, s9, s2
	v_mul_f32_e32 v10, v5, v9
	v_mul_f32_e32 v11, v5, v8
	v_fma_f32 v12, v4, v8, -v10
	v_fma_f32 v13, v4, v9, v11
	s_nop 0
	v_add_f32_e32 v8, v12, v56
	v_add_f32_e32 v9, v13, v57
	global_load_dwordx2 v[14:15], v7, s[6:7]
	s_add_u32 s6, s6, s1
	s_addc_u32 s7, s7, s2
	global_load_dwordx2 v[16:17], v7, s[6:7]
	s_add_u32 s6, s6, s1
	s_addc_u32 s7, s7, s2
	global_load_dwordx2 v[18:19], v7, s[6:7]
	s_add_u32 s6, s6, s1
	s_addc_u32 s7, s7, s2
	global_load_dwordx2 v[20:21], v7, s[6:7]
	s_add_u32 s6, s6, s1
	s_addc_u32 s7, s7, s2
	global_load_dwordx2 v[22:23], v7, s[6:7]
	s_add_u32 s6, s6, s1
	s_addc_u32 s7, s7, s2
	global_load_dwordx2 v[24:25], v7, s[6:7]
	s_add_u32 s6, s6, s1
	s_addc_u32 s7, s7, s2
	global_load_dwordx2 v[26:27], v7, s[6:7]
	s_add_u32 s6, s6, s1
	s_addc_u32 s7, s7, s2
	global_load_dwordx2 v[28:29], v7, s[6:7]
	s_add_u32 s6, s6, s1
	s_addc_u32 s7, s7, s2
	global_load_dwordx2 v[30:31], v7, s[6:7]
	s_add_u32 s6, s6, s1
	s_addc_u32 s7, s7, s2
	global_load_dwordx2 v[32:33], v7, s[6:7]
	s_add_u32 s6, s6, s1
	s_addc_u32 s7, s7, s2
	global_load_dwordx2 v[34:35], v7, s[6:7]
	s_add_u32 s6, s6, s1
	s_addc_u32 s7, s7, s2
	global_load_dwordx2 v[36:37], v7, s[6:7]
	s_add_u32 s6, s6, s1
	s_addc_u32 s7, s7, s2
	global_load_dwordx2 v[38:39], v7, s[6:7]
	s_add_u32 s6, s6, s1
	s_addc_u32 s7, s7, s2
	global_load_dwordx2 v[40:41], v7, s[6:7]
	s_add_u32 s6, s6, s1
	s_addc_u32 s7, s7, s2
	global_load_dwordx2 v[42:43], v7, s[6:7]
	s_add_u32 s6, s6, s1
	s_addc_u32 s7, s7, s2
	global_load_dwordx2 v[44:45], v7, s[6:7]
	s_add_u32 s6, s6, s1
	s_addc_u32 s7, s7, s2
	global_load_dwordx2 v[46:47], v7, s[6:7]
	s_add_u32 s6, s6, s1
	s_addc_u32 s7, s7, s2
	global_load_dwordx2 v[48:49], v7, s[6:7]
	s_add_u32 s6, s6, s1
	s_addc_u32 s7, s7, s2
	global_load_dwordx2 v[50:51], v7, s[6:7]
	s_add_u32 s6, s6, s1
	s_addc_u32 s7, s7, s2
	global_load_dwordx2 v[52:53], v7, s[6:7]
	s_add_u32 s6, s6, s1
	s_addc_u32 s7, s7, s2
	global_load_dwordx2 v[54:55], v7, s[6:7]
	s_add_u32 s6, s6, s1
	s_addc_u32 s7, s7, s2
	global_load_dwordx2 v[56:57], v7, s[6:7]
	s_add_u32 s6, s6, s1
	s_addc_u32 s7, s7, s2
	s_waitcnt vmcnt(22)
; __device__ void phase_s5_carry(CParams& p, int l, int item) {
;     ...
;   for (int s = 0; s < 132; s++) {
;     int q;
;     if (dir == 0) q = s < 4 ? (256 + 4 * b + s) : (128 * b + (s - 4));
;     else q = s < 4 ? (256 + 4 * b + 3 - s) : (128 * b + 127 - (s - 4));
;     size_t o = ((size_t)q * 2 + dir) * 1024 + gp;
;     float2 e = p.E[o];
;     p.Hin[o] = make_float2(hr, hi);
;     float nr = ar * hr - ai * hi + e.x;
;     float ni = ar * hi + ai * hr + e.y;
;     hr = nr; hi = ni;
;   }
	global_store_dwordx2 v7, v[8:9], s[8:9]
	s_add_u32 s8, s8, s1
	s_addc_u32 s9, s9, s2
	v_mul_f32_e32 v10, v5, v9
	v_mul_f32_e32 v11, v5, v8
	v_fma_f32 v12, v4, v8, -v10
	v_fma_f32 v13, v4, v9, v11
	s_nop 0
	v_add_f32_e32 v8, v12, v58
	v_add_f32_e32 v9, v13, v59
	global_store_dwordx2 v7, v[8:9], s[8:9]
	s_add_u32 s8, s8, s1
	s_addc_u32 s9, s9, s2
	v_mul_f32_e32 v10, v5, v9
	v_mul_f32_e32 v11, v5, v8
	v_fma_f32 v12, v4, v8, -v10
	v_fma_f32 v13, v4, v9, v11
	s_nop 0
	v_add_f32_e32 v8, v12, v60
	v_add_f32_e32 v9, v13, v61
	global_store_dwordx2 v7, v[8:9], s[8:9]
	s_add_u32 s8, s8, s1
	s_addc_u32 s9, s9, s2
	v_mul_f32_e32 v10, v5, v9
	v_mul_f32_e32 v11, v5, v8
	v_fma_f32 v12, v4, v8, -v10
	v_fma_f32 v13, v4, v9, v11
	s_nop 0
	v_add_f32_e32 v8, v12, v62
	v_add_f32_e32 v9, v13, v63
	global_store_dwordx2 v7, v[8:9], s[8:9]
	s_add_u32 s8, s8, s1
	s_addc_u32 s9, s9, s2
	v_mul_f32_e32 v10, v5, v9
	v_mul_f32_e32 v11, v5, v8
	v_fma_f32 v12, v4, v8, -v10
	v_fma_f32 v13, v4, v9, v11
	s_nop 0
	v_add_f32_e32 v8, v12, v64
	v_add_f32_e32 v9, v13, v65
	global_store_dwordx2 v7, v[8:9], s[8:9]
	s_add_u32 s8, s8, s1
	s_addc_u32 s9, s9, s2
	v_mul_f32_e32 v10, v5, v9
	v_mul_f32_e32 v11, v5, v8
	v_fma_f32 v12, v4, v8, -v10
	v_fma_f32 v13, v4, v9, v11
	s_nop 0
	v_add_f32_e32 v8, v12, v66
	v_add_f32_e32 v9, v13, v67
	global_store_dwordx2 v7, v[8:9], s[8:9]
	s_add_u32 s8, s8, s1
	s_addc_u32 s9, s9, s2
	v_mul_f32_e32 v10, v5, v9
	v_mul_f32_e32 v11, v5, v8
	v_fma_f32 v12, v4, v8, -v10
	v_fma_f32 v13, v4, v9, v11
	s_nop 0
	v_add_f32_e32 v8, v12, v68
	v_add_f32_e32 v9, v13, v69
	global_store_dwordx2 v7, v[8:9], s[8:9]
	s_add_u32 s8, s8, s1
	s_addc_u32 s9, s9, s2
	v_mul_f32_e32 v10, v5, v9
	v_mul_f32_e32 v11, v5, v8
	v_fma_f32 v12, v4, v8, -v10
	v_fma_f32 v13, v4, v9, v11
	s_nop 0
	v_add_f32_e32 v8, v12, v70
	v_add_f32_e32 v9, v13, v71
	global_store_dwordx2 v7, v[8:9], s[8:9]
	s_add_u32 s8, s8, s1
	s_addc_u32 s9, s9, s2
	v_mul_f32_e32 v10, v5, v9
	v_mul_f32_e32 v11, v5, v8
	v_fma_f32 v12, v4, v8, -v10
	v_fma_f32 v13, v4, v9, v11
	s_nop 0
	v_add_f32_e32 v8, v12, v72
	v_add_f32_e32 v9, v13, v73
	global_store_dwordx2 v7, v[8:9], s[8:9]
	s_add_u32 s8, s8, s1
	s_addc_u32 s9, s9, s2
	v_mul_f32_e32 v10, v5, v9
	v_mul_f32_e32 v11, v5, v8
	v_fma_f32 v12, v4, v8, -v10
	v_fma_f32 v13, v4, v9, v11
	s_nop 0
	v_add_f32_e32 v8, v12, v74
	v_add_f32_e32 v9, v13, v75
	global_store_dwordx2 v7, v[8:9], s[8:9]
	s_add_u32 s8, s8, s1
	s_addc_u32 s9, s9, s2
	v_mul_f32_e32 v10, v5, v9
	v_mul_f32_e32 v11, v5, v8
	v_fma_f32 v12, v4, v8, -v10
	v_fma_f32 v13, v4, v9, v11
	s_nop 0
	v_add_f32_e32 v8, v12, v76
	v_add_f32_e32 v9, v13, v77
	global_store_dwordx2 v7, v[8:9], s[8:9]
	s_add_u32 s8, s8, s1
	s_addc_u32 s9, s9, s2
	v_mul_f32_e32 v10, v5, v9
	v_mul_f32_e32 v11, v5, v8
	v_fma_f32 v12, v4, v8, -v10
	v_fma_f32 v13, v4, v9, v11
	s_nop 0
	v_add_f32_e32 v8, v12, v78
	v_add_f32_e32 v9, v13, v79
	global_store_dwordx2 v7, v[8:9], s[8:9]
	s_add_u32 s8, s8, s1
	s_addc_u32 s9, s9, s2
	v_mul_f32_e32 v10, v5, v9
	v_mul_f32_e32 v11, v5, v8
	v_fma_f32 v12, v4, v8, -v10
	v_fma_f32 v13, v4, v9, v11
	s_nop 0
	v_add_f32_e32 v8, v12, v80
	v_add_f32_e32 v9, v13, v81
	global_store_dwordx2 v7, v[8:9], s[8:9]
	s_add_u32 s8, s8, s1
	s_addc_u32 s9, s9, s2
	v_mul_f32_e32 v10, v5, v9
	v_mul_f32_e32 v11, v5, v8
	v_fma_f32 v12, v4, v8, -v10
	v_fma_f32 v13, v4, v9, v11
	s_nop 0
	v_add_f32_e32 v8, v12, v82
	v_add_f32_e32 v9, v13, v83
	global_store_dwordx2 v7, v[8:9], s[8:9]
	s_add_u32 s8, s8, s1
	s_addc_u32 s9, s9, s2
	v_mul_f32_e32 v10, v5, v9
	v_mul_f32_e32 v11, v5, v8
	v_fma_f32 v12, v4, v8, -v10
	v_fma_f32 v13, v4, v9, v11
	s_nop 0
	v_add_f32_e32 v8, v12, v84
	v_add_f32_e32 v9, v13, v85
	global_store_dwordx2 v7, v[8:9], s[8:9]
	s_add_u32 s8, s8, s1
	s_addc_u32 s9, s9, s2
	v_mul_f32_e32 v10, v5, v9
	v_mul_f32_e32 v11, v5, v8
	v_fma_f32 v12, v4, v8, -v10
	v_fma_f32 v13, v4, v9, v11
	s_nop 0
	v_add_f32_e32 v8, v12, v86
	v_add_f32_e32 v9, v13, v87
	global_store_dwordx2 v7, v[8:9], s[8:9]
	s_add_u32 s8, s8, s1
	s_addc_u32 s9, s9, s2
	v_mul_f32_e32 v10, v5, v9
	v_mul_f32_e32 v11, v5, v8
	v_fma_f32 v12, v4, v8, -v10
	v_fma_f32 v13, v4, v9, v11
	s_nop 0
	v_add_f32_e32 v8, v12, v88
	v_add_f32_e32 v9, v13, v89
	global_store_dwordx2 v7, v[8:9], s[8:9]
	s_add_u32 s8, s8, s1
	s_addc_u32 s9, s9, s2
	v_mul_f32_e32 v10, v5, v9
	v_mul_f32_e32 v11, v5, v8
	v_fma_f32 v12, v4, v8, -v10
	v_fma_f32 v13, v4, v9, v11
	s_nop 0
	v_add_f32_e32 v8, v12, v90
	v_add_f32_e32 v9, v13, v91
	global_store_dwordx2 v7, v[8:9], s[8:9]
	s_add_u32 s8, s8, s1
	s_addc_u32 s9, s9, s2
	v_mul_f32_e32 v10, v5, v9
	v_mul_f32_e32 v11, v5, v8
	v_fma_f32 v12, v4, v8, -v10
	v_fma_f32 v13, v4, v9, v11
	s_nop 0
	v_add_f32_e32 v8, v12, v92
	v_add_f32_e32 v9, v13, v93
	global_store_dwordx2 v7, v[8:9], s[8:9]
	s_add_u32 s8, s8, s1
	s_addc_u32 s9, s9, s2
	v_mul_f32_e32 v10, v5, v9
	v_mul_f32_e32 v11, v5, v8
	v_fma_f32 v12, v4, v8, -v10
	v_fma_f32 v13, v4, v9, v11
	s_nop 0
	v_add_f32_e32 v8, v12, v94
	v_add_f32_e32 v9, v13, v95
	global_store_dwordx2 v7, v[8:9], s[8:9]
	s_add_u32 s8, s8, s1
	s_addc_u32 s9, s9, s2
	v_mul_f32_e32 v10, v5, v9
	v_mul_f32_e32 v11, v5, v8
	v_fma_f32 v12, v4, v8, -v10
	v_fma_f32 v13, v4, v9, v11
	s_nop 0
	v_add_f32_e32 v8, v12, v96
	v_add_f32_e32 v9, v13, v97
	global_store_dwordx2 v7, v[8:9], s[8:9]
	s_add_u32 s8, s8, s1
	s_addc_u32 s9, s9, s2
	v_mul_f32_e32 v10, v5, v9
	v_mul_f32_e32 v11, v5, v8
	v_fma_f32 v12, v4, v8, -v10
	v_fma_f32 v13, v4, v9, v11
	s_nop 0
	v_add_f32_e32 v8, v12, v98
	v_add_f32_e32 v9, v13, v99
	global_store_dwordx2 v7, v[8:9], s[8:9]
	s_add_u32 s8, s8, s1
	s_addc_u32 s9, s9, s2
	v_mul_f32_e32 v10, v5, v9
	v_mul_f32_e32 v11, v5, v8
; __device__ void phase_s5_carry(CParams& p, int l, int item) {
;     ...
;   for (int s = 0; s < 132; s++) {
;     int q;
;     if (dir == 0) q = s < 4 ? (256 + 4 * b + s) : (128 * b + (s - 4));
;     else q = s < 4 ? (256 + 4 * b + 3 - s) : (128 * b + 127 - (s - 4));
;     size_t o = ((size_t)q * 2 + dir) * 1024 + gp;
;     float2 e = p.E[o];
;     p.Hin[o] = make_float2(hr, hi);
;     float nr = ar * hr - ai * hi + e.x;
;     float ni = ar * hi + ai * hr + e.y;
;     hr = nr; hi = ni;
;   }
	v_fma_f32 v12, v4, v8, -v10
	v_fma_f32 v13, v4, v9, v11
	s_nop 0
	v_add_f32_e32 v8, v12, v100
	v_add_f32_e32 v9, v13, v101
	global_load_dwordx2 v[58:59], v7, s[6:7]
	s_add_u32 s6, s6, s1
	s_addc_u32 s7, s7, s2
	global_load_dwordx2 v[60:61], v7, s[6:7]
	s_add_u32 s6, s6, s1
	s_addc_u32 s7, s7, s2
	global_load_dwordx2 v[62:63], v7, s[6:7]
	s_add_u32 s6, s6, s1
	s_addc_u32 s7, s7, s2
	global_load_dwordx2 v[64:65], v7, s[6:7]
	s_add_u32 s6, s6, s1
	s_addc_u32 s7, s7, s2
	global_load_dwordx2 v[66:67], v7, s[6:7]
	s_add_u32 s6, s6, s1
	s_addc_u32 s7, s7, s2
	global_load_dwordx2 v[68:69], v7, s[6:7]
	s_add_u32 s6, s6, s1
	s_addc_u32 s7, s7, s2
	global_load_dwordx2 v[70:71], v7, s[6:7]
	s_add_u32 s6, s6, s1
	s_addc_u32 s7, s7, s2
	global_load_dwordx2 v[72:73], v7, s[6:7]
	s_add_u32 s6, s6, s1
	s_addc_u32 s7, s7, s2
	global_load_dwordx2 v[74:75], v7, s[6:7]
	s_add_u32 s6, s6, s1
	s_addc_u32 s7, s7, s2
	global_load_dwordx2 v[76:77], v7, s[6:7]
	s_add_u32 s6, s6, s1
	s_addc_u32 s7, s7, s2
	global_load_dwordx2 v[78:79], v7, s[6:7]
	s_add_u32 s6, s6, s1
	s_addc_u32 s7, s7, s2
	global_load_dwordx2 v[80:81], v7, s[6:7]
	s_add_u32 s6, s6, s1
	s_addc_u32 s7, s7, s2
	global_load_dwordx2 v[82:83], v7, s[6:7]
	s_add_u32 s6, s6, s1
	s_addc_u32 s7, s7, s2
	global_load_dwordx2 v[84:85], v7, s[6:7]
	s_add_u32 s6, s6, s1
	s_addc_u32 s7, s7, s2
	global_load_dwordx2 v[86:87], v7, s[6:7]
	s_add_u32 s6, s6, s1
	s_addc_u32 s7, s7, s2
	global_load_dwordx2 v[88:89], v7, s[6:7]
	s_add_u32 s6, s6, s1
	s_addc_u32 s7, s7, s2
	global_load_dwordx2 v[90:91], v7, s[6:7]
	s_add_u32 s6, s6, s1
	s_addc_u32 s7, s7, s2
	global_load_dwordx2 v[92:93], v7, s[6:7]
	s_add_u32 s6, s6, s1
	s_addc_u32 s7, s7, s2
	global_load_dwordx2 v[94:95], v7, s[6:7]
	s_add_u32 s6, s6, s1
	s_addc_u32 s7, s7, s2
	global_load_dwordx2 v[96:97], v7, s[6:7]
	s_add_u32 s6, s6, s1
	s_addc_u32 s7, s7, s2
	global_load_dwordx2 v[98:99], v7, s[6:7]
	s_add_u32 s6, s6, s1
	s_addc_u32 s7, s7, s2
	global_load_dwordx2 v[100:101], v7, s[6:7]
	s_waitcnt vmcnt(22)
	global_store_dwordx2 v7, v[8:9], s[8:9]
	s_add_u32 s8, s8, s1
	s_addc_u32 s9, s9, s2
	v_mul_f32_e32 v10, v5, v9
	v_mul_f32_e32 v11, v5, v8
	v_fma_f32 v12, v4, v8, -v10
	v_fma_f32 v13, v4, v9, v11
	s_nop 0
	v_add_f32_e32 v8, v12, v14
	v_add_f32_e32 v9, v13, v15
	global_store_dwordx2 v7, v[8:9], s[8:9]
	s_add_u32 s8, s8, s1
	s_addc_u32 s9, s9, s2
	v_mul_f32_e32 v10, v5, v9
	v_mul_f32_e32 v11, v5, v8
	v_fma_f32 v12, v4, v8, -v10
	v_fma_f32 v13, v4, v9, v11
	s_nop 0
	v_add_f32_e32 v8, v12, v16
	v_add_f32_e32 v9, v13, v17
	global_store_dwordx2 v7, v[8:9], s[8:9]
	s_add_u32 s8, s8, s1
	s_addc_u32 s9, s9, s2
	v_mul_f32_e32 v10, v5, v9
	v_mul_f32_e32 v11, v5, v8
	v_fma_f32 v12, v4, v8, -v10
	v_fma_f32 v13, v4, v9, v11
	s_nop 0
	v_add_f32_e32 v8, v12, v18
	v_add_f32_e32 v9, v13, v19
	global_store_dwordx2 v7, v[8:9], s[8:9]
	s_add_u32 s8, s8, s1
	s_addc_u32 s9, s9, s2
	v_mul_f32_e32 v10, v5, v9
	v_mul_f32_e32 v11, v5, v8
	v_fma_f32 v12, v4, v8, -v10
	v_fma_f32 v13, v4, v9, v11
	s_nop 0
	v_add_f32_e32 v8, v12, v20
	v_add_f32_e32 v9, v13, v21
	global_store_dwordx2 v7, v[8:9], s[8:9]
	s_add_u32 s8, s8, s1
	s_addc_u32 s9, s9, s2
	v_mul_f32_e32 v10, v5, v9
	v_mul_f32_e32 v11, v5, v8
	v_fma_f32 v12, v4, v8, -v10
	v_fma_f32 v13, v4, v9, v11
	s_nop 0
	v_add_f32_e32 v8, v12, v22
	v_add_f32_e32 v9, v13, v23
	global_store_dwordx2 v7, v[8:9], s[8:9]
	s_add_u32 s8, s8, s1
	s_addc_u32 s9, s9, s2
	v_mul_f32_e32 v10, v5, v9
	v_mul_f32_e32 v11, v5, v8
	v_fma_f32 v12, v4, v8, -v10
	v_fma_f32 v13, v4, v9, v11
	s_nop 0
	v_add_f32_e32 v8, v12, v24
	v_add_f32_e32 v9, v13, v25
	global_store_dwordx2 v7, v[8:9], s[8:9]
	s_add_u32 s8, s8, s1
	s_addc_u32 s9, s9, s2
	v_mul_f32_e32 v10, v5, v9
	v_mul_f32_e32 v11, v5, v8
	v_fma_f32 v12, v4, v8, -v10
	v_fma_f32 v13, v4, v9, v11
	s_nop 0
	v_add_f32_e32 v8, v12, v26
	v_add_f32_e32 v9, v13, v27
	global_store_dwordx2 v7, v[8:9], s[8:9]
	s_add_u32 s8, s8, s1
	s_addc_u32 s9, s9, s2
	v_mul_f32_e32 v10, v5, v9
	v_mul_f32_e32 v11, v5, v8
	v_fma_f32 v12, v4, v8, -v10
	v_fma_f32 v13, v4, v9, v11
	s_nop 0
	v_add_f32_e32 v8, v12, v28
	v_add_f32_e32 v9, v13, v29
	global_store_dwordx2 v7, v[8:9], s[8:9]
	s_add_u32 s8, s8, s1
	s_addc_u32 s9, s9, s2
	v_mul_f32_e32 v10, v5, v9
	v_mul_f32_e32 v11, v5, v8
	v_fma_f32 v12, v4, v8, -v10
	v_fma_f32 v13, v4, v9, v11
	s_nop 0
	v_add_f32_e32 v8, v12, v30
	v_add_f32_e32 v9, v13, v31
	global_store_dwordx2 v7, v[8:9], s[8:9]
	s_add_u32 s8, s8, s1
	s_addc_u32 s9, s9, s2
	v_mul_f32_e32 v10, v5, v9
	v_mul_f32_e32 v11, v5, v8
	v_fma_f32 v12, v4, v8, -v10
	v_fma_f32 v13, v4, v9, v11
	s_nop 0
	v_add_f32_e32 v8, v12, v32
	v_add_f32_e32 v9, v13, v33
	global_store_dwordx2 v7, v[8:9], s[8:9]
	s_add_u32 s8, s8, s1
	s_addc_u32 s9, s9, s2
	v_mul_f32_e32 v10, v5, v9
	v_mul_f32_e32 v11, v5, v8
	v_fma_f32 v12, v4, v8, -v10
	v_fma_f32 v13, v4, v9, v11
	s_nop 0
	v_add_f32_e32 v8, v12, v34
	v_add_f32_e32 v9, v13, v35
	global_store_dwordx2 v7, v[8:9], s[8:9]
	s_add_u32 s8, s8, s1
	s_addc_u32 s9, s9, s2
	v_mul_f32_e32 v10, v5, v9
	v_mul_f32_e32 v11, v5, v8
	v_fma_f32 v12, v4, v8, -v10
	v_fma_f32 v13, v4, v9, v11
	s_nop 0
	v_add_f32_e32 v8, v12, v36
	v_add_f32_e32 v9, v13, v37
	global_store_dwordx2 v7, v[8:9], s[8:9]
	s_add_u32 s8, s8, s1
	s_addc_u32 s9, s9, s2
	v_mul_f32_e32 v10, v5, v9
	v_mul_f32_e32 v11, v5, v8
	v_fma_f32 v12, v4, v8, -v10
	v_fma_f32 v13, v4, v9, v11
	s_nop 0
	v_add_f32_e32 v8, v12, v38
	v_add_f32_e32 v9, v13, v39
	global_store_dwordx2 v7, v[8:9], s[8:9]
	s_add_u32 s8, s8, s1
	s_addc_u32 s9, s9, s2
	v_mul_f32_e32 v10, v5, v9
	v_mul_f32_e32 v11, v5, v8
	v_fma_f32 v12, v4, v8, -v10
	v_fma_f32 v13, v4, v9, v11
	s_nop 0
; __device__ void phase_s5_carry(CParams& p, int l, int item) {
;     ...
;   for (int s = 0; s < 132; s++) {
;     int q;
;     if (dir == 0) q = s < 4 ? (256 + 4 * b + s) : (128 * b + (s - 4));
;     else q = s < 4 ? (256 + 4 * b + 3 - s) : (128 * b + 127 - (s - 4));
;     size_t o = ((size_t)q * 2 + dir) * 1024 + gp;
;     float2 e = p.E[o];
;     p.Hin[o] = make_float2(hr, hi);
;     float nr = ar * hr - ai * hi + e.x;
;     float ni = ar * hi + ai * hr + e.y;
;     hr = nr; hi = ni;
;   }
	v_add_f32_e32 v8, v12, v40
	v_add_f32_e32 v9, v13, v41
	global_store_dwordx2 v7, v[8:9], s[8:9]
	s_add_u32 s8, s8, s1
	s_addc_u32 s9, s9, s2
	v_mul_f32_e32 v10, v5, v9
	v_mul_f32_e32 v11, v5, v8
	v_fma_f32 v12, v4, v8, -v10
	v_fma_f32 v13, v4, v9, v11
	s_nop 0
	v_add_f32_e32 v8, v12, v42
	v_add_f32_e32 v9, v13, v43
	global_store_dwordx2 v7, v[8:9], s[8:9]
	s_add_u32 s8, s8, s1
	s_addc_u32 s9, s9, s2
	v_mul_f32_e32 v10, v5, v9
	v_mul_f32_e32 v11, v5, v8
	v_fma_f32 v12, v4, v8, -v10
	v_fma_f32 v13, v4, v9, v11
	s_nop 0
	v_add_f32_e32 v8, v12, v44
	v_add_f32_e32 v9, v13, v45
	global_store_dwordx2 v7, v[8:9], s[8:9]
	s_add_u32 s8, s8, s1
	s_addc_u32 s9, s9, s2
	v_mul_f32_e32 v10, v5, v9
	v_mul_f32_e32 v11, v5, v8
	v_fma_f32 v12, v4, v8, -v10
	v_fma_f32 v13, v4, v9, v11
	s_nop 0
	v_add_f32_e32 v8, v12, v46
	v_add_f32_e32 v9, v13, v47
	global_store_dwordx2 v7, v[8:9], s[8:9]
	s_add_u32 s8, s8, s1
	s_addc_u32 s9, s9, s2
	v_mul_f32_e32 v10, v5, v9
	v_mul_f32_e32 v11, v5, v8
	v_fma_f32 v12, v4, v8, -v10
	v_fma_f32 v13, v4, v9, v11
	s_nop 0
	v_add_f32_e32 v8, v12, v48
	v_add_f32_e32 v9, v13, v49
	global_store_dwordx2 v7, v[8:9], s[8:9]
	s_add_u32 s8, s8, s1
	s_addc_u32 s9, s9, s2
	v_mul_f32_e32 v10, v5, v9
	v_mul_f32_e32 v11, v5, v8
	v_fma_f32 v12, v4, v8, -v10
	v_fma_f32 v13, v4, v9, v11
	s_nop 0
	v_add_f32_e32 v8, v12, v50
	v_add_f32_e32 v9, v13, v51
	global_store_dwordx2 v7, v[8:9], s[8:9]
	s_add_u32 s8, s8, s1
	s_addc_u32 s9, s9, s2
	v_mul_f32_e32 v10, v5, v9
	v_mul_f32_e32 v11, v5, v8
	v_fma_f32 v12, v4, v8, -v10
	v_fma_f32 v13, v4, v9, v11
	s_nop 0
	v_add_f32_e32 v8, v12, v52
	v_add_f32_e32 v9, v13, v53
	global_store_dwordx2 v7, v[8:9], s[8:9]
	s_add_u32 s8, s8, s1
	s_addc_u32 s9, s9, s2
	v_mul_f32_e32 v10, v5, v9
	v_mul_f32_e32 v11, v5, v8
	v_fma_f32 v12, v4, v8, -v10
	v_fma_f32 v13, v4, v9, v11
	s_nop 0
	v_add_f32_e32 v8, v12, v54
	v_add_f32_e32 v9, v13, v55
	global_store_dwordx2 v7, v[8:9], s[8:9]
	s_add_u32 s8, s8, s1
	s_addc_u32 s9, s9, s2
	v_mul_f32_e32 v10, v5, v9
	v_mul_f32_e32 v11, v5, v8
	v_fma_f32 v12, v4, v8, -v10
	v_fma_f32 v13, v4, v9, v11
	s_nop 0
	v_add_f32_e32 v8, v12, v56
	v_add_f32_e32 v9, v13, v57
	s_waitcnt vmcnt(0)
; __device__ void phase_s5_carry(CParams& p, int l, int item) {
;     ...
;   for (int s = 0; s < 132; s++) {
;     int q;
;     if (dir == 0) q = s < 4 ? (256 + 4 * b + s) : (128 * b + (s - 4));
;     else q = s < 4 ? (256 + 4 * b + 3 - s) : (128 * b + 127 - (s - 4));
;     size_t o = ((size_t)q * 2 + dir) * 1024 + gp;
;     float2 e = p.E[o];
;     p.Hin[o] = make_float2(hr, hi);
;     float nr = ar * hr - ai * hi + e.x;
;     float ni = ar * hi + ai * hr + e.y;
;     hr = nr; hi = ni;
;   }
; }
	global_store_dwordx2 v7, v[8:9], s[8:9]
	s_add_u32 s8, s8, s1
	s_addc_u32 s9, s9, s2
	v_mul_f32_e32 v10, v5, v9
	v_mul_f32_e32 v11, v5, v8
	v_fma_f32 v12, v4, v8, -v10
	v_fma_f32 v13, v4, v9, v11
	s_nop 0
	v_add_f32_e32 v8, v12, v58
	v_add_f32_e32 v9, v13, v59
	global_store_dwordx2 v7, v[8:9], s[8:9]
	s_add_u32 s8, s8, s1
	s_addc_u32 s9, s9, s2
	v_mul_f32_e32 v10, v5, v9
	v_mul_f32_e32 v11, v5, v8
	v_fma_f32 v12, v4, v8, -v10
	v_fma_f32 v13, v4, v9, v11
	s_nop 0
	v_add_f32_e32 v8, v12, v60
	v_add_f32_e32 v9, v13, v61
	global_store_dwordx2 v7, v[8:9], s[8:9]
	s_add_u32 s8, s8, s1
	s_addc_u32 s9, s9, s2
	v_mul_f32_e32 v10, v5, v9
	v_mul_f32_e32 v11, v5, v8
	v_fma_f32 v12, v4, v8, -v10
	v_fma_f32 v13, v4, v9, v11
	s_nop 0
	v_add_f32_e32 v8, v12, v62
	v_add_f32_e32 v9, v13, v63
	global_store_dwordx2 v7, v[8:9], s[8:9]
	s_add_u32 s8, s8, s1
	s_addc_u32 s9, s9, s2
	v_mul_f32_e32 v10, v5, v9
	v_mul_f32_e32 v11, v5, v8
	v_fma_f32 v12, v4, v8, -v10
	v_fma_f32 v13, v4, v9, v11
	s_nop 0
	v_add_f32_e32 v8, v12, v64
	v_add_f32_e32 v9, v13, v65
	global_store_dwordx2 v7, v[8:9], s[8:9]
	s_add_u32 s8, s8, s1
	s_addc_u32 s9, s9, s2
	v_mul_f32_e32 v10, v5, v9
	v_mul_f32_e32 v11, v5, v8
	v_fma_f32 v12, v4, v8, -v10
	v_fma_f32 v13, v4, v9, v11
	s_nop 0
	v_add_f32_e32 v8, v12, v66
	v_add_f32_e32 v9, v13, v67
	global_store_dwordx2 v7, v[8:9], s[8:9]
	s_add_u32 s8, s8, s1
	s_addc_u32 s9, s9, s2
	v_mul_f32_e32 v10, v5, v9
	v_mul_f32_e32 v11, v5, v8
	v_fma_f32 v12, v4, v8, -v10
	v_fma_f32 v13, v4, v9, v11
	s_nop 0
	v_add_f32_e32 v8, v12, v68
	v_add_f32_e32 v9, v13, v69
	global_store_dwordx2 v7, v[8:9], s[8:9]
	s_add_u32 s8, s8, s1
	s_addc_u32 s9, s9, s2
	v_mul_f32_e32 v10, v5, v9
	v_mul_f32_e32 v11, v5, v8
	v_fma_f32 v12, v4, v8, -v10
	v_fma_f32 v13, v4, v9, v11
	s_nop 0
	v_add_f32_e32 v8, v12, v70
	v_add_f32_e32 v9, v13, v71
	global_store_dwordx2 v7, v[8:9], s[8:9]
	s_add_u32 s8, s8, s1
	s_addc_u32 s9, s9, s2
	v_mul_f32_e32 v10, v5, v9
	v_mul_f32_e32 v11, v5, v8
	v_fma_f32 v12, v4, v8, -v10
	v_fma_f32 v13, v4, v9, v11
	s_nop 0
	v_add_f32_e32 v8, v12, v72
	v_add_f32_e32 v9, v13, v73
	global_store_dwordx2 v7, v[8:9], s[8:9]
	s_add_u32 s8, s8, s1
	s_addc_u32 s9, s9, s2
	v_mul_f32_e32 v10, v5, v9
	v_mul_f32_e32 v11, v5, v8
	v_fma_f32 v12, v4, v8, -v10
	v_fma_f32 v13, v4, v9, v11
	s_nop 0
	v_add_f32_e32 v8, v12, v74
	v_add_f32_e32 v9, v13, v75
	global_store_dwordx2 v7, v[8:9], s[8:9]
	s_add_u32 s8, s8, s1
	s_addc_u32 s9, s9, s2
	v_mul_f32_e32 v10, v5, v9
	v_mul_f32_e32 v11, v5, v8
	v_fma_f32 v12, v4, v8, -v10
	v_fma_f32 v13, v4, v9, v11
	s_nop 0
	v_add_f32_e32 v8, v12, v76
	v_add_f32_e32 v9, v13, v77
	global_store_dwordx2 v7, v[8:9], s[8:9]
	s_add_u32 s8, s8, s1
	s_addc_u32 s9, s9, s2
	v_mul_f32_e32 v10, v5, v9
	v_mul_f32_e32 v11, v5, v8
	v_fma_f32 v12, v4, v8, -v10
	v_fma_f32 v13, v4, v9, v11
	s_nop 0
	v_add_f32_e32 v8, v12, v78
	v_add_f32_e32 v9, v13, v79
	global_store_dwordx2 v7, v[8:9], s[8:9]
	s_add_u32 s8, s8, s1
	s_addc_u32 s9, s9, s2
	v_mul_f32_e32 v10, v5, v9
	v_mul_f32_e32 v11, v5, v8
	v_fma_f32 v12, v4, v8, -v10
	v_fma_f32 v13, v4, v9, v11
	s_nop 0
	v_add_f32_e32 v8, v12, v80
	v_add_f32_e32 v9, v13, v81
	global_store_dwordx2 v7, v[8:9], s[8:9]
	s_add_u32 s8, s8, s1
	s_addc_u32 s9, s9, s2
	v_mul_f32_e32 v10, v5, v9
	v_mul_f32_e32 v11, v5, v8
	v_fma_f32 v12, v4, v8, -v10
	v_fma_f32 v13, v4, v9, v11
	s_nop 0
	v_add_f32_e32 v8, v12, v82
	v_add_f32_e32 v9, v13, v83
	global_store_dwordx2 v7, v[8:9], s[8:9]
	s_add_u32 s8, s8, s1
	s_addc_u32 s9, s9, s2
	v_mul_f32_e32 v10, v5, v9
	v_mul_f32_e32 v11, v5, v8
	v_fma_f32 v12, v4, v8, -v10
	v_fma_f32 v13, v4, v9, v11
	s_nop 0
	v_add_f32_e32 v8, v12, v84
	v_add_f32_e32 v9, v13, v85
	global_store_dwordx2 v7, v[8:9], s[8:9]
	s_add_u32 s8, s8, s1
	s_addc_u32 s9, s9, s2
	v_mul_f32_e32 v10, v5, v9
	v_mul_f32_e32 v11, v5, v8
	v_fma_f32 v12, v4, v8, -v10
	v_fma_f32 v13, v4, v9, v11
	s_nop 0
	v_add_f32_e32 v8, v12, v86
	v_add_f32_e32 v9, v13, v87
	global_store_dwordx2 v7, v[8:9], s[8:9]
	s_add_u32 s8, s8, s1
	s_addc_u32 s9, s9, s2
	v_mul_f32_e32 v10, v5, v9
	v_mul_f32_e32 v11, v5, v8
	v_fma_f32 v12, v4, v8, -v10
	v_fma_f32 v13, v4, v9, v11
	s_nop 0
	v_add_f32_e32 v8, v12, v88
	v_add_f32_e32 v9, v13, v89
	global_store_dwordx2 v7, v[8:9], s[8:9]
	s_add_u32 s8, s8, s1
	s_addc_u32 s9, s9, s2
	v_mul_f32_e32 v10, v5, v9
	v_mul_f32_e32 v11, v5, v8
	v_fma_f32 v12, v4, v8, -v10
	v_fma_f32 v13, v4, v9, v11
	s_nop 0
	v_add_f32_e32 v8, v12, v90
	v_add_f32_e32 v9, v13, v91
	global_store_dwordx2 v7, v[8:9], s[8:9]
	s_add_u32 s8, s8, s1
	s_addc_u32 s9, s9, s2
	v_mul_f32_e32 v10, v5, v9
	v_mul_f32_e32 v11, v5, v8
	v_fma_f32 v12, v4, v8, -v10
	v_fma_f32 v13, v4, v9, v11
	s_nop 0
	v_add_f32_e32 v8, v12, v92
	v_add_f32_e32 v9, v13, v93
	global_store_dwordx2 v7, v[8:9], s[8:9]
	s_add_u32 s8, s8, s1
	s_addc_u32 s9, s9, s2
	v_mul_f32_e32 v10, v5, v9
	v_mul_f32_e32 v11, v5, v8
	v_fma_f32 v12, v4, v8, -v10
	v_fma_f32 v13, v4, v9, v11
	s_nop 0
	v_add_f32_e32 v8, v12, v94
	v_add_f32_e32 v9, v13, v95
	global_store_dwordx2 v7, v[8:9], s[8:9]
	s_add_u32 s8, s8, s1
	s_addc_u32 s9, s9, s2
	v_mul_f32_e32 v10, v5, v9
	v_mul_f32_e32 v11, v5, v8
	v_fma_f32 v12, v4, v8, -v10
	v_fma_f32 v13, v4, v9, v11
	s_nop 0
	v_add_f32_e32 v8, v12, v96
	v_add_f32_e32 v9, v13, v97
	global_store_dwordx2 v7, v[8:9], s[8:9]
	s_add_u32 s8, s8, s1
	s_addc_u32 s9, s9, s2
	v_mul_f32_e32 v10, v5, v9
	v_mul_f32_e32 v11, v5, v8
	v_fma_f32 v12, v4, v8, -v10
	v_fma_f32 v13, v4, v9, v11
	s_nop 0
	v_add_f32_e32 v8, v12, v98
	v_add_f32_e32 v9, v13, v99
	global_store_dwordx2 v7, v[8:9], s[8:9]
	v_mul_f32_e32 v10, v5, v9
	v_mul_f32_e32 v11, v5, v8
	v_fma_f32 v12, v4, v8, -v10
	v_fma_f32 v13, v4, v9, v11
	s_nop 0
	v_add_f32_e32 v8, v12, v100
	v_add_f32_e32 v9, v13, v101
	s_mov_b64 s[42:43], 0
	s_mov_b64 s[44:45], 0
	s_branch .LBB0_443

; __device__ __forceinline__ int otid() { int t = threadIdx.x; asm volatile("" : "+v"(t)); return t; }
; template <int NI> ...
;     ...
;   const int lane = tid & 63, wid = tid >> 6, wr = wid >> 1, wc = wid & 1;
;   const int lrow = tid >> 2, lch = (tid & 3) * 8;
;   const int l15 = lane & 15, lq = lane >> 4;
;   const bf16_t* pa = A + (size_t)lrow * lda + lch;
;   const bf16_t* pb = B + (size_t)lrow * ldb + lch;
;   const size_t a64 = (size_t)64 * lda, b64 = (size_t)64 * ldb;
;   u32x4 a0[2], a1[2], b0[NB], b1[NB];
;   const int nk = K >> 5;
;   const int klast = K - 32;
;   const int wofs = lrow * GROW + lch;
;   const int raofs = (wr * 64 + l15) * GROW + lq * 8;
;   const int rbofs = 128 * GROW + (wc * (16 * NI) + l15) * GROW + lq * 8;
;     ...
;   G_LOAD(a0, b0, 0);
;   G_LOAD(a1, b1, 32);
;   __syncthreads();
;   G_WRITE(a0, b0, 0);
;   __syncthreads();
; __device__ void phase_proj_res(CParams& p, int l, int tm, int tn, char* smem, const bf16_t* A, int K,
;                                const bf16_t* Bt, int gate_off, float gscale) {
;   const int tid = otid();
;   bf16_t* sA = (bf16_t*)smem;
;   bf16_t* sB = sA + 128 * LDSS;
;   int row0 = tm * 128, col0 = tn * 128;
;   f32x4 acc[4][4];
;   zero_acc<4>(acc);
;   gemm_mainloop<4>(A + (size_t)row0 * K, K, Bt + (size_t)col0 * K, K, K, sA, sB, acc, tid);
.LBB0_946:
	s_or_b64 exec, exec, s[22:23]
	s_mov_b64 s[42:43], s[34:35]
	s_waitcnt lgkmcnt(0)
	s_barrier
	s_lshl_b64 s[6:7], s[0:1], 21
	s_load_dwordx2 s[8:9], s[42:43], 0x118
	s_load_dwordx2 s[22:23], s[42:43], 0x1d8
	s_load_dwordx2 s[24:25], s[42:43], 0x160
	s_load_dwordx2 s[44:45], s[42:43], 0x148
	s_load_dwordx2 s[48:49], s[42:43], 0xf8
	s_waitcnt lgkmcnt(0)
	s_add_u32 s2, s8, s6
	s_addc_u32 s4, s9, s7
	v_readlane_b32 s6, v225, 63
	v_readlane_b32 s7, v224, 0
	s_add_u32 s50, s2, s6
	s_addc_u32 s51, s4, s7
	s_mov_b32 s2, 0
	s_mov_b64 exec, -1
	ds_read_b128 v[236:239], v145 offset:40960
	s_load_dwordx2 s[0:1], s[34:35], 0x1d8
	s_load_dwordx2 s[6:7], s[34:35], 0x118
	s_load_dwordx2 s[18:19], s[34:35], 0xf8
	s_load_dwordx2 s[22:23], s[34:35], 0x160
	v_readlane_b32 s2, v224, 26
	v_readlane_b32 s4, v225, 4
	v_readfirstlane_b32 s32, v147
	v_and_b32_e32 v250, 63, v147
	s_nop 3
	s_lshr_b32 s32, s32, 6
	s_lshl_b32 s24, s32, 11
	s_lshl_b32 s25, s32, 12
	v_lshrrev_b32_e32 v251, 2, v250
	v_and_b32_e32 v252, 3, v250
	v_lshrrev_b32_e32 v253, 4, v250
	v_sub_u32_e32 v253, 0, v253
	v_and_b32_e32 v253, 3, v253
	v_xor_b32_e32 v253, v252, v253
	v_lshlrev_b32_e32 v253, 4, v253
	s_lshl_b32 s29, s32, 5
	v_add_u32_e32 v252, s29, v251
	s_mov_b32 s44, 0x800
	v_mul_lo_u32 v240, v252, s44
	v_add_u32_e32 v240, v240, v253
	v_add_u32_e32 v241, 0x8000, v240
	s_lshl_b32 s29, s32, 6
	v_add_u32_e32 v252, s29, v251
	s_mov_b32 s44, 0x800
	v_mul_lo_u32 v242, v252, s44
	v_add_u32_e32 v242, v242, v253
	v_add_u32_e32 v243, 0x8000, v242
	v_add_u32_e32 v244, 0x10000, v242
	v_add_u32_e32 v245, 0x18000, v242
	v_and_b32_e32 v251, 15, v250
	v_lshrrev_b32_e32 v252, 2, v251
	v_sub_u32_e32 v252, 0, v252
	v_and_b32_e32 v252, 3, v252
	v_lshrrev_b32_e32 v253, 4, v250
	v_xor_b32_e32 v252, v253, v252
	v_lshlrev_b32_e32 v252, 4, v252
	s_lshr_b32 s29, s32, 1
	s_and_b32 s44, s32, 1
	s_lshl_b32 s45, s29, 6
	s_lshl_b32 s50, s44, 7
	v_add_u32_e32 v246, s45, v251
	v_lshl_add_u32 v246, v246, 6, v252
	v_add_u32_e32 v247, s50, v251
	v_lshl_add_u32 v247, v247, 6, v252
	v_add_u32_e32 v247, 0x2000, v247
	v_lshl_add_u32 v249, v253, 2, s50
	v_lshlrev_b32_e32 v249, 2, v249
	v_add_u32_e32 v248, s45, v251
	v_lshl_add_u32 v248, v248, 12, v249
	s_waitcnt lgkmcnt(0)
	s_mov_b32 s51, 0
.Loutp_tile:
	s_and_b32 s29, s4, 7
	s_lshl_b32 s29, s29, 4
	s_lshr_b32 s44, s4, 5
	s_add_u32 s29, s29, s44
	s_lshl_b32 s26, s29, 7
	s_lshr_b32 s44, s4, 3
	s_and_b32 s44, s44, 3
	s_lshl_b32 s27, s44, 8
	s_mul_i32 s29, s26, 0x800
	s_add_u32 s8, s0, s29
	s_addc_u32 s9, s1, 0
	s_mul_i32 s29, s2, 0x200000
	s_mul_i32 s44, s27, 0x800
	s_add_u32 s29, s29, s44
	s_add_u32 s12, s6, s29
	s_addc_u32 s13, s7, 0
	s_barrier
	s_add_u32 m0, s24, 0x0
	s_nop 0
	global_load_lds_dwordx4 v240, s[8:9]
	s_add_u32 m0, s24, 0x400
	s_nop 0
	global_load_lds_dwordx4 v241, s[8:9]
	s_add_u32 m0, s25, 0x2000
	s_nop 0
	global_load_lds_dwordx4 v242, s[12:13]
	s_add_u32 m0, s25, 0x2400
	s_nop 0
	global_load_lds_dwordx4 v243, s[12:13]
	s_add_u32 m0, s25, 0x2800
	s_nop 0
	global_load_lds_dwordx4 v244, s[12:13]
	s_add_u32 m0, s25, 0x2c00
	s_nop 0
	global_load_lds_dwordx4 v245, s[12:13]
	s_add_u32 s8, s8, 64
	s_addc_u32 s9, s9, 0
	s_add_u32 s12, s12, 64
	s_addc_u32 s13, s13, 0
	s_add_u32 m0, s24, 0x6000
	s_nop 0
	global_load_lds_dwordx4 v240, s[8:9]
	s_add_u32 m0, s24, 0x6400
	s_nop 0
	global_load_lds_dwordx4 v241, s[8:9]
	s_add_u32 m0, s25, 0x8000
	s_nop 0
	global_load_lds_dwordx4 v242, s[12:13]
	s_add_u32 m0, s25, 0x8400
	s_nop 0
	global_load_lds_dwordx4 v243, s[12:13]
	s_add_u32 m0, s25, 0x8800
	s_nop 0
	global_load_lds_dwordx4 v244, s[12:13]
	s_add_u32 m0, s25, 0x8c00
	s_nop 0
	global_load_lds_dwordx4 v245, s[12:13]
	s_add_u32 s8, s8, 64
	s_addc_u32 s9, s9, 0
	s_add_u32 s12, s12, 64
	s_addc_u32 s13, s13, 0
	s_add_u32 m0, s24, 0xc000
	s_nop 0
	global_load_lds_dwordx4 v240, s[8:9]
	s_add_u32 m0, s24, 0xc400
	s_nop 0
	global_load_lds_dwordx4 v241, s[8:9]
	s_add_u32 m0, s25, 0xe000
	s_nop 0
	global_load_lds_dwordx4 v242, s[12:13]
	s_add_u32 m0, s25, 0xe400
	s_nop 0
	global_load_lds_dwordx4 v243, s[12:13]
	s_add_u32 m0, s25, 0xe800
	s_nop 0
	global_load_lds_dwordx4 v244, s[12:13]
	s_add_u32 m0, s25, 0xec00
	s_nop 0
	global_load_lds_dwordx4 v245, s[12:13]
	s_add_u32 s8, s8, 64
	s_addc_u32 s9, s9, 0
	s_add_u32 s12, s12, 64
	s_addc_u32 s13, s13, 0
	v_mov_b32_e32 v0, 0
	v_mov_b32_e32 v1, 0
	v_mov_b32_e32 v2, 0
	v_mov_b32_e32 v3, 0
	v_mov_b32_e32 v4, 0
	v_mov_b32_e32 v5, 0
	v_mov_b32_e32 v6, 0
	v_mov_b32_e32 v7, 0
	v_mov_b32_e32 v8, 0
	v_mov_b32_e32 v9, 0
	v_mov_b32_e32 v10, 0
	v_mov_b32_e32 v11, 0
	v_mov_b32_e32 v12, 0
	v_mov_b32_e32 v13, 0
	v_mov_b32_e32 v14, 0
	v_mov_b32_e32 v15, 0
	v_mov_b32_e32 v16, 0
	v_mov_b32_e32 v17, 0
	v_mov_b32_e32 v18, 0
	v_mov_b32_e32 v19, 0
	v_mov_b32_e32 v20, 0
	v_mov_b32_e32 v21, 0
	v_mov_b32_e32 v22, 0
	v_mov_b32_e32 v23, 0
	v_mov_b32_e32 v24, 0
	v_mov_b32_e32 v25, 0
	v_mov_b32_e32 v26, 0
	v_mov_b32_e32 v27, 0
	v_mov_b32_e32 v28, 0
	v_mov_b32_e32 v29, 0
	v_mov_b32_e32 v30, 0
	v_mov_b32_e32 v31, 0
	v_mov_b32_e32 v32, 0
	v_mov_b32_e32 v33, 0
	v_mov_b32_e32 v34, 0
	v_mov_b32_e32 v35, 0
	v_mov_b32_e32 v36, 0
	v_mov_b32_e32 v37, 0
	v_mov_b32_e32 v38, 0
	v_mov_b32_e32 v39, 0
	v_mov_b32_e32 v40, 0
	v_mov_b32_e32 v41, 0
	v_mov_b32_e32 v42, 0
	v_mov_b32_e32 v43, 0
	v_mov_b32_e32 v44, 0
	v_mov_b32_e32 v45, 0
	v_mov_b32_e32 v46, 0
	v_mov_b32_e32 v47, 0
	v_mov_b32_e32 v48, 0
	v_mov_b32_e32 v49, 0
	v_mov_b32_e32 v50, 0
	v_mov_b32_e32 v51, 0
	v_mov_b32_e32 v52, 0
	v_mov_b32_e32 v53, 0
	v_mov_b32_e32 v54, 0
	v_mov_b32_e32 v55, 0
	v_mov_b32_e32 v56, 0
	v_mov_b32_e32 v57, 0
	v_mov_b32_e32 v58, 0
	v_mov_b32_e32 v59, 0
	v_mov_b32_e32 v60, 0
	v_mov_b32_e32 v61, 0
; template <int NI> ...
;     ...
;   for (int kt = 0; kt < nk; kt += 2) {
;     G_LOAD(a0, b0, min((kt + 2) * 32, klast));
;     G_COMPUTE(0);
;     G_WRITE(a1, b1, 1);
;     __syncthreads();
;     G_LOAD(a1, b1, min((kt + 3) * 32, klast));
;     G_COMPUTE(1);
	v_mov_b32_e32 v62, 0
	v_mov_b32_e32 v63, 0
	v_mov_b32_e32 v64, 0
	v_mov_b32_e32 v65, 0
	v_mov_b32_e32 v66, 0
	v_mov_b32_e32 v67, 0
	v_mov_b32_e32 v68, 0
	v_mov_b32_e32 v69, 0
	v_mov_b32_e32 v70, 0
	v_mov_b32_e32 v71, 0
	v_mov_b32_e32 v72, 0
	v_mov_b32_e32 v73, 0
	v_mov_b32_e32 v74, 0
	v_mov_b32_e32 v75, 0
	v_mov_b32_e32 v76, 0
	v_mov_b32_e32 v77, 0
	v_mov_b32_e32 v78, 0
	v_mov_b32_e32 v79, 0
	v_mov_b32_e32 v80, 0
	v_mov_b32_e32 v81, 0
	v_mov_b32_e32 v82, 0
	v_mov_b32_e32 v83, 0
	v_mov_b32_e32 v84, 0
	v_mov_b32_e32 v85, 0
	v_mov_b32_e32 v86, 0
	v_mov_b32_e32 v87, 0
	v_mov_b32_e32 v88, 0
	v_mov_b32_e32 v89, 0
	v_mov_b32_e32 v90, 0
	v_mov_b32_e32 v91, 0
	v_mov_b32_e32 v92, 0
	v_mov_b32_e32 v93, 0
	v_mov_b32_e32 v94, 0
	v_mov_b32_e32 v95, 0
	v_mov_b32_e32 v96, 0
	v_mov_b32_e32 v97, 0
	v_mov_b32_e32 v98, 0
	v_mov_b32_e32 v99, 0
	v_mov_b32_e32 v100, 0
	v_mov_b32_e32 v101, 0
	v_mov_b32_e32 v102, 0
	v_mov_b32_e32 v103, 0
	v_mov_b32_e32 v104, 0
	v_mov_b32_e32 v105, 0
	v_mov_b32_e32 v106, 0
	v_mov_b32_e32 v107, 0
	v_mov_b32_e32 v108, 0
	v_mov_b32_e32 v109, 0
	v_mov_b32_e32 v110, 0
	v_mov_b32_e32 v111, 0
	v_mov_b32_e32 v112, 0
	v_mov_b32_e32 v113, 0
	v_mov_b32_e32 v114, 0
	v_mov_b32_e32 v115, 0
	v_mov_b32_e32 v116, 0
	v_mov_b32_e32 v117, 0
	v_mov_b32_e32 v118, 0
	v_mov_b32_e32 v119, 0
	v_mov_b32_e32 v120, 0
	v_mov_b32_e32 v121, 0
	v_mov_b32_e32 v122, 0
	v_mov_b32_e32 v123, 0
	v_mov_b32_e32 v124, 0
	v_mov_b32_e32 v125, 0
	v_mov_b32_e32 v126, 0
	v_mov_b32_e32 v127, 0
	s_waitcnt vmcnt(12)
	s_barrier
	ds_read_b128 v[128:131], v246 offset:0
	ds_read_b128 v[148:151], v247 offset:0
	ds_read_b128 v[152:155], v247 offset:1024
	ds_read_b128 v[132:135], v246 offset:1024
	ds_read_b128 v[156:159], v247 offset:2048
	ds_read_b128 v[160:163], v247 offset:3072
	ds_read_b128 v[136:139], v246 offset:2048
	ds_read_b128 v[168:171], v247 offset:4096
	ds_read_b128 v[172:175], v247 offset:5120
	ds_read_b128 v[140:143], v246 offset:3072
	ds_read_b128 v[176:179], v247 offset:6144
	ds_read_b128 v[180:183], v247 offset:7168
	s_mov_b32 s28, 0
.Loutp_kloop:
	s_waitcnt vmcnt(6) lgkmcnt(0)
	s_barrier
	s_add_u32 m0, s24, 0x0
	s_nop 0
	global_load_lds_dwordx4 v240, s[8:9]
	s_add_u32 m0, s24, 0x400
	s_nop 0
	global_load_lds_dwordx4 v241, s[8:9]
	s_add_u32 m0, s25, 0x2000
	s_nop 0
	global_load_lds_dwordx4 v242, s[12:13]
	s_add_u32 m0, s25, 0x2400
	s_nop 0
	global_load_lds_dwordx4 v243, s[12:13]
	s_add_u32 m0, s25, 0x2800
	s_nop 0
	global_load_lds_dwordx4 v244, s[12:13]
	s_add_u32 m0, s25, 0x2c00
	s_nop 0
	global_load_lds_dwordx4 v245, s[12:13]
	s_add_u32 s8, s8, 64
	s_addc_u32 s9, s9, 0
	s_add_u32 s12, s12, 64
	s_addc_u32 s13, s13, 0
	v_mfma_f32_16x16x32_bf16 v[0:3], v[148:151], v[128:131], v[0:3]
	ds_read_b128 v[184:187], v246 offset:24576
	v_mfma_f32_16x16x32_bf16 v[4:7], v[152:155], v[128:131], v[4:7]
	ds_read_b128 v[200:203], v247 offset:24576
	v_mfma_f32_16x16x32_bf16 v[8:11], v[156:159], v[128:131], v[8:11]
	ds_read_b128 v[204:207], v247 offset:25600
	v_mfma_f32_16x16x32_bf16 v[12:15], v[160:163], v[128:131], v[12:15]
	ds_read_b128 v[188:191], v246 offset:25600
	v_mfma_f32_16x16x32_bf16 v[16:19], v[168:171], v[128:131], v[16:19]
	ds_read_b128 v[208:211], v247 offset:26624
	v_mfma_f32_16x16x32_bf16 v[20:23], v[172:175], v[128:131], v[20:23]
	ds_read_b128 v[212:215], v247 offset:27648
	v_mfma_f32_16x16x32_bf16 v[24:27], v[176:179], v[128:131], v[24:27]
	ds_read_b128 v[192:195], v246 offset:26624
	v_mfma_f32_16x16x32_bf16 v[28:31], v[180:183], v[128:131], v[28:31]
	ds_read_b128 v[216:219], v247 offset:28672
	v_mfma_f32_16x16x32_bf16 v[32:35], v[148:151], v[132:135], v[32:35]
	ds_read_b128 v[220:223], v247 offset:29696
	v_mfma_f32_16x16x32_bf16 v[36:39], v[152:155], v[132:135], v[36:39]
	ds_read_b128 v[196:199], v246 offset:27648
	v_mfma_f32_16x16x32_bf16 v[40:43], v[156:159], v[132:135], v[40:43]
	ds_read_b128 v[228:231], v247 offset:30720
	v_mfma_f32_16x16x32_bf16 v[44:47], v[160:163], v[132:135], v[44:47]
	ds_read_b128 v[232:235], v247 offset:31744
	v_mfma_f32_16x16x32_bf16 v[48:51], v[168:171], v[132:135], v[48:51]
	v_mfma_f32_16x16x32_bf16 v[52:55], v[172:175], v[132:135], v[52:55]
	v_mfma_f32_16x16x32_bf16 v[56:59], v[176:179], v[132:135], v[56:59]
	v_mfma_f32_16x16x32_bf16 v[60:63], v[180:183], v[132:135], v[60:63]
	v_mfma_f32_16x16x32_bf16 v[64:67], v[148:151], v[136:139], v[64:67]
	v_mfma_f32_16x16x32_bf16 v[68:71], v[152:155], v[136:139], v[68:71]
	v_mfma_f32_16x16x32_bf16 v[72:75], v[156:159], v[136:139], v[72:75]
	v_mfma_f32_16x16x32_bf16 v[76:79], v[160:163], v[136:139], v[76:79]
	v_mfma_f32_16x16x32_bf16 v[80:83], v[168:171], v[136:139], v[80:83]
	v_mfma_f32_16x16x32_bf16 v[84:87], v[172:175], v[136:139], v[84:87]
	v_mfma_f32_16x16x32_bf16 v[88:91], v[176:179], v[136:139], v[88:91]
	v_mfma_f32_16x16x32_bf16 v[92:95], v[180:183], v[136:139], v[92:95]
	v_mfma_f32_16x16x32_bf16 v[96:99], v[148:151], v[140:143], v[96:99]
	v_mfma_f32_16x16x32_bf16 v[100:103], v[152:155], v[140:143], v[100:103]
	v_mfma_f32_16x16x32_bf16 v[104:107], v[156:159], v[140:143], v[104:107]
	v_mfma_f32_16x16x32_bf16 v[108:111], v[160:163], v[140:143], v[108:111]
	v_mfma_f32_16x16x32_bf16 v[112:115], v[168:171], v[140:143], v[112:115]
	v_mfma_f32_16x16x32_bf16 v[116:119], v[172:175], v[140:143], v[116:119]
	v_mfma_f32_16x16x32_bf16 v[120:123], v[176:179], v[140:143], v[120:123]
	v_mfma_f32_16x16x32_bf16 v[124:127], v[180:183], v[140:143], v[124:127]
	s_waitcnt vmcnt(6) lgkmcnt(0)
	s_barrier
; template <int NI> ...
;     ...
;   for (int kt = 0; kt < nk; kt += 2) {
;     G_LOAD(a0, b0, min((kt + 2) * 32, klast));
;     G_COMPUTE(0);
;     G_WRITE(a1, b1, 1);
;     __syncthreads();
;     G_LOAD(a1, b1, min((kt + 3) * 32, klast));
;     G_COMPUTE(1);
;     G_WRITE(a0, b0, 0);
;     __syncthreads();
;   }
	s_add_u32 m0, s24, 0x6000
	s_nop 0
	global_load_lds_dwordx4 v240, s[8:9]
	s_add_u32 m0, s24, 0x6400
	s_nop 0
	global_load_lds_dwordx4 v241, s[8:9]
	s_add_u32 m0, s25, 0x8000
	s_nop 0
	global_load_lds_dwordx4 v242, s[12:13]
	s_add_u32 m0, s25, 0x8400
	s_nop 0
	global_load_lds_dwordx4 v243, s[12:13]
	s_add_u32 m0, s25, 0x8800
	s_nop 0
	global_load_lds_dwordx4 v244, s[12:13]
	s_add_u32 m0, s25, 0x8c00
	s_nop 0
	global_load_lds_dwordx4 v245, s[12:13]
	s_add_u32 s8, s8, 64
	s_addc_u32 s9, s9, 0
	s_add_u32 s12, s12, 64
	s_addc_u32 s13, s13, 0
	v_mfma_f32_16x16x32_bf16 v[0:3], v[200:203], v[184:187], v[0:3]
	ds_read_b128 v[128:131], v246 offset:49152
	v_mfma_f32_16x16x32_bf16 v[4:7], v[204:207], v[184:187], v[4:7]
	ds_read_b128 v[148:151], v247 offset:49152
	v_mfma_f32_16x16x32_bf16 v[8:11], v[208:211], v[184:187], v[8:11]
	ds_read_b128 v[152:155], v247 offset:50176
	v_mfma_f32_16x16x32_bf16 v[12:15], v[212:215], v[184:187], v[12:15]
	ds_read_b128 v[132:135], v246 offset:50176
	v_mfma_f32_16x16x32_bf16 v[16:19], v[216:219], v[184:187], v[16:19]
	ds_read_b128 v[156:159], v247 offset:51200
	v_mfma_f32_16x16x32_bf16 v[20:23], v[220:223], v[184:187], v[20:23]
	ds_read_b128 v[160:163], v247 offset:52224
	v_mfma_f32_16x16x32_bf16 v[24:27], v[228:231], v[184:187], v[24:27]
	ds_read_b128 v[136:139], v246 offset:51200
	v_mfma_f32_16x16x32_bf16 v[28:31], v[232:235], v[184:187], v[28:31]
	ds_read_b128 v[168:171], v247 offset:53248
	v_mfma_f32_16x16x32_bf16 v[32:35], v[200:203], v[188:191], v[32:35]
	ds_read_b128 v[172:175], v247 offset:54272
	v_mfma_f32_16x16x32_bf16 v[36:39], v[204:207], v[188:191], v[36:39]
	ds_read_b128 v[140:143], v246 offset:52224
	v_mfma_f32_16x16x32_bf16 v[40:43], v[208:211], v[188:191], v[40:43]
	ds_read_b128 v[176:179], v247 offset:55296
	v_mfma_f32_16x16x32_bf16 v[44:47], v[212:215], v[188:191], v[44:47]
	ds_read_b128 v[180:183], v247 offset:56320
	v_mfma_f32_16x16x32_bf16 v[48:51], v[216:219], v[188:191], v[48:51]
	v_mfma_f32_16x16x32_bf16 v[52:55], v[220:223], v[188:191], v[52:55]
	v_mfma_f32_16x16x32_bf16 v[56:59], v[228:231], v[188:191], v[56:59]
	v_mfma_f32_16x16x32_bf16 v[60:63], v[232:235], v[188:191], v[60:63]
	v_mfma_f32_16x16x32_bf16 v[64:67], v[200:203], v[192:195], v[64:67]
	v_mfma_f32_16x16x32_bf16 v[68:71], v[204:207], v[192:195], v[68:71]
	v_mfma_f32_16x16x32_bf16 v[72:75], v[208:211], v[192:195], v[72:75]
	v_mfma_f32_16x16x32_bf16 v[76:79], v[212:215], v[192:195], v[76:79]
	v_mfma_f32_16x16x32_bf16 v[80:83], v[216:219], v[192:195], v[80:83]
	v_mfma_f32_16x16x32_bf16 v[84:87], v[220:223], v[192:195], v[84:87]
	v_mfma_f32_16x16x32_bf16 v[88:91], v[228:231], v[192:195], v[88:91]
	v_mfma_f32_16x16x32_bf16 v[92:95], v[232:235], v[192:195], v[92:95]
	v_mfma_f32_16x16x32_bf16 v[96:99], v[200:203], v[196:199], v[96:99]
	v_mfma_f32_16x16x32_bf16 v[100:103], v[204:207], v[196:199], v[100:103]
	v_mfma_f32_16x16x32_bf16 v[104:107], v[208:211], v[196:199], v[104:107]
	v_mfma_f32_16x16x32_bf16 v[108:111], v[212:215], v[196:199], v[108:111]
	v_mfma_f32_16x16x32_bf16 v[112:115], v[216:219], v[196:199], v[112:115]
	v_mfma_f32_16x16x32_bf16 v[116:119], v[220:223], v[196:199], v[116:119]
	v_mfma_f32_16x16x32_bf16 v[120:123], v[228:231], v[196:199], v[120:123]
	v_mfma_f32_16x16x32_bf16 v[124:127], v[232:235], v[196:199], v[124:127]
	s_waitcnt vmcnt(6) lgkmcnt(0)
	s_barrier
	s_add_u32 m0, s24, 0xc000
	s_nop 0
	global_load_lds_dwordx4 v240, s[8:9]
	s_add_u32 m0, s24, 0xc400
	s_nop 0
	global_load_lds_dwordx4 v241, s[8:9]
	s_add_u32 m0, s25, 0xe000
	s_nop 0
	global_load_lds_dwordx4 v242, s[12:13]
	s_add_u32 m0, s25, 0xe400
	s_nop 0
	global_load_lds_dwordx4 v243, s[12:13]
	s_add_u32 m0, s25, 0xe800
	s_nop 0
	global_load_lds_dwordx4 v244, s[12:13]
	s_add_u32 m0, s25, 0xec00
	s_nop 0
	global_load_lds_dwordx4 v245, s[12:13]
	s_add_u32 s8, s8, 64
	s_addc_u32 s9, s9, 0
	s_add_u32 s12, s12, 64
	s_addc_u32 s13, s13, 0
	v_mfma_f32_16x16x32_bf16 v[0:3], v[148:151], v[128:131], v[0:3]
	ds_read_b128 v[184:187], v246 offset:0
	v_mfma_f32_16x16x32_bf16 v[4:7], v[152:155], v[128:131], v[4:7]
	ds_read_b128 v[200:203], v247 offset:0
	v_mfma_f32_16x16x32_bf16 v[8:11], v[156:159], v[128:131], v[8:11]
	ds_read_b128 v[204:207], v247 offset:1024
	v_mfma_f32_16x16x32_bf16 v[12:15], v[160:163], v[128:131], v[12:15]
	ds_read_b128 v[188:191], v246 offset:1024
	v_mfma_f32_16x16x32_bf16 v[16:19], v[168:171], v[128:131], v[16:19]
	ds_read_b128 v[208:211], v247 offset:2048
	v_mfma_f32_16x16x32_bf16 v[20:23], v[172:175], v[128:131], v[20:23]
	ds_read_b128 v[212:215], v247 offset:3072
	v_mfma_f32_16x16x32_bf16 v[24:27], v[176:179], v[128:131], v[24:27]
	ds_read_b128 v[192:195], v246 offset:2048
	v_mfma_f32_16x16x32_bf16 v[28:31], v[180:183], v[128:131], v[28:31]
	ds_read_b128 v[216:219], v247 offset:4096
	v_mfma_f32_16x16x32_bf16 v[32:35], v[148:151], v[132:135], v[32:35]
	ds_read_b128 v[220:223], v247 offset:5120
	v_mfma_f32_16x16x32_bf16 v[36:39], v[152:155], v[132:135], v[36:39]
	ds_read_b128 v[196:199], v246 offset:3072
	v_mfma_f32_16x16x32_bf16 v[40:43], v[156:159], v[132:135], v[40:43]
	ds_read_b128 v[228:231], v247 offset:6144
	v_mfma_f32_16x16x32_bf16 v[44:47], v[160:163], v[132:135], v[44:47]
	ds_read_b128 v[232:235], v247 offset:7168
	v_mfma_f32_16x16x32_bf16 v[48:51], v[168:171], v[132:135], v[48:51]
	v_mfma_f32_16x16x32_bf16 v[52:55], v[172:175], v[132:135], v[52:55]
	v_mfma_f32_16x16x32_bf16 v[56:59], v[176:179], v[132:135], v[56:59]
	v_mfma_f32_16x16x32_bf16 v[60:63], v[180:183], v[132:135], v[60:63]
	v_mfma_f32_16x16x32_bf16 v[64:67], v[148:151], v[136:139], v[64:67]
	v_mfma_f32_16x16x32_bf16 v[68:71], v[152:155], v[136:139], v[68:71]
	v_mfma_f32_16x16x32_bf16 v[72:75], v[156:159], v[136:139], v[72:75]
	v_mfma_f32_16x16x32_bf16 v[76:79], v[160:163], v[136:139], v[76:79]
	v_mfma_f32_16x16x32_bf16 v[80:83], v[168:171], v[136:139], v[80:83]
	v_mfma_f32_16x16x32_bf16 v[84:87], v[172:175], v[136:139], v[84:87]
	v_mfma_f32_16x16x32_bf16 v[88:91], v[176:179], v[136:139], v[88:91]
	v_mfma_f32_16x16x32_bf16 v[92:95], v[180:183], v[136:139], v[92:95]
	v_mfma_f32_16x16x32_bf16 v[96:99], v[148:151], v[140:143], v[96:99]
	v_mfma_f32_16x16x32_bf16 v[100:103], v[152:155], v[140:143], v[100:103]
	v_mfma_f32_16x16x32_bf16 v[104:107], v[156:159], v[140:143], v[104:107]
	v_mfma_f32_16x16x32_bf16 v[108:111], v[160:163], v[140:143], v[108:111]
	v_mfma_f32_16x16x32_bf16 v[112:115], v[168:171], v[140:143], v[112:115]
	v_mfma_f32_16x16x32_bf16 v[116:119], v[172:175], v[140:143], v[116:119]
	v_mfma_f32_16x16x32_bf16 v[120:123], v[176:179], v[140:143], v[120:123]
	v_mfma_f32_16x16x32_bf16 v[124:127], v[180:183], v[140:143], v[124:127]
	s_waitcnt vmcnt(6) lgkmcnt(0)
	s_barrier
; template <int NI> ...
;     ...
;   for (int kt = 0; kt < nk; kt += 2) {
;     G_LOAD(a0, b0, min((kt + 2) * 32, klast));
;     G_COMPUTE(0);
;     G_WRITE(a1, b1, 1);
;     __syncthreads();
;     G_LOAD(a1, b1, min((kt + 3) * 32, klast));
;     G_COMPUTE(1);
;     G_WRITE(a0, b0, 0);
;     __syncthreads();
;   }
	s_add_u32 m0, s24, 0x0
	s_nop 0
	global_load_lds_dwordx4 v240, s[8:9]
	s_add_u32 m0, s24, 0x400
	s_nop 0
	global_load_lds_dwordx4 v241, s[8:9]
	s_add_u32 m0, s25, 0x2000
	s_nop 0
	global_load_lds_dwordx4 v242, s[12:13]
	s_add_u32 m0, s25, 0x2400
	s_nop 0
	global_load_lds_dwordx4 v243, s[12:13]
	s_add_u32 m0, s25, 0x2800
	s_nop 0
	global_load_lds_dwordx4 v244, s[12:13]
	s_add_u32 m0, s25, 0x2c00
	s_nop 0
	global_load_lds_dwordx4 v245, s[12:13]
	s_add_u32 s8, s8, 64
	s_addc_u32 s9, s9, 0
	s_add_u32 s12, s12, 64
	s_addc_u32 s13, s13, 0
	v_mfma_f32_16x16x32_bf16 v[0:3], v[200:203], v[184:187], v[0:3]
	ds_read_b128 v[128:131], v246 offset:24576
	v_mfma_f32_16x16x32_bf16 v[4:7], v[204:207], v[184:187], v[4:7]
	ds_read_b128 v[148:151], v247 offset:24576
	v_mfma_f32_16x16x32_bf16 v[8:11], v[208:211], v[184:187], v[8:11]
	ds_read_b128 v[152:155], v247 offset:25600
	v_mfma_f32_16x16x32_bf16 v[12:15], v[212:215], v[184:187], v[12:15]
	ds_read_b128 v[132:135], v246 offset:25600
	v_mfma_f32_16x16x32_bf16 v[16:19], v[216:219], v[184:187], v[16:19]
	ds_read_b128 v[156:159], v247 offset:26624
	v_mfma_f32_16x16x32_bf16 v[20:23], v[220:223], v[184:187], v[20:23]
	ds_read_b128 v[160:163], v247 offset:27648
	v_mfma_f32_16x16x32_bf16 v[24:27], v[228:231], v[184:187], v[24:27]
	ds_read_b128 v[136:139], v246 offset:26624
	v_mfma_f32_16x16x32_bf16 v[28:31], v[232:235], v[184:187], v[28:31]
	ds_read_b128 v[168:171], v247 offset:28672
	v_mfma_f32_16x16x32_bf16 v[32:35], v[200:203], v[188:191], v[32:35]
	ds_read_b128 v[172:175], v247 offset:29696
	v_mfma_f32_16x16x32_bf16 v[36:39], v[204:207], v[188:191], v[36:39]
	ds_read_b128 v[140:143], v246 offset:27648
	v_mfma_f32_16x16x32_bf16 v[40:43], v[208:211], v[188:191], v[40:43]
	ds_read_b128 v[176:179], v247 offset:30720
	v_mfma_f32_16x16x32_bf16 v[44:47], v[212:215], v[188:191], v[44:47]
	ds_read_b128 v[180:183], v247 offset:31744
	v_mfma_f32_16x16x32_bf16 v[48:51], v[216:219], v[188:191], v[48:51]
	v_mfma_f32_16x16x32_bf16 v[52:55], v[220:223], v[188:191], v[52:55]
	v_mfma_f32_16x16x32_bf16 v[56:59], v[228:231], v[188:191], v[56:59]
	v_mfma_f32_16x16x32_bf16 v[60:63], v[232:235], v[188:191], v[60:63]
	v_mfma_f32_16x16x32_bf16 v[64:67], v[200:203], v[192:195], v[64:67]
	v_mfma_f32_16x16x32_bf16 v[68:71], v[204:207], v[192:195], v[68:71]
	v_mfma_f32_16x16x32_bf16 v[72:75], v[208:211], v[192:195], v[72:75]
	v_mfma_f32_16x16x32_bf16 v[76:79], v[212:215], v[192:195], v[76:79]
	v_mfma_f32_16x16x32_bf16 v[80:83], v[216:219], v[192:195], v[80:83]
	v_mfma_f32_16x16x32_bf16 v[84:87], v[220:223], v[192:195], v[84:87]
	v_mfma_f32_16x16x32_bf16 v[88:91], v[228:231], v[192:195], v[88:91]
	v_mfma_f32_16x16x32_bf16 v[92:95], v[232:235], v[192:195], v[92:95]
	v_mfma_f32_16x16x32_bf16 v[96:99], v[200:203], v[196:199], v[96:99]
	v_mfma_f32_16x16x32_bf16 v[100:103], v[204:207], v[196:199], v[100:103]
	v_mfma_f32_16x16x32_bf16 v[104:107], v[208:211], v[196:199], v[104:107]
	v_mfma_f32_16x16x32_bf16 v[108:111], v[212:215], v[196:199], v[108:111]
	v_mfma_f32_16x16x32_bf16 v[112:115], v[216:219], v[196:199], v[112:115]
	v_mfma_f32_16x16x32_bf16 v[116:119], v[220:223], v[196:199], v[116:119]
	v_mfma_f32_16x16x32_bf16 v[120:123], v[228:231], v[196:199], v[120:123]
	v_mfma_f32_16x16x32_bf16 v[124:127], v[232:235], v[196:199], v[124:127]
	s_waitcnt vmcnt(6) lgkmcnt(0)
	s_barrier
	s_add_u32 m0, s24, 0x6000
	s_nop 0
	global_load_lds_dwordx4 v240, s[8:9]
	s_add_u32 m0, s24, 0x6400
	s_nop 0
	global_load_lds_dwordx4 v241, s[8:9]
	s_add_u32 m0, s25, 0x8000
	s_nop 0
	global_load_lds_dwordx4 v242, s[12:13]
	s_add_u32 m0, s25, 0x8400
	s_nop 0
	global_load_lds_dwordx4 v243, s[12:13]
	s_add_u32 m0, s25, 0x8800
	s_nop 0
	global_load_lds_dwordx4 v244, s[12:13]
	s_add_u32 m0, s25, 0x8c00
	s_nop 0
	global_load_lds_dwordx4 v245, s[12:13]
	s_add_u32 s8, s8, 64
	s_addc_u32 s9, s9, 0
	s_add_u32 s12, s12, 64
	s_addc_u32 s13, s13, 0
	v_mfma_f32_16x16x32_bf16 v[0:3], v[148:151], v[128:131], v[0:3]
	ds_read_b128 v[184:187], v246 offset:49152
	v_mfma_f32_16x16x32_bf16 v[4:7], v[152:155], v[128:131], v[4:7]
	ds_read_b128 v[200:203], v247 offset:49152
	v_mfma_f32_16x16x32_bf16 v[8:11], v[156:159], v[128:131], v[8:11]
	ds_read_b128 v[204:207], v247 offset:50176
	v_mfma_f32_16x16x32_bf16 v[12:15], v[160:163], v[128:131], v[12:15]
	ds_read_b128 v[188:191], v246 offset:50176
	v_mfma_f32_16x16x32_bf16 v[16:19], v[168:171], v[128:131], v[16:19]
	ds_read_b128 v[208:211], v247 offset:51200
	v_mfma_f32_16x16x32_bf16 v[20:23], v[172:175], v[128:131], v[20:23]
	ds_read_b128 v[212:215], v247 offset:52224
	v_mfma_f32_16x16x32_bf16 v[24:27], v[176:179], v[128:131], v[24:27]
	ds_read_b128 v[192:195], v246 offset:51200
	v_mfma_f32_16x16x32_bf16 v[28:31], v[180:183], v[128:131], v[28:31]
	ds_read_b128 v[216:219], v247 offset:53248
	v_mfma_f32_16x16x32_bf16 v[32:35], v[148:151], v[132:135], v[32:35]
	ds_read_b128 v[220:223], v247 offset:54272
	v_mfma_f32_16x16x32_bf16 v[36:39], v[152:155], v[132:135], v[36:39]
	ds_read_b128 v[196:199], v246 offset:52224
	v_mfma_f32_16x16x32_bf16 v[40:43], v[156:159], v[132:135], v[40:43]
	ds_read_b128 v[228:231], v247 offset:55296
	v_mfma_f32_16x16x32_bf16 v[44:47], v[160:163], v[132:135], v[44:47]
	ds_read_b128 v[232:235], v247 offset:56320
	v_mfma_f32_16x16x32_bf16 v[48:51], v[168:171], v[132:135], v[48:51]
	v_mfma_f32_16x16x32_bf16 v[52:55], v[172:175], v[132:135], v[52:55]
	v_mfma_f32_16x16x32_bf16 v[56:59], v[176:179], v[132:135], v[56:59]
	v_mfma_f32_16x16x32_bf16 v[60:63], v[180:183], v[132:135], v[60:63]
	v_mfma_f32_16x16x32_bf16 v[64:67], v[148:151], v[136:139], v[64:67]
	v_mfma_f32_16x16x32_bf16 v[68:71], v[152:155], v[136:139], v[68:71]
	v_mfma_f32_16x16x32_bf16 v[72:75], v[156:159], v[136:139], v[72:75]
	v_mfma_f32_16x16x32_bf16 v[76:79], v[160:163], v[136:139], v[76:79]
	v_mfma_f32_16x16x32_bf16 v[80:83], v[168:171], v[136:139], v[80:83]
	v_mfma_f32_16x16x32_bf16 v[84:87], v[172:175], v[136:139], v[84:87]
	v_mfma_f32_16x16x32_bf16 v[88:91], v[176:179], v[136:139], v[88:91]
	v_mfma_f32_16x16x32_bf16 v[92:95], v[180:183], v[136:139], v[92:95]
	v_mfma_f32_16x16x32_bf16 v[96:99], v[148:151], v[140:143], v[96:99]
	v_mfma_f32_16x16x32_bf16 v[100:103], v[152:155], v[140:143], v[100:103]
	v_mfma_f32_16x16x32_bf16 v[104:107], v[156:159], v[140:143], v[104:107]
	v_mfma_f32_16x16x32_bf16 v[108:111], v[160:163], v[140:143], v[108:111]
	v_mfma_f32_16x16x32_bf16 v[112:115], v[168:171], v[140:143], v[112:115]
	v_mfma_f32_16x16x32_bf16 v[116:119], v[172:175], v[140:143], v[116:119]
	v_mfma_f32_16x16x32_bf16 v[120:123], v[176:179], v[140:143], v[120:123]
	v_mfma_f32_16x16x32_bf16 v[124:127], v[180:183], v[140:143], v[124:127]
	s_waitcnt vmcnt(6) lgkmcnt(0)
	s_barrier
; template <int NI> ...
;     ...
;   for (int kt = 0; kt < nk; kt += 2) {
;     G_LOAD(a0, b0, min((kt + 2) * 32, klast));
;     G_COMPUTE(0);
;     G_WRITE(a1, b1, 1);
;     __syncthreads();
;     G_LOAD(a1, b1, min((kt + 3) * 32, klast));
;     G_COMPUTE(1);
;     G_WRITE(a0, b0, 0);
;     __syncthreads();
;   }
	s_add_u32 m0, s24, 0xc000
	s_nop 0
	global_load_lds_dwordx4 v240, s[8:9]
	s_add_u32 m0, s24, 0xc400
	s_nop 0
	global_load_lds_dwordx4 v241, s[8:9]
	s_add_u32 m0, s25, 0xe000
	s_nop 0
	global_load_lds_dwordx4 v242, s[12:13]
	s_add_u32 m0, s25, 0xe400
	s_nop 0
	global_load_lds_dwordx4 v243, s[12:13]
	s_add_u32 m0, s25, 0xe800
	s_nop 0
	global_load_lds_dwordx4 v244, s[12:13]
	s_add_u32 m0, s25, 0xec00
	s_nop 0
	global_load_lds_dwordx4 v245, s[12:13]
	s_add_u32 s8, s8, 64
	s_addc_u32 s9, s9, 0
	s_add_u32 s12, s12, 64
	s_addc_u32 s13, s13, 0
	v_mfma_f32_16x16x32_bf16 v[0:3], v[200:203], v[184:187], v[0:3]
	ds_read_b128 v[128:131], v246 offset:0
	v_mfma_f32_16x16x32_bf16 v[4:7], v[204:207], v[184:187], v[4:7]
	ds_read_b128 v[148:151], v247 offset:0
	v_mfma_f32_16x16x32_bf16 v[8:11], v[208:211], v[184:187], v[8:11]
	ds_read_b128 v[152:155], v247 offset:1024
	v_mfma_f32_16x16x32_bf16 v[12:15], v[212:215], v[184:187], v[12:15]
	ds_read_b128 v[132:135], v246 offset:1024
	v_mfma_f32_16x16x32_bf16 v[16:19], v[216:219], v[184:187], v[16:19]
	ds_read_b128 v[156:159], v247 offset:2048
	v_mfma_f32_16x16x32_bf16 v[20:23], v[220:223], v[184:187], v[20:23]
	ds_read_b128 v[160:163], v247 offset:3072
	v_mfma_f32_16x16x32_bf16 v[24:27], v[228:231], v[184:187], v[24:27]
	ds_read_b128 v[136:139], v246 offset:2048
	v_mfma_f32_16x16x32_bf16 v[28:31], v[232:235], v[184:187], v[28:31]
	ds_read_b128 v[168:171], v247 offset:4096
	v_mfma_f32_16x16x32_bf16 v[32:35], v[200:203], v[188:191], v[32:35]
	ds_read_b128 v[172:175], v247 offset:5120
	v_mfma_f32_16x16x32_bf16 v[36:39], v[204:207], v[188:191], v[36:39]
	ds_read_b128 v[140:143], v246 offset:3072
	v_mfma_f32_16x16x32_bf16 v[40:43], v[208:211], v[188:191], v[40:43]
	ds_read_b128 v[176:179], v247 offset:6144
	v_mfma_f32_16x16x32_bf16 v[44:47], v[212:215], v[188:191], v[44:47]
	ds_read_b128 v[180:183], v247 offset:7168
	v_mfma_f32_16x16x32_bf16 v[48:51], v[216:219], v[188:191], v[48:51]
	v_mfma_f32_16x16x32_bf16 v[52:55], v[220:223], v[188:191], v[52:55]
	v_mfma_f32_16x16x32_bf16 v[56:59], v[228:231], v[188:191], v[56:59]
	v_mfma_f32_16x16x32_bf16 v[60:63], v[232:235], v[188:191], v[60:63]
	v_mfma_f32_16x16x32_bf16 v[64:67], v[200:203], v[192:195], v[64:67]
	v_mfma_f32_16x16x32_bf16 v[68:71], v[204:207], v[192:195], v[68:71]
	v_mfma_f32_16x16x32_bf16 v[72:75], v[208:211], v[192:195], v[72:75]
	v_mfma_f32_16x16x32_bf16 v[76:79], v[212:215], v[192:195], v[76:79]
	v_mfma_f32_16x16x32_bf16 v[80:83], v[216:219], v[192:195], v[80:83]
	v_mfma_f32_16x16x32_bf16 v[84:87], v[220:223], v[192:195], v[84:87]
	v_mfma_f32_16x16x32_bf16 v[88:91], v[228:231], v[192:195], v[88:91]
	v_mfma_f32_16x16x32_bf16 v[92:95], v[232:235], v[192:195], v[92:95]
	v_mfma_f32_16x16x32_bf16 v[96:99], v[200:203], v[196:199], v[96:99]
	v_mfma_f32_16x16x32_bf16 v[100:103], v[204:207], v[196:199], v[100:103]
	v_mfma_f32_16x16x32_bf16 v[104:107], v[208:211], v[196:199], v[104:107]
	v_mfma_f32_16x16x32_bf16 v[108:111], v[212:215], v[196:199], v[108:111]
	v_mfma_f32_16x16x32_bf16 v[112:115], v[216:219], v[196:199], v[112:115]
	v_mfma_f32_16x16x32_bf16 v[116:119], v[220:223], v[196:199], v[116:119]
	v_mfma_f32_16x16x32_bf16 v[120:123], v[228:231], v[196:199], v[120:123]
	v_mfma_f32_16x16x32_bf16 v[124:127], v[232:235], v[196:199], v[124:127]
	s_add_u32 s28, s28, 1
	s_cmp_lt_u32 s28, 5
	s_cbranch_scc1 .Loutp_kloop
	s_waitcnt vmcnt(6) lgkmcnt(0)
	s_barrier
	s_add_u32 m0, s24, 0x0
	s_nop 0
	global_load_lds_dwordx4 v240, s[8:9]
	s_add_u32 m0, s24, 0x400
	s_nop 0
	global_load_lds_dwordx4 v241, s[8:9]
	s_add_u32 m0, s25, 0x2000
	s_nop 0
	global_load_lds_dwordx4 v242, s[12:13]
	s_add_u32 m0, s25, 0x2400
	s_nop 0
	global_load_lds_dwordx4 v243, s[12:13]
	s_add_u32 m0, s25, 0x2800
	s_nop 0
	global_load_lds_dwordx4 v244, s[12:13]
	s_add_u32 m0, s25, 0x2c00
	s_nop 0
	global_load_lds_dwordx4 v245, s[12:13]
	s_add_u32 s8, s8, 64
	s_addc_u32 s9, s9, 0
	s_add_u32 s12, s12, 64
	s_addc_u32 s13, s13, 0
	v_mfma_f32_16x16x32_bf16 v[0:3], v[148:151], v[128:131], v[0:3]
	ds_read_b128 v[184:187], v246 offset:24576
	v_mfma_f32_16x16x32_bf16 v[4:7], v[152:155], v[128:131], v[4:7]
	ds_read_b128 v[200:203], v247 offset:24576
	v_mfma_f32_16x16x32_bf16 v[8:11], v[156:159], v[128:131], v[8:11]
	ds_read_b128 v[204:207], v247 offset:25600
	v_mfma_f32_16x16x32_bf16 v[12:15], v[160:163], v[128:131], v[12:15]
	ds_read_b128 v[188:191], v246 offset:25600
	v_mfma_f32_16x16x32_bf16 v[16:19], v[168:171], v[128:131], v[16:19]
	ds_read_b128 v[208:211], v247 offset:26624
	v_mfma_f32_16x16x32_bf16 v[20:23], v[172:175], v[128:131], v[20:23]
	ds_read_b128 v[212:215], v247 offset:27648
	v_mfma_f32_16x16x32_bf16 v[24:27], v[176:179], v[128:131], v[24:27]
	ds_read_b128 v[192:195], v246 offset:26624
	v_mfma_f32_16x16x32_bf16 v[28:31], v[180:183], v[128:131], v[28:31]
	ds_read_b128 v[216:219], v247 offset:28672
	v_mfma_f32_16x16x32_bf16 v[32:35], v[148:151], v[132:135], v[32:35]
	ds_read_b128 v[220:223], v247 offset:29696
	v_mfma_f32_16x16x32_bf16 v[36:39], v[152:155], v[132:135], v[36:39]
	ds_read_b128 v[196:199], v246 offset:27648
	v_mfma_f32_16x16x32_bf16 v[40:43], v[156:159], v[132:135], v[40:43]
	ds_read_b128 v[228:231], v247 offset:30720
	v_mfma_f32_16x16x32_bf16 v[44:47], v[160:163], v[132:135], v[44:47]
	ds_read_b128 v[232:235], v247 offset:31744
	v_mfma_f32_16x16x32_bf16 v[48:51], v[168:171], v[132:135], v[48:51]
	v_mfma_f32_16x16x32_bf16 v[52:55], v[172:175], v[132:135], v[52:55]
	v_mfma_f32_16x16x32_bf16 v[56:59], v[176:179], v[132:135], v[56:59]
	v_mfma_f32_16x16x32_bf16 v[60:63], v[180:183], v[132:135], v[60:63]
	v_mfma_f32_16x16x32_bf16 v[64:67], v[148:151], v[136:139], v[64:67]
	v_mfma_f32_16x16x32_bf16 v[68:71], v[152:155], v[136:139], v[68:71]
	v_mfma_f32_16x16x32_bf16 v[72:75], v[156:159], v[136:139], v[72:75]
	v_mfma_f32_16x16x32_bf16 v[76:79], v[160:163], v[136:139], v[76:79]
	v_mfma_f32_16x16x32_bf16 v[80:83], v[168:171], v[136:139], v[80:83]
	v_mfma_f32_16x16x32_bf16 v[84:87], v[172:175], v[136:139], v[84:87]
	v_mfma_f32_16x16x32_bf16 v[88:91], v[176:179], v[136:139], v[88:91]
	v_mfma_f32_16x16x32_bf16 v[92:95], v[180:183], v[136:139], v[92:95]
	v_mfma_f32_16x16x32_bf16 v[96:99], v[148:151], v[140:143], v[96:99]
	v_mfma_f32_16x16x32_bf16 v[100:103], v[152:155], v[140:143], v[100:103]
	v_mfma_f32_16x16x32_bf16 v[104:107], v[156:159], v[140:143], v[104:107]
	v_mfma_f32_16x16x32_bf16 v[108:111], v[160:163], v[140:143], v[108:111]
	v_mfma_f32_16x16x32_bf16 v[112:115], v[168:171], v[140:143], v[112:115]
	v_mfma_f32_16x16x32_bf16 v[116:119], v[172:175], v[140:143], v[116:119]
	v_mfma_f32_16x16x32_bf16 v[120:123], v[176:179], v[140:143], v[120:123]
	v_mfma_f32_16x16x32_bf16 v[124:127], v[180:183], v[140:143], v[124:127]
	s_waitcnt vmcnt(6) lgkmcnt(0)
	s_barrier
; template <int NI> ...
;     ...
;   for (int kt = 0; kt < nk; kt += 2) {
;     G_LOAD(a0, b0, min((kt + 2) * 32, klast));
;     G_COMPUTE(0);
;     G_WRITE(a1, b1, 1);
;     __syncthreads();
;     G_LOAD(a1, b1, min((kt + 3) * 32, klast));
;     G_COMPUTE(1);
;     G_WRITE(a0, b0, 0);
;     __syncthreads();
;   }
;   asm volatile("s_nop 15\n\ts_nop 15" ::: "memory");
; __device__ void phase_proj_res(CParams& p, int l, int tm, int tn, char* smem, const bf16_t* A, int K,
;                                const bf16_t* Bt, int gate_off, float gscale) {
;     ...
;   const float* md = p.mod + ((size_t)l * 3 + modvec_of_tok(row0)) * 6144 + gate_off;
;   EPI_LOOP({
;     float* xp = xrow(p, row0 + rl) + col0 + cl;
;     *xp = *xp + gscale * md[col0 + cl] * acc[mi][ni][j];
	s_add_u32 m0, s24, 0x6000
	s_nop 0
	global_load_lds_dwordx4 v240, s[8:9]
	s_add_u32 m0, s24, 0x6400
	s_nop 0
	global_load_lds_dwordx4 v241, s[8:9]
	s_add_u32 m0, s25, 0x8000
	s_nop 0
	global_load_lds_dwordx4 v242, s[12:13]
	s_add_u32 m0, s25, 0x8400
	s_nop 0
	global_load_lds_dwordx4 v243, s[12:13]
	s_add_u32 m0, s25, 0x8800
	s_nop 0
	global_load_lds_dwordx4 v244, s[12:13]
	s_add_u32 m0, s25, 0x8c00
	s_nop 0
	global_load_lds_dwordx4 v245, s[12:13]
	s_add_u32 s8, s8, 64
	s_addc_u32 s9, s9, 0
	s_add_u32 s12, s12, 64
	s_addc_u32 s13, s13, 0
	v_mfma_f32_16x16x32_bf16 v[0:3], v[200:203], v[184:187], v[0:3]
	ds_read_b128 v[128:131], v246 offset:49152
	v_mfma_f32_16x16x32_bf16 v[4:7], v[204:207], v[184:187], v[4:7]
	ds_read_b128 v[148:151], v247 offset:49152
	v_mfma_f32_16x16x32_bf16 v[8:11], v[208:211], v[184:187], v[8:11]
	ds_read_b128 v[152:155], v247 offset:50176
	v_mfma_f32_16x16x32_bf16 v[12:15], v[212:215], v[184:187], v[12:15]
	ds_read_b128 v[132:135], v246 offset:50176
	v_mfma_f32_16x16x32_bf16 v[16:19], v[216:219], v[184:187], v[16:19]
	ds_read_b128 v[156:159], v247 offset:51200
	v_mfma_f32_16x16x32_bf16 v[20:23], v[220:223], v[184:187], v[20:23]
	ds_read_b128 v[160:163], v247 offset:52224
	v_mfma_f32_16x16x32_bf16 v[24:27], v[228:231], v[184:187], v[24:27]
	ds_read_b128 v[136:139], v246 offset:51200
	v_mfma_f32_16x16x32_bf16 v[28:31], v[232:235], v[184:187], v[28:31]
	ds_read_b128 v[168:171], v247 offset:53248
	v_mfma_f32_16x16x32_bf16 v[32:35], v[200:203], v[188:191], v[32:35]
	ds_read_b128 v[172:175], v247 offset:54272
	v_mfma_f32_16x16x32_bf16 v[36:39], v[204:207], v[188:191], v[36:39]
	ds_read_b128 v[140:143], v246 offset:52224
	v_mfma_f32_16x16x32_bf16 v[40:43], v[208:211], v[188:191], v[40:43]
	ds_read_b128 v[176:179], v247 offset:55296
	v_mfma_f32_16x16x32_bf16 v[44:47], v[212:215], v[188:191], v[44:47]
	ds_read_b128 v[180:183], v247 offset:56320
	v_mfma_f32_16x16x32_bf16 v[48:51], v[216:219], v[188:191], v[48:51]
	v_mfma_f32_16x16x32_bf16 v[52:55], v[220:223], v[188:191], v[52:55]
	v_mfma_f32_16x16x32_bf16 v[56:59], v[228:231], v[188:191], v[56:59]
	v_mfma_f32_16x16x32_bf16 v[60:63], v[232:235], v[188:191], v[60:63]
	v_mfma_f32_16x16x32_bf16 v[64:67], v[200:203], v[192:195], v[64:67]
	v_mfma_f32_16x16x32_bf16 v[68:71], v[204:207], v[192:195], v[68:71]
	v_mfma_f32_16x16x32_bf16 v[72:75], v[208:211], v[192:195], v[72:75]
	v_mfma_f32_16x16x32_bf16 v[76:79], v[212:215], v[192:195], v[76:79]
	v_mfma_f32_16x16x32_bf16 v[80:83], v[216:219], v[192:195], v[80:83]
	v_mfma_f32_16x16x32_bf16 v[84:87], v[220:223], v[192:195], v[84:87]
	v_mfma_f32_16x16x32_bf16 v[88:91], v[228:231], v[192:195], v[88:91]
	v_mfma_f32_16x16x32_bf16 v[92:95], v[232:235], v[192:195], v[92:95]
	v_mfma_f32_16x16x32_bf16 v[96:99], v[200:203], v[196:199], v[96:99]
	v_mfma_f32_16x16x32_bf16 v[100:103], v[204:207], v[196:199], v[100:103]
	v_mfma_f32_16x16x32_bf16 v[104:107], v[208:211], v[196:199], v[104:107]
	v_mfma_f32_16x16x32_bf16 v[108:111], v[212:215], v[196:199], v[108:111]
	v_mfma_f32_16x16x32_bf16 v[112:115], v[216:219], v[196:199], v[112:115]
	v_mfma_f32_16x16x32_bf16 v[116:119], v[220:223], v[196:199], v[116:119]
	v_mfma_f32_16x16x32_bf16 v[120:123], v[228:231], v[196:199], v[120:123]
	v_mfma_f32_16x16x32_bf16 v[124:127], v[232:235], v[196:199], v[124:127]
	s_waitcnt vmcnt(0) lgkmcnt(0)
	s_barrier
	s_nop 15
	s_nop 15
	s_mul_i32 s29, s2, 3
	s_lshr_b32 s44, s26, 13
	s_add_u32 s29, s29, s44
	s_mul_i32 s29, s29, 6144
	s_add_u32 s29, s29, s27
	s_add_u32 s29, s29, 2048
	s_lshl_b32 s29, s29, 2
	s_add_u32 s56, s22, s29
	s_addc_u32 s57, s23, 0
	s_lshl_b32 s29, s26, 12
	s_lshl_b32 s44, s27, 2
	s_add_u32 s29, s29, s44
	s_add_u32 s54, s18, s29
	s_addc_u32 s55, s19, 0
	global_load_dwordx4 v[148:151], v249, s[56:57] offset:0
	global_load_dwordx4 v[152:155], v249, s[56:57] offset:64
	global_load_dwordx4 v[156:159], v249, s[56:57] offset:128
	global_load_dwordx4 v[160:163], v249, s[56:57] offset:192
	global_load_dwordx4 v[168:171], v249, s[56:57] offset:256
	global_load_dwordx4 v[172:175], v249, s[56:57] offset:320
	global_load_dwordx4 v[176:179], v249, s[56:57] offset:384
	global_load_dwordx4 v[180:183], v249, s[56:57] offset:448
	global_load_dwordx4 v[200:203], v248, s[54:55] offset:0
	global_load_dwordx4 v[204:207], v248, s[54:55] offset:64
	global_load_dwordx4 v[208:211], v248, s[54:55] offset:128
	global_load_dwordx4 v[212:215], v248, s[54:55] offset:192
	global_load_dwordx4 v[216:219], v248, s[54:55] offset:256
	global_load_dwordx4 v[220:223], v248, s[54:55] offset:320
	global_load_dwordx4 v[228:231], v248, s[54:55] offset:384
	global_load_dwordx4 v[232:235], v248, s[54:55] offset:448
	s_add_u32 s54, s54, 0x10000
	s_addc_u32 s55, s55, 0
	global_load_dwordx4 v[128:131], v248, s[54:55] offset:0
	global_load_dwordx4 v[132:135], v248, s[54:55] offset:64
	global_load_dwordx4 v[136:139], v248, s[54:55] offset:128
	global_load_dwordx4 v[140:143], v248, s[54:55] offset:192
	global_load_dwordx4 v[184:187], v248, s[54:55] offset:256
	global_load_dwordx4 v[188:191], v248, s[54:55] offset:320
	global_load_dwordx4 v[192:195], v248, s[54:55] offset:384
	global_load_dwordx4 v[196:199], v248, s[54:55] offset:448
	s_sub_u32 s54, s54, 0x10000
	s_subb_u32 s55, s55, 0
	s_waitcnt vmcnt(8)
; __device__ void phase_proj_res(CParams& p, int l, int tm, int tn, char* smem, const bf16_t* A, int K,
;                                const bf16_t* Bt, int gate_off, float gscale) {
;     ...
;   EPI_LOOP({
;     float* xp = xrow(p, row0 + rl) + col0 + cl;
;     *xp = *xp + gscale * md[col0 + cl] * acc[mi][ni][j];
;   })
	v_fmac_f32_e32 v200, v148, v0
	v_fmac_f32_e32 v201, v149, v1
	v_fmac_f32_e32 v202, v150, v2
	v_fmac_f32_e32 v203, v151, v3
	v_fmac_f32_e32 v204, v152, v4
	v_fmac_f32_e32 v205, v153, v5
	v_fmac_f32_e32 v206, v154, v6
	v_fmac_f32_e32 v207, v155, v7
	v_fmac_f32_e32 v208, v156, v8
	v_fmac_f32_e32 v209, v157, v9
	v_fmac_f32_e32 v210, v158, v10
	v_fmac_f32_e32 v211, v159, v11
	v_fmac_f32_e32 v212, v160, v12
	v_fmac_f32_e32 v213, v161, v13
	v_fmac_f32_e32 v214, v162, v14
	v_fmac_f32_e32 v215, v163, v15
	v_fmac_f32_e32 v216, v168, v16
	v_fmac_f32_e32 v217, v169, v17
	v_fmac_f32_e32 v218, v170, v18
	v_fmac_f32_e32 v219, v171, v19
	v_fmac_f32_e32 v220, v172, v20
	v_fmac_f32_e32 v221, v173, v21
	v_fmac_f32_e32 v222, v174, v22
	v_fmac_f32_e32 v223, v175, v23
	v_fmac_f32_e32 v228, v176, v24
	v_fmac_f32_e32 v229, v177, v25
	v_fmac_f32_e32 v230, v178, v26
	v_fmac_f32_e32 v231, v179, v27
	v_fmac_f32_e32 v232, v180, v28
	v_fmac_f32_e32 v233, v181, v29
	v_fmac_f32_e32 v234, v182, v30
	v_fmac_f32_e32 v235, v183, v31
	global_store_dwordx4 v248, v[200:203], s[54:55] offset:0
	global_store_dwordx4 v248, v[204:207], s[54:55] offset:64
	global_store_dwordx4 v248, v[208:211], s[54:55] offset:128
	global_store_dwordx4 v248, v[212:215], s[54:55] offset:192
	global_store_dwordx4 v248, v[216:219], s[54:55] offset:256
	global_store_dwordx4 v248, v[220:223], s[54:55] offset:320
	global_store_dwordx4 v248, v[228:231], s[54:55] offset:384
	global_store_dwordx4 v248, v[232:235], s[54:55] offset:448
	s_add_u32 s54, s54, 0x10000
	s_addc_u32 s55, s55, 0
	s_add_u32 s54, s54, 0x10000
	s_addc_u32 s55, s55, 0
	global_load_dwordx4 v[200:203], v248, s[54:55] offset:0
	global_load_dwordx4 v[204:207], v248, s[54:55] offset:64
	global_load_dwordx4 v[208:211], v248, s[54:55] offset:128
	global_load_dwordx4 v[212:215], v248, s[54:55] offset:192
	global_load_dwordx4 v[216:219], v248, s[54:55] offset:256
	global_load_dwordx4 v[220:223], v248, s[54:55] offset:320
	global_load_dwordx4 v[228:231], v248, s[54:55] offset:384
	global_load_dwordx4 v[232:235], v248, s[54:55] offset:448
	s_sub_u32 s54, s54, 0x10000
	s_subb_u32 s55, s55, 0
	s_waitcnt vmcnt(8)
	v_fmac_f32_e32 v128, v148, v32
	v_fmac_f32_e32 v129, v149, v33
	v_fmac_f32_e32 v130, v150, v34
	v_fmac_f32_e32 v131, v151, v35
	v_fmac_f32_e32 v132, v152, v36
	v_fmac_f32_e32 v133, v153, v37
	v_fmac_f32_e32 v134, v154, v38
	v_fmac_f32_e32 v135, v155, v39
	v_fmac_f32_e32 v136, v156, v40
	v_fmac_f32_e32 v137, v157, v41
	v_fmac_f32_e32 v138, v158, v42
	v_fmac_f32_e32 v139, v159, v43
	v_fmac_f32_e32 v140, v160, v44
	v_fmac_f32_e32 v141, v161, v45
	v_fmac_f32_e32 v142, v162, v46
	v_fmac_f32_e32 v143, v163, v47
	v_fmac_f32_e32 v184, v168, v48
	v_fmac_f32_e32 v185, v169, v49
	v_fmac_f32_e32 v186, v170, v50
	v_fmac_f32_e32 v187, v171, v51
	v_fmac_f32_e32 v188, v172, v52
	v_fmac_f32_e32 v189, v173, v53
	v_fmac_f32_e32 v190, v174, v54
	v_fmac_f32_e32 v191, v175, v55
	v_fmac_f32_e32 v192, v176, v56
	v_fmac_f32_e32 v193, v177, v57
	v_fmac_f32_e32 v194, v178, v58
	v_fmac_f32_e32 v195, v179, v59
	v_fmac_f32_e32 v196, v180, v60
	v_fmac_f32_e32 v197, v181, v61
	v_fmac_f32_e32 v198, v182, v62
	v_fmac_f32_e32 v199, v183, v63
	global_store_dwordx4 v248, v[128:131], s[54:55] offset:0
	global_store_dwordx4 v248, v[132:135], s[54:55] offset:64
	global_store_dwordx4 v248, v[136:139], s[54:55] offset:128
	global_store_dwordx4 v248, v[140:143], s[54:55] offset:192
	global_store_dwordx4 v248, v[184:187], s[54:55] offset:256
	global_store_dwordx4 v248, v[188:191], s[54:55] offset:320
	global_store_dwordx4 v248, v[192:195], s[54:55] offset:384
	global_store_dwordx4 v248, v[196:199], s[54:55] offset:448
	s_add_u32 s54, s54, 0x10000
	s_addc_u32 s55, s55, 0
	s_add_u32 s54, s54, 0x10000
	s_addc_u32 s55, s55, 0
	global_load_dwordx4 v[128:131], v248, s[54:55] offset:0
	global_load_dwordx4 v[132:135], v248, s[54:55] offset:64
	global_load_dwordx4 v[136:139], v248, s[54:55] offset:128
	global_load_dwordx4 v[140:143], v248, s[54:55] offset:192
	global_load_dwordx4 v[184:187], v248, s[54:55] offset:256
	global_load_dwordx4 v[188:191], v248, s[54:55] offset:320
	global_load_dwordx4 v[192:195], v248, s[54:55] offset:384
	global_load_dwordx4 v[196:199], v248, s[54:55] offset:448
	s_sub_u32 s54, s54, 0x10000
	s_subb_u32 s55, s55, 0
	s_waitcnt vmcnt(8)
; __device__ void phase_proj_res(CParams& p, int l, int tm, int tn, char* smem, const bf16_t* A, int K,
;                                const bf16_t* Bt, int gate_off, float gscale) {
;     ...
;   EPI_LOOP({
;     float* xp = xrow(p, row0 + rl) + col0 + cl;
;     *xp = *xp + gscale * md[col0 + cl] * acc[mi][ni][j];
;   })
	v_fmac_f32_e32 v200, v148, v64
	v_fmac_f32_e32 v201, v149, v65
	v_fmac_f32_e32 v202, v150, v66
	v_fmac_f32_e32 v203, v151, v67
	v_fmac_f32_e32 v204, v152, v68
	v_fmac_f32_e32 v205, v153, v69
	v_fmac_f32_e32 v206, v154, v70
	v_fmac_f32_e32 v207, v155, v71
	v_fmac_f32_e32 v208, v156, v72
	v_fmac_f32_e32 v209, v157, v73
	v_fmac_f32_e32 v210, v158, v74
	v_fmac_f32_e32 v211, v159, v75
	v_fmac_f32_e32 v212, v160, v76
	v_fmac_f32_e32 v213, v161, v77
	v_fmac_f32_e32 v214, v162, v78
	v_fmac_f32_e32 v215, v163, v79
	v_fmac_f32_e32 v216, v168, v80
	v_fmac_f32_e32 v217, v169, v81
	v_fmac_f32_e32 v218, v170, v82
	v_fmac_f32_e32 v219, v171, v83
	v_fmac_f32_e32 v220, v172, v84
	v_fmac_f32_e32 v221, v173, v85
	v_fmac_f32_e32 v222, v174, v86
	v_fmac_f32_e32 v223, v175, v87
	v_fmac_f32_e32 v228, v176, v88
	v_fmac_f32_e32 v229, v177, v89
	v_fmac_f32_e32 v230, v178, v90
	v_fmac_f32_e32 v231, v179, v91
	v_fmac_f32_e32 v232, v180, v92
	v_fmac_f32_e32 v233, v181, v93
	v_fmac_f32_e32 v234, v182, v94
	v_fmac_f32_e32 v235, v183, v95
	global_store_dwordx4 v248, v[200:203], s[54:55] offset:0
	global_store_dwordx4 v248, v[204:207], s[54:55] offset:64
	global_store_dwordx4 v248, v[208:211], s[54:55] offset:128
	global_store_dwordx4 v248, v[212:215], s[54:55] offset:192
	global_store_dwordx4 v248, v[216:219], s[54:55] offset:256
	global_store_dwordx4 v248, v[220:223], s[54:55] offset:320
	global_store_dwordx4 v248, v[228:231], s[54:55] offset:384
	global_store_dwordx4 v248, v[232:235], s[54:55] offset:448
	s_add_u32 s54, s54, 0x10000
	s_addc_u32 s55, s55, 0
	s_waitcnt vmcnt(0)
	v_fmac_f32_e32 v128, v148, v96
	v_fmac_f32_e32 v129, v149, v97
	v_fmac_f32_e32 v130, v150, v98
	v_fmac_f32_e32 v131, v151, v99
	v_fmac_f32_e32 v132, v152, v100
	v_fmac_f32_e32 v133, v153, v101
	v_fmac_f32_e32 v134, v154, v102
	v_fmac_f32_e32 v135, v155, v103
	v_fmac_f32_e32 v136, v156, v104
	v_fmac_f32_e32 v137, v157, v105
	v_fmac_f32_e32 v138, v158, v106
	v_fmac_f32_e32 v139, v159, v107
	v_fmac_f32_e32 v140, v160, v108
	v_fmac_f32_e32 v141, v161, v109
	v_fmac_f32_e32 v142, v162, v110
	v_fmac_f32_e32 v143, v163, v111
	v_fmac_f32_e32 v184, v168, v112
	v_fmac_f32_e32 v185, v169, v113
	v_fmac_f32_e32 v186, v170, v114
	v_fmac_f32_e32 v187, v171, v115
	v_fmac_f32_e32 v188, v172, v116
	v_fmac_f32_e32 v189, v173, v117
	v_fmac_f32_e32 v190, v174, v118
	v_fmac_f32_e32 v191, v175, v119
	v_fmac_f32_e32 v192, v176, v120
	v_fmac_f32_e32 v193, v177, v121
	v_fmac_f32_e32 v194, v178, v122
	v_fmac_f32_e32 v195, v179, v123
	v_fmac_f32_e32 v196, v180, v124
	v_fmac_f32_e32 v197, v181, v125
	v_fmac_f32_e32 v198, v182, v126
	v_fmac_f32_e32 v199, v183, v127
	global_store_dwordx4 v248, v[128:131], s[54:55] offset:0
	global_store_dwordx4 v248, v[132:135], s[54:55] offset:64
	global_store_dwordx4 v248, v[136:139], s[54:55] offset:128
	global_store_dwordx4 v248, v[140:143], s[54:55] offset:192
	global_store_dwordx4 v248, v[184:187], s[54:55] offset:256
	global_store_dwordx4 v248, v[188:191], s[54:55] offset:320
	global_store_dwordx4 v248, v[192:195], s[54:55] offset:384
	global_store_dwordx4 v248, v[196:199], s[54:55] offset:448
	s_waitcnt vmcnt(0) lgkmcnt(0)
	s_barrier
	ds_write_b128 v145, v[236:239] offset:40960
	s_waitcnt lgkmcnt(0)
	s_barrier
	s_mov_b64 s[52:53], 0

; __device__ __forceinline__ int otid() { int t = threadIdx.x; asm volatile("" : "+v"(t)); return t; }
; __device__ __forceinline__ void gemm_mainloop8(const bf16_t* __restrict__ A, int lda,
;                                                const bf16_t* __restrict__ B, int ldb, int K,
;                                                bf16_t* sbase, f32x4 (&acc)[4][8], const int tid) {
;   const int lane = tid & 63, wid = tid >> 6, wr = wid >> 1, wc = wid & 1;
;   const int lrow = tid >> 2, lch = (tid & 3) * 8;
;   const int l15 = lane & 15, lq = lane >> 4;
;   const bf16_t* pa = A + (size_t)lrow * lda + lch;
;   const bf16_t* pb = B + (size_t)lrow * ldb + lch;
;   const size_t a64 = (size_t)64 * lda, b64 = (size_t)64 * ldb;
;   u32x4 ra[2], rb[4];
;   const int nk = K >> 5;
;   const int wofs = lrow * GROW + lch;
;   const int raofs = (wr * 64 + l15) * GROW + lq * 8;
;   const int rbofs = 128 * GROW + (wc * 128 + l15) * GROW + lq * 8;
;   ra[0] = *(const u32x4*)(pa); ra[1] = *(const u32x4*)(pa + a64);
; #pragma unroll
;   for (int i = 0; i < 4; i++) rb[i] = *(const u32x4*)(pb + (size_t)i * b64);
; __device__ void phase_mlp1_big(CParams& p, int l, int tm, int tn, char* smem) {
;   const int tid = otid();
;   int row0 = tm * 128, col0 = tn * 256;
;   f32x4 acc[4][8];
;   zero_acc<8>(acc);
;   gemm_mainloop8(p.hbuf + (size_t)row0 * DM, DM, p.W1T + ((size_t)l * DFF + col0) * DM, DM, DM, (bf16_t*)smem, acc, tid);
.LBB0_1064:
	s_or_b64 exec, exec, s[22:23]
	s_mov_b64 s[22:23], s[34:35]
	s_waitcnt lgkmcnt(0)
	s_barrier
	s_load_dwordx2 s[6:7], s[22:23], 0x120
	s_lshl_b64 s[18:19], s[0:1], 23
	s_load_dwordx2 s[24:25], s[22:23], 0x150
	s_load_dwordx2 s[8:9], s[22:23], 0x1e0
	v_readlane_b32 s16, v224, 4
	v_readlane_b32 s17, v224, 5
	s_waitcnt lgkmcnt(0)
	s_add_u32 s2, s6, s18
	s_addc_u32 s4, s7, s19
	s_add_u32 s42, s2, s16
	s_addc_u32 s43, s4, s17
	v_readlane_b32 s0, v224, 13
	v_readlane_b32 s1, v224, 14
	s_add_u32 s44, s8, s0
	s_addc_u32 s45, s9, s1
	s_add_u32 s2, s6, s16
	s_addc_u32 s4, s7, s17
	s_add_u32 s48, s2, s18
	s_addc_u32 s49, s4, s19
	s_mov_b64 exec, -1
	ds_read_b128 v[236:239], v145 offset:40960
	s_load_dwordx2 s[0:1], s[34:35], 0x150
	s_load_dwordx2 s[6:7], s[34:35], 0x120
	s_load_dwordx2 s[24:25], s[34:35], 0x1e0
	s_load_dwordx2 s[26:27], s[34:35], 0x160
	v_readlane_b32 s2, v224, 26
	v_readlane_b32 s4, v225, 4
	v_readfirstlane_b32 s8, v147
	v_and_b32_e32 v250, 63, v147
	s_nop 3
	s_lshr_b32 s8, s8, 6
	s_lshl_b32 s10, s8, 11
	s_lshl_b32 s32, s8, 12
	v_lshrrev_b32_e32 v251, 2, v250
	v_and_b32_e32 v252, 3, v250
	v_lshrrev_b32_e32 v253, 4, v250
	v_sub_u32_e32 v253, 0, v253
	v_and_b32_e32 v253, 3, v253
	v_xor_b32_e32 v253, v252, v253
	v_lshlrev_b32_e32 v253, 4, v253
	s_lshl_b32 s43, s8, 5
	v_add_u32_e32 v252, s43, v251
	s_mov_b32 s44, 0x800
	v_mul_lo_u32 v240, v252, s44
	v_add_u32_e32 v240, v240, v253
	v_add_u32_e32 v241, 0x8000, v240
	s_lshl_b32 s43, s8, 6
	v_add_u32_e32 v252, s43, v251
	s_mov_b32 s44, 0x800
	v_mul_lo_u32 v242, v252, s44
	v_and_b32_e32 v253, 3, v250
	v_xor_b32_e32 v252, 1, v253
	v_lshlrev_b32_e32 v252, 4, v252
	v_add_u32_e32 v252, 0x18000, v252
	v_add_u32_e32 v245, v242, v252
	v_xor_b32_e32 v252, 2, v253
	v_lshlrev_b32_e32 v252, 4, v252
	v_add_u32_e32 v252, 0x10000, v252
	v_add_u32_e32 v244, v242, v252
	v_xor_b32_e32 v252, 3, v253
	v_lshlrev_b32_e32 v252, 4, v252
	v_add_u32_e32 v252, 0x8000, v252
	v_add_u32_e32 v243, v242, v252
	v_xor_b32_e32 v252, 0, v253
	v_lshlrev_b32_e32 v252, 4, v252
	v_add_u32_e32 v252, 0x0, v252
	v_add_u32_e32 v242, v242, v252
	v_and_b32_e32 v251, 15, v250
	v_lshrrev_b32_e32 v252, 2, v251
	v_sub_u32_e32 v252, 0, v252
	v_and_b32_e32 v252, 3, v252
	v_lshrrev_b32_e32 v253, 4, v250
	v_xor_b32_e32 v252, v253, v252
	v_lshlrev_b32_e32 v252, 4, v252
	s_lshr_b32 s43, s8, 1
	s_and_b32 s44, s8, 1
	s_lshl_b32 s45, s43, 6
	s_lshl_b32 s50, s44, 7
	v_add_u32_e32 v246, s45, v251
	v_lshl_add_u32 v246, v246, 6, v252
	v_and_b32_e32 v247, 3, v251
	v_lshrrev_b32_e32 v249, 2, v251
	v_lshl_add_u32 v247, v249, 4, v247
	v_add_u32_e32 v247, s50, v247
	v_lshl_add_u32 v247, v247, 6, v252
	v_add_u32_e32 v247, 0x2000, v247
	v_lshl_add_u32 v249, v253, 4, s50
	v_lshlrev_b32_e32 v249, 1, v249
	v_add_u32_e32 v248, s45, v251
	v_lshl_add_u32 v248, v248, 13, v249
	s_waitcnt lgkmcnt(0)
	s_mov_b32 s51, 0
.Lmlp1_tile:
	s_lshl_b32 s43, s51, 3
	s_and_b32 s44, s4, 7
	s_add_u32 s43, s43, s44
	s_lshr_b32 s44, s43, 1
	s_lshl_b32 s44, s44, 3
	s_lshr_b32 s45, s4, 6
	s_add_u32 s44, s44, s45
	s_lshl_b32 s28, s44, 7
	s_and_b32 s43, s43, 1
	s_lshl_b32 s43, s43, 3
	s_lshr_b32 s45, s4, 3
	s_and_b32 s45, s45, 7
	s_add_u32 s43, s43, s45
	s_lshl_b32 s29, s43, 8
	s_mul_i32 s43, s28, 0x800
	s_add_u32 s12, s0, s43
	s_addc_u32 s13, s1, 0
	s_mul_i32 s43, s2, 0x800000
	s_mul_i32 s44, s29, 0x800
	s_add_u32 s43, s43, s44
	s_add_u32 s16, s6, s43
	s_addc_u32 s17, s7, 0
	s_barrier
	s_add_u32 m0, s10, 0x0
	s_nop 0
	global_load_lds_dwordx4 v240, s[12:13]
	s_add_u32 m0, s10, 0x400
	s_nop 0
	global_load_lds_dwordx4 v241, s[12:13]
	s_add_u32 m0, s32, 0x2000
	s_nop 0
	global_load_lds_dwordx4 v242, s[16:17]
	s_add_u32 m0, s32, 0x2400
	s_nop 0
	global_load_lds_dwordx4 v243, s[16:17]
	s_add_u32 m0, s32, 0x2800
	s_nop 0
	global_load_lds_dwordx4 v244, s[16:17]
	s_add_u32 m0, s32, 0x2c00
	s_nop 0
	global_load_lds_dwordx4 v245, s[16:17]
	s_add_u32 s12, s12, 64
	s_addc_u32 s13, s13, 0
	s_add_u32 s16, s16, 64
	s_addc_u32 s17, s17, 0
	s_add_u32 m0, s10, 0x6000
	s_nop 0
	global_load_lds_dwordx4 v240, s[12:13]
	s_add_u32 m0, s10, 0x6400
	s_nop 0
	global_load_lds_dwordx4 v241, s[12:13]
	s_add_u32 m0, s32, 0x8000
	s_nop 0
	global_load_lds_dwordx4 v242, s[16:17]
	s_add_u32 m0, s32, 0x8400
	s_nop 0
	global_load_lds_dwordx4 v243, s[16:17]
	s_add_u32 m0, s32, 0x8800
	s_nop 0
	global_load_lds_dwordx4 v244, s[16:17]
	s_add_u32 m0, s32, 0x8c00
	s_nop 0
	global_load_lds_dwordx4 v245, s[16:17]
	s_add_u32 s12, s12, 64
	s_addc_u32 s13, s13, 0
	s_add_u32 s16, s16, 64
	s_addc_u32 s17, s17, 0
	s_add_u32 m0, s10, 0xc000
	s_nop 0
	global_load_lds_dwordx4 v240, s[12:13]
	s_add_u32 m0, s10, 0xc400
	s_nop 0
	global_load_lds_dwordx4 v241, s[12:13]
	s_add_u32 m0, s32, 0xe000
	s_nop 0
	global_load_lds_dwordx4 v242, s[16:17]
	s_add_u32 m0, s32, 0xe400
	s_nop 0
	global_load_lds_dwordx4 v243, s[16:17]
	s_add_u32 m0, s32, 0xe800
	s_nop 0
	global_load_lds_dwordx4 v244, s[16:17]
	s_add_u32 m0, s32, 0xec00
	s_nop 0
	global_load_lds_dwordx4 v245, s[16:17]
	s_add_u32 s12, s12, 64
	s_addc_u32 s13, s13, 0
	s_add_u32 s16, s16, 64
	s_addc_u32 s17, s17, 0
	v_mov_b32_e32 v0, 0
	v_mov_b32_e32 v1, 0
	v_mov_b32_e32 v2, 0
	v_mov_b32_e32 v3, 0
	v_mov_b32_e32 v4, 0
	v_mov_b32_e32 v5, 0
	v_mov_b32_e32 v6, 0
	v_mov_b32_e32 v7, 0
	v_mov_b32_e32 v8, 0
	v_mov_b32_e32 v9, 0
	v_mov_b32_e32 v10, 0
	v_mov_b32_e32 v11, 0
	v_mov_b32_e32 v12, 0
	v_mov_b32_e32 v13, 0
	v_mov_b32_e32 v14, 0
	v_mov_b32_e32 v15, 0
	v_mov_b32_e32 v16, 0
	v_mov_b32_e32 v17, 0
	v_mov_b32_e32 v18, 0
	v_mov_b32_e32 v19, 0
	v_mov_b32_e32 v20, 0
	v_mov_b32_e32 v21, 0
	v_mov_b32_e32 v22, 0
	v_mov_b32_e32 v23, 0
	v_mov_b32_e32 v24, 0
	v_mov_b32_e32 v25, 0
	v_mov_b32_e32 v26, 0
; __device__ __forceinline__ void gemm_mainloop8(const bf16_t* __restrict__ A, int lda,
;                                                const bf16_t* __restrict__ B, int ldb, int K,
;                                                bf16_t* sbase, f32x4 (&acc)[4][8], const int tid) {
;     ...
;   for (int kt = 0; kt < nk; kt++) {
;     __syncthreads();
;     {
;       bf16_t* d_ = sbase + wofs;
;       *(u32x4*)(d_) = ra[0];
;       *(u32x4*)(d_ + 64 * GROW) = ra[1];
; #pragma unroll
;       for (int i = 0; i < 4; i++) *(u32x4*)(d_ + (128 + 64 * i) * GROW) = rb[i];
;     }
;     __syncthreads();
;     {
;       int kofs = min((kt + 1) * 32, K - 32);
;       ra[0] = *(const u32x4*)(pa + kofs); ra[1] = *(const u32x4*)(pa + a64 + kofs);
; #pragma unroll
;       for (int i = 0; i < 4; i++) rb[i] = *(const u32x4*)(pb + (size_t)i * b64 + kofs);
;     }
;     bf16x8 af[4], bfr[8];
; #pragma unroll
;     for (int mi = 0; mi < 4; mi++) af[mi] = *(const bf16x8*)(sbase + raofs + mi * 16 * GROW);
; #pragma unroll
;     for (int ni = 0; ni < 8; ni++) bfr[ni] = *(const bf16x8*)(sbase + rbofs + ni * 16 * GROW);
; #pragma unroll
;     for (int mi = 0; mi < 4; mi++)
; #pragma unroll
;       for (int ni = 0; ni < 8; ni++)
;         acc[mi][ni] = __builtin_amdgcn_mfma_f32_16x16x32_bf16(af[mi], bfr[ni], acc[mi][ni], 0, 0, 0);
; template <int NI>
; __device__ __forceinline__ void zero_acc(f32x4 (&acc)[4][NI]) {
; #pragma unroll
;   for (int a = 0; a < 4; a++)
; #pragma unroll
;     for (int b = 0; b < NI; b++) acc[a][b] = f32x4{0.f, 0.f, 0.f, 0.f};
	v_mov_b32_e32 v27, 0
	v_mov_b32_e32 v28, 0
	v_mov_b32_e32 v29, 0
	v_mov_b32_e32 v30, 0
	v_mov_b32_e32 v31, 0
	v_mov_b32_e32 v32, 0
	v_mov_b32_e32 v33, 0
	v_mov_b32_e32 v34, 0
	v_mov_b32_e32 v35, 0
	v_mov_b32_e32 v36, 0
	v_mov_b32_e32 v37, 0
	v_mov_b32_e32 v38, 0
	v_mov_b32_e32 v39, 0
	v_mov_b32_e32 v40, 0
	v_mov_b32_e32 v41, 0
	v_mov_b32_e32 v42, 0
	v_mov_b32_e32 v43, 0
	v_mov_b32_e32 v44, 0
	v_mov_b32_e32 v45, 0
	v_mov_b32_e32 v46, 0
	v_mov_b32_e32 v47, 0
	v_mov_b32_e32 v48, 0
	v_mov_b32_e32 v49, 0
	v_mov_b32_e32 v50, 0
	v_mov_b32_e32 v51, 0
	v_mov_b32_e32 v52, 0
	v_mov_b32_e32 v53, 0
	v_mov_b32_e32 v54, 0
	v_mov_b32_e32 v55, 0
	v_mov_b32_e32 v56, 0
	v_mov_b32_e32 v57, 0
	v_mov_b32_e32 v58, 0
	v_mov_b32_e32 v59, 0
	v_mov_b32_e32 v60, 0
	v_mov_b32_e32 v61, 0
	v_mov_b32_e32 v62, 0
	v_mov_b32_e32 v63, 0
	v_mov_b32_e32 v64, 0
	v_mov_b32_e32 v65, 0
	v_mov_b32_e32 v66, 0
	v_mov_b32_e32 v67, 0
	v_mov_b32_e32 v68, 0
	v_mov_b32_e32 v69, 0
	v_mov_b32_e32 v70, 0
	v_mov_b32_e32 v71, 0
	v_mov_b32_e32 v72, 0
	v_mov_b32_e32 v73, 0
	v_mov_b32_e32 v74, 0
	v_mov_b32_e32 v75, 0
	v_mov_b32_e32 v76, 0
	v_mov_b32_e32 v77, 0
	v_mov_b32_e32 v78, 0
	v_mov_b32_e32 v79, 0
	v_mov_b32_e32 v80, 0
	v_mov_b32_e32 v81, 0
	v_mov_b32_e32 v82, 0
	v_mov_b32_e32 v83, 0
	v_mov_b32_e32 v84, 0
	v_mov_b32_e32 v85, 0
	v_mov_b32_e32 v86, 0
	v_mov_b32_e32 v87, 0
	v_mov_b32_e32 v88, 0
	v_mov_b32_e32 v89, 0
	v_mov_b32_e32 v90, 0
	v_mov_b32_e32 v91, 0
	v_mov_b32_e32 v92, 0
	v_mov_b32_e32 v93, 0
	v_mov_b32_e32 v94, 0
	v_mov_b32_e32 v95, 0
	v_mov_b32_e32 v96, 0
	v_mov_b32_e32 v97, 0
	v_mov_b32_e32 v98, 0
	v_mov_b32_e32 v99, 0
	v_mov_b32_e32 v100, 0
	v_mov_b32_e32 v101, 0
	v_mov_b32_e32 v102, 0
	v_mov_b32_e32 v103, 0
	v_mov_b32_e32 v104, 0
	v_mov_b32_e32 v105, 0
	v_mov_b32_e32 v106, 0
	v_mov_b32_e32 v107, 0
	v_mov_b32_e32 v108, 0
	v_mov_b32_e32 v109, 0
	v_mov_b32_e32 v110, 0
	v_mov_b32_e32 v111, 0
	v_mov_b32_e32 v112, 0
	v_mov_b32_e32 v113, 0
	v_mov_b32_e32 v114, 0
	v_mov_b32_e32 v115, 0
	v_mov_b32_e32 v116, 0
	v_mov_b32_e32 v117, 0
	v_mov_b32_e32 v118, 0
	v_mov_b32_e32 v119, 0
	v_mov_b32_e32 v120, 0
	v_mov_b32_e32 v121, 0
	v_mov_b32_e32 v122, 0
	v_mov_b32_e32 v123, 0
	v_mov_b32_e32 v124, 0
	v_mov_b32_e32 v125, 0
	v_mov_b32_e32 v126, 0
	v_mov_b32_e32 v127, 0
	s_waitcnt vmcnt(12)
	s_barrier
	ds_read_b128 v[128:131], v246 offset:0
	ds_read_b128 v[148:151], v247 offset:0
	ds_read_b128 v[152:155], v247 offset:256
	ds_read_b128 v[132:135], v246 offset:1024
	ds_read_b128 v[156:159], v247 offset:512
	ds_read_b128 v[160:163], v247 offset:768
	ds_read_b128 v[136:139], v246 offset:2048
	ds_read_b128 v[168:171], v247 offset:4096
	ds_read_b128 v[172:175], v247 offset:4352
	ds_read_b128 v[140:143], v246 offset:3072
	ds_read_b128 v[176:179], v247 offset:4608
	ds_read_b128 v[180:183], v247 offset:4864
	s_mov_b32 s42, 0
.Lmlp1_kloop:
	s_waitcnt vmcnt(6) lgkmcnt(0)
	s_barrier
	s_add_u32 m0, s10, 0x0
	s_nop 0
	global_load_lds_dwordx4 v240, s[12:13]
	s_add_u32 m0, s10, 0x400
	s_nop 0
	global_load_lds_dwordx4 v241, s[12:13]
	s_add_u32 m0, s32, 0x2000
	s_nop 0
	global_load_lds_dwordx4 v242, s[16:17]
	s_add_u32 m0, s32, 0x2400
	s_nop 0
	global_load_lds_dwordx4 v243, s[16:17]
	s_add_u32 m0, s32, 0x2800
	s_nop 0
	global_load_lds_dwordx4 v244, s[16:17]
	s_add_u32 m0, s32, 0x2c00
	s_nop 0
	global_load_lds_dwordx4 v245, s[16:17]
	s_add_u32 s12, s12, 64
	s_addc_u32 s13, s13, 0
	s_add_u32 s16, s16, 64
	s_addc_u32 s17, s17, 0
	v_mfma_f32_16x16x32_bf16 v[0:3], v[148:151], v[128:131], v[0:3]
	ds_read_b128 v[184:187], v246 offset:24576
	v_mfma_f32_16x16x32_bf16 v[4:7], v[152:155], v[128:131], v[4:7]
	ds_read_b128 v[200:203], v247 offset:24576
	v_mfma_f32_16x16x32_bf16 v[8:11], v[156:159], v[128:131], v[8:11]
	ds_read_b128 v[204:207], v247 offset:24832
	v_mfma_f32_16x16x32_bf16 v[12:15], v[160:163], v[128:131], v[12:15]
	ds_read_b128 v[188:191], v246 offset:25600
	v_mfma_f32_16x16x32_bf16 v[16:19], v[168:171], v[128:131], v[16:19]
	ds_read_b128 v[208:211], v247 offset:25088
	v_mfma_f32_16x16x32_bf16 v[20:23], v[172:175], v[128:131], v[20:23]
	ds_read_b128 v[212:215], v247 offset:25344
	v_mfma_f32_16x16x32_bf16 v[24:27], v[176:179], v[128:131], v[24:27]
	ds_read_b128 v[192:195], v246 offset:26624
	v_mfma_f32_16x16x32_bf16 v[28:31], v[180:183], v[128:131], v[28:31]
	ds_read_b128 v[216:219], v247 offset:28672
	v_mfma_f32_16x16x32_bf16 v[32:35], v[148:151], v[132:135], v[32:35]
	ds_read_b128 v[220:223], v247 offset:28928
	v_mfma_f32_16x16x32_bf16 v[36:39], v[152:155], v[132:135], v[36:39]
	ds_read_b128 v[196:199], v246 offset:27648
	v_mfma_f32_16x16x32_bf16 v[40:43], v[156:159], v[132:135], v[40:43]
	ds_read_b128 v[228:231], v247 offset:29184
	v_mfma_f32_16x16x32_bf16 v[44:47], v[160:163], v[132:135], v[44:47]
	ds_read_b128 v[232:235], v247 offset:29440
	v_mfma_f32_16x16x32_bf16 v[48:51], v[168:171], v[132:135], v[48:51]
	v_mfma_f32_16x16x32_bf16 v[52:55], v[172:175], v[132:135], v[52:55]
	v_mfma_f32_16x16x32_bf16 v[56:59], v[176:179], v[132:135], v[56:59]
	v_mfma_f32_16x16x32_bf16 v[60:63], v[180:183], v[132:135], v[60:63]
	v_mfma_f32_16x16x32_bf16 v[64:67], v[148:151], v[136:139], v[64:67]
	v_mfma_f32_16x16x32_bf16 v[68:71], v[152:155], v[136:139], v[68:71]
	v_mfma_f32_16x16x32_bf16 v[72:75], v[156:159], v[136:139], v[72:75]
	v_mfma_f32_16x16x32_bf16 v[76:79], v[160:163], v[136:139], v[76:79]
	v_mfma_f32_16x16x32_bf16 v[80:83], v[168:171], v[136:139], v[80:83]
	v_mfma_f32_16x16x32_bf16 v[84:87], v[172:175], v[136:139], v[84:87]
	v_mfma_f32_16x16x32_bf16 v[88:91], v[176:179], v[136:139], v[88:91]
	v_mfma_f32_16x16x32_bf16 v[92:95], v[180:183], v[136:139], v[92:95]
	v_mfma_f32_16x16x32_bf16 v[96:99], v[148:151], v[140:143], v[96:99]
	v_mfma_f32_16x16x32_bf16 v[100:103], v[152:155], v[140:143], v[100:103]
	v_mfma_f32_16x16x32_bf16 v[104:107], v[156:159], v[140:143], v[104:107]
	v_mfma_f32_16x16x32_bf16 v[108:111], v[160:163], v[140:143], v[108:111]
	v_mfma_f32_16x16x32_bf16 v[112:115], v[168:171], v[140:143], v[112:115]
	v_mfma_f32_16x16x32_bf16 v[116:119], v[172:175], v[140:143], v[116:119]
	v_mfma_f32_16x16x32_bf16 v[120:123], v[176:179], v[140:143], v[120:123]
	v_mfma_f32_16x16x32_bf16 v[124:127], v[180:183], v[140:143], v[124:127]
	s_waitcnt vmcnt(6) lgkmcnt(0)
	s_barrier
; __device__ __forceinline__ void gemm_mainloop8(const bf16_t* __restrict__ A, int lda,
;                                                const bf16_t* __restrict__ B, int ldb, int K,
;                                                bf16_t* sbase, f32x4 (&acc)[4][8], const int tid) {
;     ...
;   for (int kt = 0; kt < nk; kt++) {
;     __syncthreads();
;     {
;       bf16_t* d_ = sbase + wofs;
;       *(u32x4*)(d_) = ra[0];
;       *(u32x4*)(d_ + 64 * GROW) = ra[1];
; #pragma unroll
;       for (int i = 0; i < 4; i++) *(u32x4*)(d_ + (128 + 64 * i) * GROW) = rb[i];
;     }
;     __syncthreads();
;     {
;       int kofs = min((kt + 1) * 32, K - 32);
;       ra[0] = *(const u32x4*)(pa + kofs); ra[1] = *(const u32x4*)(pa + a64 + kofs);
; #pragma unroll
;       for (int i = 0; i < 4; i++) rb[i] = *(const u32x4*)(pb + (size_t)i * b64 + kofs);
;     }
;     bf16x8 af[4], bfr[8];
; #pragma unroll
;     for (int mi = 0; mi < 4; mi++) af[mi] = *(const bf16x8*)(sbase + raofs + mi * 16 * GROW);
; #pragma unroll
;     for (int ni = 0; ni < 8; ni++) bfr[ni] = *(const bf16x8*)(sbase + rbofs + ni * 16 * GROW);
; #pragma unroll
;     for (int mi = 0; mi < 4; mi++)
; #pragma unroll
;       for (int ni = 0; ni < 8; ni++)
;         acc[mi][ni] = __builtin_amdgcn_mfma_f32_16x16x32_bf16(af[mi], bfr[ni], acc[mi][ni], 0, 0, 0);
	s_add_u32 m0, s10, 0x6000
	s_nop 0
	global_load_lds_dwordx4 v240, s[12:13]
	s_add_u32 m0, s10, 0x6400
	s_nop 0
	global_load_lds_dwordx4 v241, s[12:13]
	s_add_u32 m0, s32, 0x8000
	s_nop 0
	global_load_lds_dwordx4 v242, s[16:17]
	s_add_u32 m0, s32, 0x8400
	s_nop 0
	global_load_lds_dwordx4 v243, s[16:17]
	s_add_u32 m0, s32, 0x8800
	s_nop 0
	global_load_lds_dwordx4 v244, s[16:17]
	s_add_u32 m0, s32, 0x8c00
	s_nop 0
	global_load_lds_dwordx4 v245, s[16:17]
	s_add_u32 s12, s12, 64
	s_addc_u32 s13, s13, 0
	s_add_u32 s16, s16, 64
	s_addc_u32 s17, s17, 0
	v_mfma_f32_16x16x32_bf16 v[0:3], v[200:203], v[184:187], v[0:3]
	ds_read_b128 v[128:131], v246 offset:49152
	v_mfma_f32_16x16x32_bf16 v[4:7], v[204:207], v[184:187], v[4:7]
	ds_read_b128 v[148:151], v247 offset:49152
	v_mfma_f32_16x16x32_bf16 v[8:11], v[208:211], v[184:187], v[8:11]
	ds_read_b128 v[152:155], v247 offset:49408
	v_mfma_f32_16x16x32_bf16 v[12:15], v[212:215], v[184:187], v[12:15]
	ds_read_b128 v[132:135], v246 offset:50176
	v_mfma_f32_16x16x32_bf16 v[16:19], v[216:219], v[184:187], v[16:19]
	ds_read_b128 v[156:159], v247 offset:49664
	v_mfma_f32_16x16x32_bf16 v[20:23], v[220:223], v[184:187], v[20:23]
	ds_read_b128 v[160:163], v247 offset:49920
	v_mfma_f32_16x16x32_bf16 v[24:27], v[228:231], v[184:187], v[24:27]
	ds_read_b128 v[136:139], v246 offset:51200
	v_mfma_f32_16x16x32_bf16 v[28:31], v[232:235], v[184:187], v[28:31]
	ds_read_b128 v[168:171], v247 offset:53248
	v_mfma_f32_16x16x32_bf16 v[32:35], v[200:203], v[188:191], v[32:35]
	ds_read_b128 v[172:175], v247 offset:53504
	v_mfma_f32_16x16x32_bf16 v[36:39], v[204:207], v[188:191], v[36:39]
	ds_read_b128 v[140:143], v246 offset:52224
	v_mfma_f32_16x16x32_bf16 v[40:43], v[208:211], v[188:191], v[40:43]
	ds_read_b128 v[176:179], v247 offset:53760
	v_mfma_f32_16x16x32_bf16 v[44:47], v[212:215], v[188:191], v[44:47]
	ds_read_b128 v[180:183], v247 offset:54016
	v_mfma_f32_16x16x32_bf16 v[48:51], v[216:219], v[188:191], v[48:51]
	v_mfma_f32_16x16x32_bf16 v[52:55], v[220:223], v[188:191], v[52:55]
	v_mfma_f32_16x16x32_bf16 v[56:59], v[228:231], v[188:191], v[56:59]
	v_mfma_f32_16x16x32_bf16 v[60:63], v[232:235], v[188:191], v[60:63]
	v_mfma_f32_16x16x32_bf16 v[64:67], v[200:203], v[192:195], v[64:67]
	v_mfma_f32_16x16x32_bf16 v[68:71], v[204:207], v[192:195], v[68:71]
	v_mfma_f32_16x16x32_bf16 v[72:75], v[208:211], v[192:195], v[72:75]
	v_mfma_f32_16x16x32_bf16 v[76:79], v[212:215], v[192:195], v[76:79]
	v_mfma_f32_16x16x32_bf16 v[80:83], v[216:219], v[192:195], v[80:83]
	v_mfma_f32_16x16x32_bf16 v[84:87], v[220:223], v[192:195], v[84:87]
	v_mfma_f32_16x16x32_bf16 v[88:91], v[228:231], v[192:195], v[88:91]
	v_mfma_f32_16x16x32_bf16 v[92:95], v[232:235], v[192:195], v[92:95]
	v_mfma_f32_16x16x32_bf16 v[96:99], v[200:203], v[196:199], v[96:99]
	v_mfma_f32_16x16x32_bf16 v[100:103], v[204:207], v[196:199], v[100:103]
	v_mfma_f32_16x16x32_bf16 v[104:107], v[208:211], v[196:199], v[104:107]
	v_mfma_f32_16x16x32_bf16 v[108:111], v[212:215], v[196:199], v[108:111]
	v_mfma_f32_16x16x32_bf16 v[112:115], v[216:219], v[196:199], v[112:115]
	v_mfma_f32_16x16x32_bf16 v[116:119], v[220:223], v[196:199], v[116:119]
	v_mfma_f32_16x16x32_bf16 v[120:123], v[228:231], v[196:199], v[120:123]
	v_mfma_f32_16x16x32_bf16 v[124:127], v[232:235], v[196:199], v[124:127]
	s_waitcnt vmcnt(6) lgkmcnt(0)
	s_barrier
	s_add_u32 m0, s10, 0xc000
	s_nop 0
	global_load_lds_dwordx4 v240, s[12:13]
	s_add_u32 m0, s10, 0xc400
	s_nop 0
	global_load_lds_dwordx4 v241, s[12:13]
	s_add_u32 m0, s32, 0xe000
	s_nop 0
	global_load_lds_dwordx4 v242, s[16:17]
	s_add_u32 m0, s32, 0xe400
	s_nop 0
	global_load_lds_dwordx4 v243, s[16:17]
	s_add_u32 m0, s32, 0xe800
	s_nop 0
	global_load_lds_dwordx4 v244, s[16:17]
	s_add_u32 m0, s32, 0xec00
	s_nop 0
	global_load_lds_dwordx4 v245, s[16:17]
	s_add_u32 s12, s12, 64
	s_addc_u32 s13, s13, 0
	s_add_u32 s16, s16, 64
	s_addc_u32 s17, s17, 0
	v_mfma_f32_16x16x32_bf16 v[0:3], v[148:151], v[128:131], v[0:3]
	ds_read_b128 v[184:187], v246 offset:0
	v_mfma_f32_16x16x32_bf16 v[4:7], v[152:155], v[128:131], v[4:7]
	ds_read_b128 v[200:203], v247 offset:0
	v_mfma_f32_16x16x32_bf16 v[8:11], v[156:159], v[128:131], v[8:11]
	ds_read_b128 v[204:207], v247 offset:256
	v_mfma_f32_16x16x32_bf16 v[12:15], v[160:163], v[128:131], v[12:15]
	ds_read_b128 v[188:191], v246 offset:1024
	v_mfma_f32_16x16x32_bf16 v[16:19], v[168:171], v[128:131], v[16:19]
	ds_read_b128 v[208:211], v247 offset:512
	v_mfma_f32_16x16x32_bf16 v[20:23], v[172:175], v[128:131], v[20:23]
	ds_read_b128 v[212:215], v247 offset:768
	v_mfma_f32_16x16x32_bf16 v[24:27], v[176:179], v[128:131], v[24:27]
	ds_read_b128 v[192:195], v246 offset:2048
	v_mfma_f32_16x16x32_bf16 v[28:31], v[180:183], v[128:131], v[28:31]
	ds_read_b128 v[216:219], v247 offset:4096
	v_mfma_f32_16x16x32_bf16 v[32:35], v[148:151], v[132:135], v[32:35]
	ds_read_b128 v[220:223], v247 offset:4352
	v_mfma_f32_16x16x32_bf16 v[36:39], v[152:155], v[132:135], v[36:39]
	ds_read_b128 v[196:199], v246 offset:3072
	v_mfma_f32_16x16x32_bf16 v[40:43], v[156:159], v[132:135], v[40:43]
	ds_read_b128 v[228:231], v247 offset:4608
	v_mfma_f32_16x16x32_bf16 v[44:47], v[160:163], v[132:135], v[44:47]
	ds_read_b128 v[232:235], v247 offset:4864
	v_mfma_f32_16x16x32_bf16 v[48:51], v[168:171], v[132:135], v[48:51]
	v_mfma_f32_16x16x32_bf16 v[52:55], v[172:175], v[132:135], v[52:55]
	v_mfma_f32_16x16x32_bf16 v[56:59], v[176:179], v[132:135], v[56:59]
	v_mfma_f32_16x16x32_bf16 v[60:63], v[180:183], v[132:135], v[60:63]
	v_mfma_f32_16x16x32_bf16 v[64:67], v[148:151], v[136:139], v[64:67]
	v_mfma_f32_16x16x32_bf16 v[68:71], v[152:155], v[136:139], v[68:71]
	v_mfma_f32_16x16x32_bf16 v[72:75], v[156:159], v[136:139], v[72:75]
	v_mfma_f32_16x16x32_bf16 v[76:79], v[160:163], v[136:139], v[76:79]
	v_mfma_f32_16x16x32_bf16 v[80:83], v[168:171], v[136:139], v[80:83]
	v_mfma_f32_16x16x32_bf16 v[84:87], v[172:175], v[136:139], v[84:87]
	v_mfma_f32_16x16x32_bf16 v[88:91], v[176:179], v[136:139], v[88:91]
	v_mfma_f32_16x16x32_bf16 v[92:95], v[180:183], v[136:139], v[92:95]
	v_mfma_f32_16x16x32_bf16 v[96:99], v[148:151], v[140:143], v[96:99]
	v_mfma_f32_16x16x32_bf16 v[100:103], v[152:155], v[140:143], v[100:103]
	v_mfma_f32_16x16x32_bf16 v[104:107], v[156:159], v[140:143], v[104:107]
	v_mfma_f32_16x16x32_bf16 v[108:111], v[160:163], v[140:143], v[108:111]
	v_mfma_f32_16x16x32_bf16 v[112:115], v[168:171], v[140:143], v[112:115]
	v_mfma_f32_16x16x32_bf16 v[116:119], v[172:175], v[140:143], v[116:119]
	v_mfma_f32_16x16x32_bf16 v[120:123], v[176:179], v[140:143], v[120:123]
	v_mfma_f32_16x16x32_bf16 v[124:127], v[180:183], v[140:143], v[124:127]
	s_waitcnt vmcnt(6) lgkmcnt(0)
	s_barrier
; __device__ __forceinline__ void gemm_mainloop8(const bf16_t* __restrict__ A, int lda,
;                                                const bf16_t* __restrict__ B, int ldb, int K,
;                                                bf16_t* sbase, f32x4 (&acc)[4][8], const int tid) {
;     ...
;   for (int kt = 0; kt < nk; kt++) {
;     __syncthreads();
;     {
;       bf16_t* d_ = sbase + wofs;
;       *(u32x4*)(d_) = ra[0];
;       *(u32x4*)(d_ + 64 * GROW) = ra[1];
; #pragma unroll
;       for (int i = 0; i < 4; i++) *(u32x4*)(d_ + (128 + 64 * i) * GROW) = rb[i];
;     }
;     __syncthreads();
;     {
;       int kofs = min((kt + 1) * 32, K - 32);
;       ra[0] = *(const u32x4*)(pa + kofs); ra[1] = *(const u32x4*)(pa + a64 + kofs);
; #pragma unroll
;       for (int i = 0; i < 4; i++) rb[i] = *(const u32x4*)(pb + (size_t)i * b64 + kofs);
;     }
;     bf16x8 af[4], bfr[8];
; #pragma unroll
;     for (int mi = 0; mi < 4; mi++) af[mi] = *(const bf16x8*)(sbase + raofs + mi * 16 * GROW);
; #pragma unroll
;     for (int ni = 0; ni < 8; ni++) bfr[ni] = *(const bf16x8*)(sbase + rbofs + ni * 16 * GROW);
; #pragma unroll
;     for (int mi = 0; mi < 4; mi++)
; #pragma unroll
;       for (int ni = 0; ni < 8; ni++)
;         acc[mi][ni] = __builtin_amdgcn_mfma_f32_16x16x32_bf16(af[mi], bfr[ni], acc[mi][ni], 0, 0, 0);
	s_add_u32 m0, s10, 0x0
	s_nop 0
	global_load_lds_dwordx4 v240, s[12:13]
	s_add_u32 m0, s10, 0x400
	s_nop 0
	global_load_lds_dwordx4 v241, s[12:13]
	s_add_u32 m0, s32, 0x2000
	s_nop 0
	global_load_lds_dwordx4 v242, s[16:17]
	s_add_u32 m0, s32, 0x2400
	s_nop 0
	global_load_lds_dwordx4 v243, s[16:17]
	s_add_u32 m0, s32, 0x2800
	s_nop 0
	global_load_lds_dwordx4 v244, s[16:17]
	s_add_u32 m0, s32, 0x2c00
	s_nop 0
	global_load_lds_dwordx4 v245, s[16:17]
	s_add_u32 s12, s12, 64
	s_addc_u32 s13, s13, 0
	s_add_u32 s16, s16, 64
	s_addc_u32 s17, s17, 0
	v_mfma_f32_16x16x32_bf16 v[0:3], v[200:203], v[184:187], v[0:3]
	ds_read_b128 v[128:131], v246 offset:24576
	v_mfma_f32_16x16x32_bf16 v[4:7], v[204:207], v[184:187], v[4:7]
	ds_read_b128 v[148:151], v247 offset:24576
	v_mfma_f32_16x16x32_bf16 v[8:11], v[208:211], v[184:187], v[8:11]
	ds_read_b128 v[152:155], v247 offset:24832
	v_mfma_f32_16x16x32_bf16 v[12:15], v[212:215], v[184:187], v[12:15]
	ds_read_b128 v[132:135], v246 offset:25600
	v_mfma_f32_16x16x32_bf16 v[16:19], v[216:219], v[184:187], v[16:19]
	ds_read_b128 v[156:159], v247 offset:25088
	v_mfma_f32_16x16x32_bf16 v[20:23], v[220:223], v[184:187], v[20:23]
	ds_read_b128 v[160:163], v247 offset:25344
	v_mfma_f32_16x16x32_bf16 v[24:27], v[228:231], v[184:187], v[24:27]
	ds_read_b128 v[136:139], v246 offset:26624
	v_mfma_f32_16x16x32_bf16 v[28:31], v[232:235], v[184:187], v[28:31]
	ds_read_b128 v[168:171], v247 offset:28672
	v_mfma_f32_16x16x32_bf16 v[32:35], v[200:203], v[188:191], v[32:35]
	ds_read_b128 v[172:175], v247 offset:28928
	v_mfma_f32_16x16x32_bf16 v[36:39], v[204:207], v[188:191], v[36:39]
	ds_read_b128 v[140:143], v246 offset:27648
	v_mfma_f32_16x16x32_bf16 v[40:43], v[208:211], v[188:191], v[40:43]
	ds_read_b128 v[176:179], v247 offset:29184
	v_mfma_f32_16x16x32_bf16 v[44:47], v[212:215], v[188:191], v[44:47]
	ds_read_b128 v[180:183], v247 offset:29440
	v_mfma_f32_16x16x32_bf16 v[48:51], v[216:219], v[188:191], v[48:51]
	v_mfma_f32_16x16x32_bf16 v[52:55], v[220:223], v[188:191], v[52:55]
	v_mfma_f32_16x16x32_bf16 v[56:59], v[228:231], v[188:191], v[56:59]
	v_mfma_f32_16x16x32_bf16 v[60:63], v[232:235], v[188:191], v[60:63]
	v_mfma_f32_16x16x32_bf16 v[64:67], v[200:203], v[192:195], v[64:67]
	v_mfma_f32_16x16x32_bf16 v[68:71], v[204:207], v[192:195], v[68:71]
	v_mfma_f32_16x16x32_bf16 v[72:75], v[208:211], v[192:195], v[72:75]
	v_mfma_f32_16x16x32_bf16 v[76:79], v[212:215], v[192:195], v[76:79]
	v_mfma_f32_16x16x32_bf16 v[80:83], v[216:219], v[192:195], v[80:83]
	v_mfma_f32_16x16x32_bf16 v[84:87], v[220:223], v[192:195], v[84:87]
	v_mfma_f32_16x16x32_bf16 v[88:91], v[228:231], v[192:195], v[88:91]
	v_mfma_f32_16x16x32_bf16 v[92:95], v[232:235], v[192:195], v[92:95]
	v_mfma_f32_16x16x32_bf16 v[96:99], v[200:203], v[196:199], v[96:99]
	v_mfma_f32_16x16x32_bf16 v[100:103], v[204:207], v[196:199], v[100:103]
	v_mfma_f32_16x16x32_bf16 v[104:107], v[208:211], v[196:199], v[104:107]
	v_mfma_f32_16x16x32_bf16 v[108:111], v[212:215], v[196:199], v[108:111]
	v_mfma_f32_16x16x32_bf16 v[112:115], v[216:219], v[196:199], v[112:115]
	v_mfma_f32_16x16x32_bf16 v[116:119], v[220:223], v[196:199], v[116:119]
	v_mfma_f32_16x16x32_bf16 v[120:123], v[228:231], v[196:199], v[120:123]
	v_mfma_f32_16x16x32_bf16 v[124:127], v[232:235], v[196:199], v[124:127]
	s_waitcnt vmcnt(6) lgkmcnt(0)
	s_barrier
	s_add_u32 m0, s10, 0x6000
	s_nop 0
	global_load_lds_dwordx4 v240, s[12:13]
	s_add_u32 m0, s10, 0x6400
	s_nop 0
	global_load_lds_dwordx4 v241, s[12:13]
	s_add_u32 m0, s32, 0x8000
	s_nop 0
	global_load_lds_dwordx4 v242, s[16:17]
	s_add_u32 m0, s32, 0x8400
	s_nop 0
	global_load_lds_dwordx4 v243, s[16:17]
	s_add_u32 m0, s32, 0x8800
	s_nop 0
	global_load_lds_dwordx4 v244, s[16:17]
	s_add_u32 m0, s32, 0x8c00
	s_nop 0
	global_load_lds_dwordx4 v245, s[16:17]
	s_add_u32 s12, s12, 64
	s_addc_u32 s13, s13, 0
	s_add_u32 s16, s16, 64
	s_addc_u32 s17, s17, 0
	v_mfma_f32_16x16x32_bf16 v[0:3], v[148:151], v[128:131], v[0:3]
	ds_read_b128 v[184:187], v246 offset:49152
	v_mfma_f32_16x16x32_bf16 v[4:7], v[152:155], v[128:131], v[4:7]
	ds_read_b128 v[200:203], v247 offset:49152
	v_mfma_f32_16x16x32_bf16 v[8:11], v[156:159], v[128:131], v[8:11]
	ds_read_b128 v[204:207], v247 offset:49408
	v_mfma_f32_16x16x32_bf16 v[12:15], v[160:163], v[128:131], v[12:15]
	ds_read_b128 v[188:191], v246 offset:50176
	v_mfma_f32_16x16x32_bf16 v[16:19], v[168:171], v[128:131], v[16:19]
	ds_read_b128 v[208:211], v247 offset:49664
	v_mfma_f32_16x16x32_bf16 v[20:23], v[172:175], v[128:131], v[20:23]
	ds_read_b128 v[212:215], v247 offset:49920
	v_mfma_f32_16x16x32_bf16 v[24:27], v[176:179], v[128:131], v[24:27]
	ds_read_b128 v[192:195], v246 offset:51200
	v_mfma_f32_16x16x32_bf16 v[28:31], v[180:183], v[128:131], v[28:31]
	ds_read_b128 v[216:219], v247 offset:53248
	v_mfma_f32_16x16x32_bf16 v[32:35], v[148:151], v[132:135], v[32:35]
	ds_read_b128 v[220:223], v247 offset:53504
	v_mfma_f32_16x16x32_bf16 v[36:39], v[152:155], v[132:135], v[36:39]
	ds_read_b128 v[196:199], v246 offset:52224
	v_mfma_f32_16x16x32_bf16 v[40:43], v[156:159], v[132:135], v[40:43]
	ds_read_b128 v[228:231], v247 offset:53760
	v_mfma_f32_16x16x32_bf16 v[44:47], v[160:163], v[132:135], v[44:47]
	ds_read_b128 v[232:235], v247 offset:54016
	v_mfma_f32_16x16x32_bf16 v[48:51], v[168:171], v[132:135], v[48:51]
	v_mfma_f32_16x16x32_bf16 v[52:55], v[172:175], v[132:135], v[52:55]
	v_mfma_f32_16x16x32_bf16 v[56:59], v[176:179], v[132:135], v[56:59]
	v_mfma_f32_16x16x32_bf16 v[60:63], v[180:183], v[132:135], v[60:63]
	v_mfma_f32_16x16x32_bf16 v[64:67], v[148:151], v[136:139], v[64:67]
	v_mfma_f32_16x16x32_bf16 v[68:71], v[152:155], v[136:139], v[68:71]
	v_mfma_f32_16x16x32_bf16 v[72:75], v[156:159], v[136:139], v[72:75]
	v_mfma_f32_16x16x32_bf16 v[76:79], v[160:163], v[136:139], v[76:79]
	v_mfma_f32_16x16x32_bf16 v[80:83], v[168:171], v[136:139], v[80:83]
	v_mfma_f32_16x16x32_bf16 v[84:87], v[172:175], v[136:139], v[84:87]
	v_mfma_f32_16x16x32_bf16 v[88:91], v[176:179], v[136:139], v[88:91]
	v_mfma_f32_16x16x32_bf16 v[92:95], v[180:183], v[136:139], v[92:95]
	v_mfma_f32_16x16x32_bf16 v[96:99], v[148:151], v[140:143], v[96:99]
	v_mfma_f32_16x16x32_bf16 v[100:103], v[152:155], v[140:143], v[100:103]
	v_mfma_f32_16x16x32_bf16 v[104:107], v[156:159], v[140:143], v[104:107]
	v_mfma_f32_16x16x32_bf16 v[108:111], v[160:163], v[140:143], v[108:111]
	v_mfma_f32_16x16x32_bf16 v[112:115], v[168:171], v[140:143], v[112:115]
	v_mfma_f32_16x16x32_bf16 v[116:119], v[172:175], v[140:143], v[116:119]
	v_mfma_f32_16x16x32_bf16 v[120:123], v[176:179], v[140:143], v[120:123]
	v_mfma_f32_16x16x32_bf16 v[124:127], v[180:183], v[140:143], v[124:127]
	s_waitcnt vmcnt(6) lgkmcnt(0)
	s_barrier
; __device__ __forceinline__ void gemm_mainloop8(const bf16_t* __restrict__ A, int lda,
;                                                const bf16_t* __restrict__ B, int ldb, int K,
;                                                bf16_t* sbase, f32x4 (&acc)[4][8], const int tid) {
;     ...
;   for (int kt = 0; kt < nk; kt++) {
;     __syncthreads();
;     {
;       bf16_t* d_ = sbase + wofs;
;       *(u32x4*)(d_) = ra[0];
;       *(u32x4*)(d_ + 64 * GROW) = ra[1];
; #pragma unroll
;       for (int i = 0; i < 4; i++) *(u32x4*)(d_ + (128 + 64 * i) * GROW) = rb[i];
;     }
;     __syncthreads();
;     {
;       int kofs = min((kt + 1) * 32, K - 32);
;       ra[0] = *(const u32x4*)(pa + kofs); ra[1] = *(const u32x4*)(pa + a64 + kofs);
; #pragma unroll
;       for (int i = 0; i < 4; i++) rb[i] = *(const u32x4*)(pb + (size_t)i * b64 + kofs);
;     }
;     bf16x8 af[4], bfr[8];
; #pragma unroll
;     for (int mi = 0; mi < 4; mi++) af[mi] = *(const bf16x8*)(sbase + raofs + mi * 16 * GROW);
; #pragma unroll
;     for (int ni = 0; ni < 8; ni++) bfr[ni] = *(const bf16x8*)(sbase + rbofs + ni * 16 * GROW);
; #pragma unroll
;     for (int mi = 0; mi < 4; mi++)
; #pragma unroll
;       for (int ni = 0; ni < 8; ni++)
;         acc[mi][ni] = __builtin_amdgcn_mfma_f32_16x16x32_bf16(af[mi], bfr[ni], acc[mi][ni], 0, 0, 0);
	s_add_u32 m0, s10, 0xc000
	s_nop 0
	global_load_lds_dwordx4 v240, s[12:13]
	s_add_u32 m0, s10, 0xc400
	s_nop 0
	global_load_lds_dwordx4 v241, s[12:13]
	s_add_u32 m0, s32, 0xe000
	s_nop 0
	global_load_lds_dwordx4 v242, s[16:17]
	s_add_u32 m0, s32, 0xe400
	s_nop 0
	global_load_lds_dwordx4 v243, s[16:17]
	s_add_u32 m0, s32, 0xe800
	s_nop 0
	global_load_lds_dwordx4 v244, s[16:17]
	s_add_u32 m0, s32, 0xec00
	s_nop 0
	global_load_lds_dwordx4 v245, s[16:17]
	s_add_u32 s12, s12, 64
	s_addc_u32 s13, s13, 0
	s_add_u32 s16, s16, 64
	s_addc_u32 s17, s17, 0
	v_mfma_f32_16x16x32_bf16 v[0:3], v[200:203], v[184:187], v[0:3]
	ds_read_b128 v[128:131], v246 offset:0
	v_mfma_f32_16x16x32_bf16 v[4:7], v[204:207], v[184:187], v[4:7]
	ds_read_b128 v[148:151], v247 offset:0
	v_mfma_f32_16x16x32_bf16 v[8:11], v[208:211], v[184:187], v[8:11]
	ds_read_b128 v[152:155], v247 offset:256
	v_mfma_f32_16x16x32_bf16 v[12:15], v[212:215], v[184:187], v[12:15]
	ds_read_b128 v[132:135], v246 offset:1024
	v_mfma_f32_16x16x32_bf16 v[16:19], v[216:219], v[184:187], v[16:19]
	ds_read_b128 v[156:159], v247 offset:512
	v_mfma_f32_16x16x32_bf16 v[20:23], v[220:223], v[184:187], v[20:23]
	ds_read_b128 v[160:163], v247 offset:768
	v_mfma_f32_16x16x32_bf16 v[24:27], v[228:231], v[184:187], v[24:27]
	ds_read_b128 v[136:139], v246 offset:2048
	v_mfma_f32_16x16x32_bf16 v[28:31], v[232:235], v[184:187], v[28:31]
	ds_read_b128 v[168:171], v247 offset:4096
	v_mfma_f32_16x16x32_bf16 v[32:35], v[200:203], v[188:191], v[32:35]
	ds_read_b128 v[172:175], v247 offset:4352
	v_mfma_f32_16x16x32_bf16 v[36:39], v[204:207], v[188:191], v[36:39]
	ds_read_b128 v[140:143], v246 offset:3072
	v_mfma_f32_16x16x32_bf16 v[40:43], v[208:211], v[188:191], v[40:43]
	ds_read_b128 v[176:179], v247 offset:4608
	v_mfma_f32_16x16x32_bf16 v[44:47], v[212:215], v[188:191], v[44:47]
	ds_read_b128 v[180:183], v247 offset:4864
	v_mfma_f32_16x16x32_bf16 v[48:51], v[216:219], v[188:191], v[48:51]
	v_mfma_f32_16x16x32_bf16 v[52:55], v[220:223], v[188:191], v[52:55]
	v_mfma_f32_16x16x32_bf16 v[56:59], v[228:231], v[188:191], v[56:59]
	v_mfma_f32_16x16x32_bf16 v[60:63], v[232:235], v[188:191], v[60:63]
	v_mfma_f32_16x16x32_bf16 v[64:67], v[200:203], v[192:195], v[64:67]
	v_mfma_f32_16x16x32_bf16 v[68:71], v[204:207], v[192:195], v[68:71]
	v_mfma_f32_16x16x32_bf16 v[72:75], v[208:211], v[192:195], v[72:75]
	v_mfma_f32_16x16x32_bf16 v[76:79], v[212:215], v[192:195], v[76:79]
	v_mfma_f32_16x16x32_bf16 v[80:83], v[216:219], v[192:195], v[80:83]
	v_mfma_f32_16x16x32_bf16 v[84:87], v[220:223], v[192:195], v[84:87]
	v_mfma_f32_16x16x32_bf16 v[88:91], v[228:231], v[192:195], v[88:91]
	v_mfma_f32_16x16x32_bf16 v[92:95], v[232:235], v[192:195], v[92:95]
	v_mfma_f32_16x16x32_bf16 v[96:99], v[200:203], v[196:199], v[96:99]
	v_mfma_f32_16x16x32_bf16 v[100:103], v[204:207], v[196:199], v[100:103]
	v_mfma_f32_16x16x32_bf16 v[104:107], v[208:211], v[196:199], v[104:107]
	v_mfma_f32_16x16x32_bf16 v[108:111], v[212:215], v[196:199], v[108:111]
	v_mfma_f32_16x16x32_bf16 v[112:115], v[216:219], v[196:199], v[112:115]
	v_mfma_f32_16x16x32_bf16 v[116:119], v[220:223], v[196:199], v[116:119]
	v_mfma_f32_16x16x32_bf16 v[120:123], v[228:231], v[196:199], v[120:123]
	v_mfma_f32_16x16x32_bf16 v[124:127], v[232:235], v[196:199], v[124:127]
	s_add_u32 s42, s42, 1
	s_cmp_lt_u32 s42, 5
	s_cbranch_scc1 .Lmlp1_kloop
	s_waitcnt vmcnt(6) lgkmcnt(0)
	s_barrier
	s_add_u32 m0, s10, 0x0
	s_nop 0
	global_load_lds_dwordx4 v240, s[12:13]
	s_add_u32 m0, s10, 0x400
	s_nop 0
	global_load_lds_dwordx4 v241, s[12:13]
	s_add_u32 m0, s32, 0x2000
	s_nop 0
	global_load_lds_dwordx4 v242, s[16:17]
	s_add_u32 m0, s32, 0x2400
	s_nop 0
	global_load_lds_dwordx4 v243, s[16:17]
	s_add_u32 m0, s32, 0x2800
	s_nop 0
	global_load_lds_dwordx4 v244, s[16:17]
	s_add_u32 m0, s32, 0x2c00
	s_nop 0
	global_load_lds_dwordx4 v245, s[16:17]
	s_add_u32 s12, s12, 64
	s_addc_u32 s13, s13, 0
	s_add_u32 s16, s16, 64
	s_addc_u32 s17, s17, 0
	v_mfma_f32_16x16x32_bf16 v[0:3], v[148:151], v[128:131], v[0:3]
	ds_read_b128 v[184:187], v246 offset:24576
	v_mfma_f32_16x16x32_bf16 v[4:7], v[152:155], v[128:131], v[4:7]
	ds_read_b128 v[200:203], v247 offset:24576
	v_mfma_f32_16x16x32_bf16 v[8:11], v[156:159], v[128:131], v[8:11]
	ds_read_b128 v[204:207], v247 offset:24832
	v_mfma_f32_16x16x32_bf16 v[12:15], v[160:163], v[128:131], v[12:15]
	ds_read_b128 v[188:191], v246 offset:25600
	v_mfma_f32_16x16x32_bf16 v[16:19], v[168:171], v[128:131], v[16:19]
	ds_read_b128 v[208:211], v247 offset:25088
	v_mfma_f32_16x16x32_bf16 v[20:23], v[172:175], v[128:131], v[20:23]
	ds_read_b128 v[212:215], v247 offset:25344
	v_mfma_f32_16x16x32_bf16 v[24:27], v[176:179], v[128:131], v[24:27]
	ds_read_b128 v[192:195], v246 offset:26624
	v_mfma_f32_16x16x32_bf16 v[28:31], v[180:183], v[128:131], v[28:31]
	ds_read_b128 v[216:219], v247 offset:28672
	v_mfma_f32_16x16x32_bf16 v[32:35], v[148:151], v[132:135], v[32:35]
	ds_read_b128 v[220:223], v247 offset:28928
	v_mfma_f32_16x16x32_bf16 v[36:39], v[152:155], v[132:135], v[36:39]
	ds_read_b128 v[196:199], v246 offset:27648
	v_mfma_f32_16x16x32_bf16 v[40:43], v[156:159], v[132:135], v[40:43]
	ds_read_b128 v[228:231], v247 offset:29184
	v_mfma_f32_16x16x32_bf16 v[44:47], v[160:163], v[132:135], v[44:47]
	ds_read_b128 v[232:235], v247 offset:29440
	v_mfma_f32_16x16x32_bf16 v[48:51], v[168:171], v[132:135], v[48:51]
	v_mfma_f32_16x16x32_bf16 v[52:55], v[172:175], v[132:135], v[52:55]
	v_mfma_f32_16x16x32_bf16 v[56:59], v[176:179], v[132:135], v[56:59]
	v_mfma_f32_16x16x32_bf16 v[60:63], v[180:183], v[132:135], v[60:63]
	v_mfma_f32_16x16x32_bf16 v[64:67], v[148:151], v[136:139], v[64:67]
	v_mfma_f32_16x16x32_bf16 v[68:71], v[152:155], v[136:139], v[68:71]
	v_mfma_f32_16x16x32_bf16 v[72:75], v[156:159], v[136:139], v[72:75]
	v_mfma_f32_16x16x32_bf16 v[76:79], v[160:163], v[136:139], v[76:79]
	v_mfma_f32_16x16x32_bf16 v[80:83], v[168:171], v[136:139], v[80:83]
	v_mfma_f32_16x16x32_bf16 v[84:87], v[172:175], v[136:139], v[84:87]
	v_mfma_f32_16x16x32_bf16 v[88:91], v[176:179], v[136:139], v[88:91]
	v_mfma_f32_16x16x32_bf16 v[92:95], v[180:183], v[136:139], v[92:95]
	v_mfma_f32_16x16x32_bf16 v[96:99], v[148:151], v[140:143], v[96:99]
	v_mfma_f32_16x16x32_bf16 v[100:103], v[152:155], v[140:143], v[100:103]
	v_mfma_f32_16x16x32_bf16 v[104:107], v[156:159], v[140:143], v[104:107]
	v_mfma_f32_16x16x32_bf16 v[108:111], v[160:163], v[140:143], v[108:111]
	v_mfma_f32_16x16x32_bf16 v[112:115], v[168:171], v[140:143], v[112:115]
	v_mfma_f32_16x16x32_bf16 v[116:119], v[172:175], v[140:143], v[116:119]
	v_mfma_f32_16x16x32_bf16 v[120:123], v[176:179], v[140:143], v[120:123]
	v_mfma_f32_16x16x32_bf16 v[124:127], v[180:183], v[140:143], v[124:127]
	s_waitcnt vmcnt(6) lgkmcnt(0)
	s_barrier
; __device__ __forceinline__ void gemm_mainloop8(const bf16_t* __restrict__ A, int lda,
;                                                const bf16_t* __restrict__ B, int ldb, int K,
;                                                bf16_t* sbase, f32x4 (&acc)[4][8], const int tid) {
;     ...
;     bf16x8 af[4], bfr[8];
; #pragma unroll
;     for (int mi = 0; mi < 4; mi++) af[mi] = *(const bf16x8*)(sbase + raofs + mi * 16 * GROW);
; #pragma unroll
;     for (int ni = 0; ni < 8; ni++) bfr[ni] = *(const bf16x8*)(sbase + rbofs + ni * 16 * GROW);
; #pragma unroll
;     for (int mi = 0; mi < 4; mi++)
; #pragma unroll
;       for (int ni = 0; ni < 8; ni++)
;         acc[mi][ni] = __builtin_amdgcn_mfma_f32_16x16x32_bf16(af[mi], bfr[ni], acc[mi][ni], 0, 0, 0);
;   }
;   asm volatile("s_nop 15\n\ts_nop 15" ::: "memory");
; __device__ void phase_mlp1_big(CParams& p, int l, int tm, int tn, char* smem) {
;     ...
;   const int lane = tid & 63, wid = tid >> 6, wr = wid >> 1, wc = wid & 1;
; #pragma unroll
;   for (int mi = 0; mi < 4; mi++)
; #pragma unroll
;     for (int ni = 0; ni < 8; ni++)
; #pragma unroll
;       for (int j = 0; j < 4; j++) {
;         int rl = wr * 64 + mi * 16 + (lane >> 4) * 4 + j;
;         int cl = wc * 128 + ni * 16 + (lane & 15);
;         float a = fmaxf(acc[mi][ni][j], 0.f);
;         p.hidden[(size_t)(row0 + rl) * DFF + col0 + cl] = f2bf(a * a);
;       }
	s_add_u32 m0, s10, 0x6000
	s_nop 0
	global_load_lds_dwordx4 v240, s[12:13]
	s_add_u32 m0, s10, 0x6400
	s_nop 0
	global_load_lds_dwordx4 v241, s[12:13]
	s_add_u32 m0, s32, 0x8000
	s_nop 0
	global_load_lds_dwordx4 v242, s[16:17]
	s_add_u32 m0, s32, 0x8400
	s_nop 0
	global_load_lds_dwordx4 v243, s[16:17]
	s_add_u32 m0, s32, 0x8800
	s_nop 0
	global_load_lds_dwordx4 v244, s[16:17]
	s_add_u32 m0, s32, 0x8c00
	s_nop 0
	global_load_lds_dwordx4 v245, s[16:17]
	s_add_u32 s12, s12, 64
	s_addc_u32 s13, s13, 0
	s_add_u32 s16, s16, 64
	s_addc_u32 s17, s17, 0
	v_mfma_f32_16x16x32_bf16 v[0:3], v[200:203], v[184:187], v[0:3]
	ds_read_b128 v[128:131], v246 offset:49152
	v_mfma_f32_16x16x32_bf16 v[4:7], v[204:207], v[184:187], v[4:7]
	ds_read_b128 v[148:151], v247 offset:49152
	v_mfma_f32_16x16x32_bf16 v[8:11], v[208:211], v[184:187], v[8:11]
	ds_read_b128 v[152:155], v247 offset:49408
	v_mfma_f32_16x16x32_bf16 v[12:15], v[212:215], v[184:187], v[12:15]
	ds_read_b128 v[132:135], v246 offset:50176
	v_mfma_f32_16x16x32_bf16 v[16:19], v[216:219], v[184:187], v[16:19]
	ds_read_b128 v[156:159], v247 offset:49664
	v_mfma_f32_16x16x32_bf16 v[20:23], v[220:223], v[184:187], v[20:23]
	ds_read_b128 v[160:163], v247 offset:49920
	v_mfma_f32_16x16x32_bf16 v[24:27], v[228:231], v[184:187], v[24:27]
	ds_read_b128 v[136:139], v246 offset:51200
	v_mfma_f32_16x16x32_bf16 v[28:31], v[232:235], v[184:187], v[28:31]
	ds_read_b128 v[168:171], v247 offset:53248
	v_mfma_f32_16x16x32_bf16 v[32:35], v[200:203], v[188:191], v[32:35]
	ds_read_b128 v[172:175], v247 offset:53504
	v_mfma_f32_16x16x32_bf16 v[36:39], v[204:207], v[188:191], v[36:39]
	ds_read_b128 v[140:143], v246 offset:52224
	v_mfma_f32_16x16x32_bf16 v[40:43], v[208:211], v[188:191], v[40:43]
	ds_read_b128 v[176:179], v247 offset:53760
	v_mfma_f32_16x16x32_bf16 v[44:47], v[212:215], v[188:191], v[44:47]
	ds_read_b128 v[180:183], v247 offset:54016
	v_mfma_f32_16x16x32_bf16 v[48:51], v[216:219], v[188:191], v[48:51]
	v_mfma_f32_16x16x32_bf16 v[52:55], v[220:223], v[188:191], v[52:55]
	v_mfma_f32_16x16x32_bf16 v[56:59], v[228:231], v[188:191], v[56:59]
	v_mfma_f32_16x16x32_bf16 v[60:63], v[232:235], v[188:191], v[60:63]
	v_mfma_f32_16x16x32_bf16 v[64:67], v[200:203], v[192:195], v[64:67]
	v_mfma_f32_16x16x32_bf16 v[68:71], v[204:207], v[192:195], v[68:71]
	v_mfma_f32_16x16x32_bf16 v[72:75], v[208:211], v[192:195], v[72:75]
	v_mfma_f32_16x16x32_bf16 v[76:79], v[212:215], v[192:195], v[76:79]
	v_mfma_f32_16x16x32_bf16 v[80:83], v[216:219], v[192:195], v[80:83]
	v_mfma_f32_16x16x32_bf16 v[84:87], v[220:223], v[192:195], v[84:87]
	v_mfma_f32_16x16x32_bf16 v[88:91], v[228:231], v[192:195], v[88:91]
	v_mfma_f32_16x16x32_bf16 v[92:95], v[232:235], v[192:195], v[92:95]
	v_mfma_f32_16x16x32_bf16 v[96:99], v[200:203], v[196:199], v[96:99]
	v_mfma_f32_16x16x32_bf16 v[100:103], v[204:207], v[196:199], v[100:103]
	v_mfma_f32_16x16x32_bf16 v[104:107], v[208:211], v[196:199], v[104:107]
	v_mfma_f32_16x16x32_bf16 v[108:111], v[212:215], v[196:199], v[108:111]
	v_mfma_f32_16x16x32_bf16 v[112:115], v[216:219], v[196:199], v[112:115]
	v_mfma_f32_16x16x32_bf16 v[116:119], v[220:223], v[196:199], v[116:119]
	v_mfma_f32_16x16x32_bf16 v[120:123], v[228:231], v[196:199], v[120:123]
	v_mfma_f32_16x16x32_bf16 v[124:127], v[232:235], v[196:199], v[124:127]
	s_waitcnt vmcnt(0) lgkmcnt(0)
	s_barrier
	s_nop 15
	s_nop 15
	s_mul_i32 s43, s28, 0x2000
	s_lshl_b32 s44, s29, 1
	s_add_u32 s43, s43, s44
	s_add_u32 s54, s24, s43
	s_addc_u32 s55, s25, 0
	v_max_f32_e32 v0, 0, v0
	v_max_f32_e32 v1, 0, v1
	v_max_f32_e32 v2, 0, v2
	v_max_f32_e32 v3, 0, v3
	v_max_f32_e32 v4, 0, v4
	v_max_f32_e32 v5, 0, v5
	v_max_f32_e32 v6, 0, v6
	v_max_f32_e32 v7, 0, v7
	v_max_f32_e32 v8, 0, v8
	v_max_f32_e32 v9, 0, v9
	v_max_f32_e32 v10, 0, v10
	v_max_f32_e32 v11, 0, v11
	v_max_f32_e32 v12, 0, v12
	v_max_f32_e32 v13, 0, v13
	v_max_f32_e32 v14, 0, v14
	v_max_f32_e32 v15, 0, v15
	v_max_f32_e32 v16, 0, v16
	v_max_f32_e32 v17, 0, v17
	v_max_f32_e32 v18, 0, v18
	v_max_f32_e32 v19, 0, v19
	v_max_f32_e32 v20, 0, v20
	v_max_f32_e32 v21, 0, v21
	v_max_f32_e32 v22, 0, v22
	v_max_f32_e32 v23, 0, v23
	v_max_f32_e32 v24, 0, v24
	v_max_f32_e32 v25, 0, v25
	v_max_f32_e32 v26, 0, v26
	v_max_f32_e32 v27, 0, v27
	v_max_f32_e32 v28, 0, v28
	v_max_f32_e32 v29, 0, v29
	v_max_f32_e32 v30, 0, v30
	v_max_f32_e32 v31, 0, v31
	v_mul_f32_e32 v0, v0, v0
	v_mul_f32_e32 v1, v1, v1
	v_mul_f32_e32 v2, v2, v2
	v_mul_f32_e32 v3, v3, v3
	v_mul_f32_e32 v4, v4, v4
	v_mul_f32_e32 v5, v5, v5
	v_mul_f32_e32 v6, v6, v6
	v_mul_f32_e32 v7, v7, v7
	v_mul_f32_e32 v8, v8, v8
	v_mul_f32_e32 v9, v9, v9
	v_mul_f32_e32 v10, v10, v10
	v_mul_f32_e32 v11, v11, v11
	v_mul_f32_e32 v12, v12, v12
	v_mul_f32_e32 v13, v13, v13
	v_mul_f32_e32 v14, v14, v14
	v_mul_f32_e32 v15, v15, v15
	v_mul_f32_e32 v16, v16, v16
	v_mul_f32_e32 v17, v17, v17
	v_mul_f32_e32 v18, v18, v18
	v_mul_f32_e32 v19, v19, v19
	v_mul_f32_e32 v20, v20, v20
	v_mul_f32_e32 v21, v21, v21
	v_mul_f32_e32 v22, v22, v22
	v_mul_f32_e32 v23, v23, v23
	v_mul_f32_e32 v24, v24, v24
	v_mul_f32_e32 v25, v25, v25
	v_mul_f32_e32 v26, v26, v26
	v_mul_f32_e32 v27, v27, v27
	v_mul_f32_e32 v28, v28, v28
	v_mul_f32_e32 v29, v29, v29
	v_mul_f32_e32 v30, v30, v30
	v_mul_f32_e32 v31, v31, v31
	v_cvt_pk_bf16_f32 v148, v0, v1
	v_cvt_pk_bf16_f32 v149, v2, v3
	v_cvt_pk_bf16_f32 v150, v4, v5
	v_cvt_pk_bf16_f32 v151, v6, v7
	global_store_dwordx4 v248, v[148:151], s[54:55] offset:0
	v_cvt_pk_bf16_f32 v152, v8, v9
	v_cvt_pk_bf16_f32 v153, v10, v11
	v_cvt_pk_bf16_f32 v154, v12, v13
	v_cvt_pk_bf16_f32 v155, v14, v15
	global_store_dwordx4 v248, v[152:155], s[54:55] offset:16
	v_cvt_pk_bf16_f32 v156, v16, v17
; __device__ void phase_mlp1_big(CParams& p, int l, int tm, int tn, char* smem) {
;     ...
;   const int lane = tid & 63, wid = tid >> 6, wr = wid >> 1, wc = wid & 1;
; #pragma unroll
;   for (int mi = 0; mi < 4; mi++)
; #pragma unroll
;     for (int ni = 0; ni < 8; ni++)
; #pragma unroll
;       for (int j = 0; j < 4; j++) {
;         int rl = wr * 64 + mi * 16 + (lane >> 4) * 4 + j;
;         int cl = wc * 128 + ni * 16 + (lane & 15);
;         float a = fmaxf(acc[mi][ni][j], 0.f);
;         p.hidden[(size_t)(row0 + rl) * DFF + col0 + cl] = f2bf(a * a);
;       }
	v_cvt_pk_bf16_f32 v157, v18, v19
	v_cvt_pk_bf16_f32 v158, v20, v21
	v_cvt_pk_bf16_f32 v159, v22, v23
	global_store_dwordx4 v248, v[156:159], s[54:55] offset:128
	v_cvt_pk_bf16_f32 v160, v24, v25
	v_cvt_pk_bf16_f32 v161, v26, v27
	v_cvt_pk_bf16_f32 v162, v28, v29
	v_cvt_pk_bf16_f32 v163, v30, v31
	global_store_dwordx4 v248, v[160:163], s[54:55] offset:144
	s_add_u32 s54, s54, 0x20000
	s_addc_u32 s55, s55, 0
	v_max_f32_e32 v32, 0, v32
	v_max_f32_e32 v33, 0, v33
	v_max_f32_e32 v34, 0, v34
	v_max_f32_e32 v35, 0, v35
	v_max_f32_e32 v36, 0, v36
	v_max_f32_e32 v37, 0, v37
	v_max_f32_e32 v38, 0, v38
	v_max_f32_e32 v39, 0, v39
	v_max_f32_e32 v40, 0, v40
	v_max_f32_e32 v41, 0, v41
	v_max_f32_e32 v42, 0, v42
	v_max_f32_e32 v43, 0, v43
	v_max_f32_e32 v44, 0, v44
	v_max_f32_e32 v45, 0, v45
	v_max_f32_e32 v46, 0, v46
	v_max_f32_e32 v47, 0, v47
	v_max_f32_e32 v48, 0, v48
	v_max_f32_e32 v49, 0, v49
	v_max_f32_e32 v50, 0, v50
	v_max_f32_e32 v51, 0, v51
	v_max_f32_e32 v52, 0, v52
	v_max_f32_e32 v53, 0, v53
	v_max_f32_e32 v54, 0, v54
	v_max_f32_e32 v55, 0, v55
	v_max_f32_e32 v56, 0, v56
	v_max_f32_e32 v57, 0, v57
	v_max_f32_e32 v58, 0, v58
	v_max_f32_e32 v59, 0, v59
	v_max_f32_e32 v60, 0, v60
	v_max_f32_e32 v61, 0, v61
	v_max_f32_e32 v62, 0, v62
	v_max_f32_e32 v63, 0, v63
	v_mul_f32_e32 v32, v32, v32
	v_mul_f32_e32 v33, v33, v33
	v_mul_f32_e32 v34, v34, v34
	v_mul_f32_e32 v35, v35, v35
	v_mul_f32_e32 v36, v36, v36
	v_mul_f32_e32 v37, v37, v37
	v_mul_f32_e32 v38, v38, v38
	v_mul_f32_e32 v39, v39, v39
	v_mul_f32_e32 v40, v40, v40
	v_mul_f32_e32 v41, v41, v41
	v_mul_f32_e32 v42, v42, v42
	v_mul_f32_e32 v43, v43, v43
	v_mul_f32_e32 v44, v44, v44
	v_mul_f32_e32 v45, v45, v45
	v_mul_f32_e32 v46, v46, v46
	v_mul_f32_e32 v47, v47, v47
	v_mul_f32_e32 v48, v48, v48
	v_mul_f32_e32 v49, v49, v49
	v_mul_f32_e32 v50, v50, v50
	v_mul_f32_e32 v51, v51, v51
	v_mul_f32_e32 v52, v52, v52
	v_mul_f32_e32 v53, v53, v53
	v_mul_f32_e32 v54, v54, v54
	v_mul_f32_e32 v55, v55, v55
	v_mul_f32_e32 v56, v56, v56
	v_mul_f32_e32 v57, v57, v57
	v_mul_f32_e32 v58, v58, v58
	v_mul_f32_e32 v59, v59, v59
	v_mul_f32_e32 v60, v60, v60
	v_mul_f32_e32 v61, v61, v61
	v_mul_f32_e32 v62, v62, v62
	v_mul_f32_e32 v63, v63, v63
	v_cvt_pk_bf16_f32 v168, v32, v33
	v_cvt_pk_bf16_f32 v169, v34, v35
	v_cvt_pk_bf16_f32 v170, v36, v37
	v_cvt_pk_bf16_f32 v171, v38, v39
	global_store_dwordx4 v248, v[168:171], s[54:55] offset:0
	v_cvt_pk_bf16_f32 v172, v40, v41
	v_cvt_pk_bf16_f32 v173, v42, v43
	v_cvt_pk_bf16_f32 v174, v44, v45
	v_cvt_pk_bf16_f32 v175, v46, v47
	global_store_dwordx4 v248, v[172:175], s[54:55] offset:16
	v_cvt_pk_bf16_f32 v176, v48, v49
	v_cvt_pk_bf16_f32 v177, v50, v51
	v_cvt_pk_bf16_f32 v178, v52, v53
	v_cvt_pk_bf16_f32 v179, v54, v55
	global_store_dwordx4 v248, v[176:179], s[54:55] offset:128
	v_cvt_pk_bf16_f32 v180, v56, v57
	v_cvt_pk_bf16_f32 v181, v58, v59
	v_cvt_pk_bf16_f32 v182, v60, v61
	v_cvt_pk_bf16_f32 v183, v62, v63
	global_store_dwordx4 v248, v[180:183], s[54:55] offset:144
	s_add_u32 s54, s54, 0x20000
	s_addc_u32 s55, s55, 0
	v_max_f32_e32 v64, 0, v64
	v_max_f32_e32 v65, 0, v65
	v_max_f32_e32 v66, 0, v66
	v_max_f32_e32 v67, 0, v67
	v_max_f32_e32 v68, 0, v68
	v_max_f32_e32 v69, 0, v69
	v_max_f32_e32 v70, 0, v70
	v_max_f32_e32 v71, 0, v71
	v_max_f32_e32 v72, 0, v72
	v_max_f32_e32 v73, 0, v73
	v_max_f32_e32 v74, 0, v74
	v_max_f32_e32 v75, 0, v75
	v_max_f32_e32 v76, 0, v76
	v_max_f32_e32 v77, 0, v77
	v_max_f32_e32 v78, 0, v78
	v_max_f32_e32 v79, 0, v79
	v_max_f32_e32 v80, 0, v80
	v_max_f32_e32 v81, 0, v81
	v_max_f32_e32 v82, 0, v82
	v_max_f32_e32 v83, 0, v83
	v_max_f32_e32 v84, 0, v84
	v_max_f32_e32 v85, 0, v85
	v_max_f32_e32 v86, 0, v86
	v_max_f32_e32 v87, 0, v87
	v_max_f32_e32 v88, 0, v88
	v_max_f32_e32 v89, 0, v89
	v_max_f32_e32 v90, 0, v90
	v_max_f32_e32 v91, 0, v91
	v_max_f32_e32 v92, 0, v92
	v_max_f32_e32 v93, 0, v93
	v_max_f32_e32 v94, 0, v94
	v_max_f32_e32 v95, 0, v95
	v_mul_f32_e32 v64, v64, v64
	v_mul_f32_e32 v65, v65, v65
	v_mul_f32_e32 v66, v66, v66
	v_mul_f32_e32 v67, v67, v67
	v_mul_f32_e32 v68, v68, v68
	v_mul_f32_e32 v69, v69, v69
	v_mul_f32_e32 v70, v70, v70
	v_mul_f32_e32 v71, v71, v71
	v_mul_f32_e32 v72, v72, v72
	v_mul_f32_e32 v73, v73, v73
	v_mul_f32_e32 v74, v74, v74
	v_mul_f32_e32 v75, v75, v75
	v_mul_f32_e32 v76, v76, v76
	v_mul_f32_e32 v77, v77, v77
; __device__ void phase_mlp1_big(CParams& p, int l, int tm, int tn, char* smem) {
;     ...
;   const int lane = tid & 63, wid = tid >> 6, wr = wid >> 1, wc = wid & 1;
; #pragma unroll
;   for (int mi = 0; mi < 4; mi++)
; #pragma unroll
;     for (int ni = 0; ni < 8; ni++)
; #pragma unroll
;       for (int j = 0; j < 4; j++) {
;         int rl = wr * 64 + mi * 16 + (lane >> 4) * 4 + j;
;         int cl = wc * 128 + ni * 16 + (lane & 15);
;         float a = fmaxf(acc[mi][ni][j], 0.f);
;         p.hidden[(size_t)(row0 + rl) * DFF + col0 + cl] = f2bf(a * a);
;       }
	v_mul_f32_e32 v78, v78, v78
	v_mul_f32_e32 v79, v79, v79
	v_mul_f32_e32 v80, v80, v80
	v_mul_f32_e32 v81, v81, v81
	v_mul_f32_e32 v82, v82, v82
	v_mul_f32_e32 v83, v83, v83
	v_mul_f32_e32 v84, v84, v84
	v_mul_f32_e32 v85, v85, v85
	v_mul_f32_e32 v86, v86, v86
	v_mul_f32_e32 v87, v87, v87
	v_mul_f32_e32 v88, v88, v88
	v_mul_f32_e32 v89, v89, v89
	v_mul_f32_e32 v90, v90, v90
	v_mul_f32_e32 v91, v91, v91
	v_mul_f32_e32 v92, v92, v92
	v_mul_f32_e32 v93, v93, v93
	v_mul_f32_e32 v94, v94, v94
	v_mul_f32_e32 v95, v95, v95
	v_cvt_pk_bf16_f32 v200, v64, v65
	v_cvt_pk_bf16_f32 v201, v66, v67
	v_cvt_pk_bf16_f32 v202, v68, v69
	v_cvt_pk_bf16_f32 v203, v70, v71
	global_store_dwordx4 v248, v[200:203], s[54:55] offset:0
	v_cvt_pk_bf16_f32 v204, v72, v73
	v_cvt_pk_bf16_f32 v205, v74, v75
	v_cvt_pk_bf16_f32 v206, v76, v77
	v_cvt_pk_bf16_f32 v207, v78, v79
	global_store_dwordx4 v248, v[204:207], s[54:55] offset:16
	v_cvt_pk_bf16_f32 v208, v80, v81
	v_cvt_pk_bf16_f32 v209, v82, v83
	v_cvt_pk_bf16_f32 v210, v84, v85
	v_cvt_pk_bf16_f32 v211, v86, v87
	global_store_dwordx4 v248, v[208:211], s[54:55] offset:128
	v_cvt_pk_bf16_f32 v212, v88, v89
	v_cvt_pk_bf16_f32 v213, v90, v91
	v_cvt_pk_bf16_f32 v214, v92, v93
	v_cvt_pk_bf16_f32 v215, v94, v95
	global_store_dwordx4 v248, v[212:215], s[54:55] offset:144
	s_add_u32 s54, s54, 0x20000
	s_addc_u32 s55, s55, 0
	v_max_f32_e32 v96, 0, v96
	v_max_f32_e32 v97, 0, v97
	v_max_f32_e32 v98, 0, v98
	v_max_f32_e32 v99, 0, v99
	v_max_f32_e32 v100, 0, v100
	v_max_f32_e32 v101, 0, v101
	v_max_f32_e32 v102, 0, v102
	v_max_f32_e32 v103, 0, v103
	v_max_f32_e32 v104, 0, v104
	v_max_f32_e32 v105, 0, v105
	v_max_f32_e32 v106, 0, v106
	v_max_f32_e32 v107, 0, v107
	v_max_f32_e32 v108, 0, v108
	v_max_f32_e32 v109, 0, v109
	v_max_f32_e32 v110, 0, v110
	v_max_f32_e32 v111, 0, v111
	v_max_f32_e32 v112, 0, v112
	v_max_f32_e32 v113, 0, v113
	v_max_f32_e32 v114, 0, v114
	v_max_f32_e32 v115, 0, v115
	v_max_f32_e32 v116, 0, v116
	v_max_f32_e32 v117, 0, v117
	v_max_f32_e32 v118, 0, v118
	v_max_f32_e32 v119, 0, v119
	v_max_f32_e32 v120, 0, v120
	v_max_f32_e32 v121, 0, v121
	v_max_f32_e32 v122, 0, v122
	v_max_f32_e32 v123, 0, v123
	v_max_f32_e32 v124, 0, v124
	v_max_f32_e32 v125, 0, v125
	v_max_f32_e32 v126, 0, v126
	v_max_f32_e32 v127, 0, v127
	v_mul_f32_e32 v96, v96, v96
	v_mul_f32_e32 v97, v97, v97
	v_mul_f32_e32 v98, v98, v98
	v_mul_f32_e32 v99, v99, v99
	v_mul_f32_e32 v100, v100, v100
	v_mul_f32_e32 v101, v101, v101
	v_mul_f32_e32 v102, v102, v102
	v_mul_f32_e32 v103, v103, v103
	v_mul_f32_e32 v104, v104, v104
	v_mul_f32_e32 v105, v105, v105
	v_mul_f32_e32 v106, v106, v106
	v_mul_f32_e32 v107, v107, v107
	v_mul_f32_e32 v108, v108, v108
	v_mul_f32_e32 v109, v109, v109
	v_mul_f32_e32 v110, v110, v110
	v_mul_f32_e32 v111, v111, v111
	v_mul_f32_e32 v112, v112, v112
	v_mul_f32_e32 v113, v113, v113
	v_mul_f32_e32 v114, v114, v114
	v_mul_f32_e32 v115, v115, v115
	v_mul_f32_e32 v116, v116, v116
	v_mul_f32_e32 v117, v117, v117
	v_mul_f32_e32 v118, v118, v118
	v_mul_f32_e32 v119, v119, v119
	v_mul_f32_e32 v120, v120, v120
	v_mul_f32_e32 v121, v121, v121
	v_mul_f32_e32 v122, v122, v122
	v_mul_f32_e32 v123, v123, v123
	v_mul_f32_e32 v124, v124, v124
	v_mul_f32_e32 v125, v125, v125
	v_mul_f32_e32 v126, v126, v126
	v_mul_f32_e32 v127, v127, v127
	v_cvt_pk_bf16_f32 v216, v96, v97
	v_cvt_pk_bf16_f32 v217, v98, v99
	v_cvt_pk_bf16_f32 v218, v100, v101
	v_cvt_pk_bf16_f32 v219, v102, v103
	global_store_dwordx4 v248, v[216:219], s[54:55] offset:0
	v_cvt_pk_bf16_f32 v220, v104, v105
	v_cvt_pk_bf16_f32 v221, v106, v107
	v_cvt_pk_bf16_f32 v222, v108, v109
	v_cvt_pk_bf16_f32 v223, v110, v111
	global_store_dwordx4 v248, v[220:223], s[54:55] offset:16
	v_cvt_pk_bf16_f32 v228, v112, v113
	v_cvt_pk_bf16_f32 v229, v114, v115
	v_cvt_pk_bf16_f32 v230, v116, v117
	v_cvt_pk_bf16_f32 v231, v118, v119
	global_store_dwordx4 v248, v[228:231], s[54:55] offset:128
	v_cvt_pk_bf16_f32 v232, v120, v121
	v_cvt_pk_bf16_f32 v233, v122, v123
	v_cvt_pk_bf16_f32 v234, v124, v125
	v_cvt_pk_bf16_f32 v235, v126, v127
	global_store_dwordx4 v248, v[232:235], s[54:55] offset:144
	s_waitcnt vmcnt(0) lgkmcnt(0)
	s_add_u32 s51, s51, 1
	s_cmp_lt_u32 s51, 4
	s_cbranch_scc1 .Lmlp1_tile
	s_barrier
	ds_write_b128 v145, v[236:239] offset:40960
	s_waitcnt lgkmcnt(0)
	s_barrier

; __device__ __forceinline__ int otid() { int t = threadIdx.x; asm volatile("" : "+v"(t)); return t; }
; template <int NI> ...
;     ...
;   G_LOAD(a0, b0, 0);
;   G_LOAD(a1, b1, 32);
;   __syncthreads();
;   G_WRITE(a0, b0, 0);
;   __syncthreads();
;   for (int kt = 0; kt < nk; kt += 2) {
;     G_LOAD(a0, b0, min((kt + 2) * 32, klast));
;     G_COMPUTE(0);
;     G_WRITE(a1, b1, 1);
;     __syncthreads();
;     G_LOAD(a1, b1, min((kt + 3) * 32, klast));
;     G_COMPUTE(1);
;     G_WRITE(a0, b0, 0);
;     __syncthreads();
;   }
; __device__ void phase_proj_res(CParams& p, int l, int tm, int tn, char* smem, const bf16_t* A, int K,
;                                const bf16_t* Bt, int gate_off, float gscale) {
;   const int tid = otid();
;   bf16_t* sA = (bf16_t*)smem;
;   bf16_t* sB = sA + 128 * LDSS;
;   int row0 = tm * 128, col0 = tn * 128;
;   f32x4 acc[4][4];
;   zero_acc<4>(acc);
;   gemm_mainloop<4>(A + (size_t)row0 * K, K, Bt + (size_t)col0 * K, K, K, sA, sB, acc, tid);
.LBB0_1127:
	s_or_b64 exec, exec, s[20:21]
	s_mov_b64 s[20:21], s[34:35]
	s_waitcnt lgkmcnt(0)
	s_barrier
	s_load_dwordx2 s[6:7], s[20:21], 0x128
	s_load_dwordx2 s[22:23], s[20:21], 0x1e0
	s_load_dwordx2 s[24:25], s[20:21], 0x160
	s_load_dwordx2 s[44:45], s[20:21], 0x148
	s_load_dwordx2 s[48:49], s[20:21], 0xf8
	s_waitcnt lgkmcnt(0)
	s_add_u32 s2, s6, s18
	s_addc_u32 s4, s7, s19
	v_readlane_b32 s6, v224, 15
	v_readlane_b32 s7, v224, 16
	s_add_u32 s18, s2, s6
	s_addc_u32 s19, s4, s7
	s_mov_b32 s2, 0
	s_mov_b64 exec, -1
	ds_read_b128 v[236:239], v145 offset:40960
	s_load_dwordx2 s[6:7], s[20:21], 0x1e0
	s_load_dwordx2 s[12:13], s[20:21], 0x128
	s_load_dwordx2 s[22:23], s[20:21], 0xf8
	s_load_dwordx2 s[26:27], s[20:21], 0x160
	v_readlane_b32 s0, v224, 26
	v_readlane_b32 s2, v225, 4
	v_readfirstlane_b32 s4, v147
	v_and_b32_e32 v250, 63, v147
	s_nop 3
	s_lshr_b32 s4, s4, 6
	s_lshl_b32 s8, s4, 11
	s_lshl_b32 s10, s4, 12
	v_lshrrev_b32_e32 v251, 2, v250
	v_and_b32_e32 v252, 3, v250
	v_lshrrev_b32_e32 v253, 4, v250
	v_sub_u32_e32 v253, 0, v253
	v_and_b32_e32 v253, 3, v253
	v_xor_b32_e32 v253, v252, v253
	v_lshlrev_b32_e32 v253, 4, v253
	s_lshl_b32 s40, s4, 5
	v_add_u32_e32 v252, s40, v251
	s_mov_b32 s41, 0x2000
	v_mul_lo_u32 v240, v252, s41
	v_add_u32_e32 v240, v240, v253
	v_add_u32_e32 v241, 0x20000, v240
	s_lshl_b32 s40, s4, 6
	v_add_u32_e32 v252, s40, v251
	s_mov_b32 s41, 0x2000
	v_mul_lo_u32 v242, v252, s41
	v_add_u32_e32 v242, v242, v253
	v_add_u32_e32 v243, 0x20000, v242
	v_add_u32_e32 v244, 0x40000, v242
	v_add_u32_e32 v245, 0x60000, v242
	v_and_b32_e32 v251, 15, v250
	v_lshrrev_b32_e32 v252, 2, v251
	v_sub_u32_e32 v252, 0, v252
	v_and_b32_e32 v252, 3, v252
	v_lshrrev_b32_e32 v253, 4, v250
	v_xor_b32_e32 v252, v253, v252
	v_lshlrev_b32_e32 v252, 4, v252
	s_lshr_b32 s40, s4, 1
	s_and_b32 s41, s4, 1
	s_lshl_b32 s52, s40, 6
	s_lshl_b32 s53, s41, 7
	v_add_u32_e32 v246, s52, v251
	v_lshl_add_u32 v246, v246, 6, v252
	v_add_u32_e32 v247, s53, v251
	v_lshl_add_u32 v247, v247, 6, v252
	v_add_u32_e32 v247, 0x2000, v247
	v_lshl_add_u32 v249, v253, 2, s53
	v_lshlrev_b32_e32 v249, 2, v249
	v_add_u32_e32 v248, s52, v251
	v_lshl_add_u32 v248, v248, 12, v249
	s_waitcnt lgkmcnt(0)
	s_mov_b32 s58, 0
.Lmlp2_tile:
	s_and_b32 s40, s2, 7
	s_lshl_b32 s40, s40, 4
	s_lshr_b32 s41, s2, 5
	s_add_u32 s40, s40, s41
	s_lshl_b32 s32, s40, 7
	s_lshr_b32 s41, s2, 3
	s_and_b32 s41, s41, 3
	s_lshl_b32 s28, s41, 8
	s_mul_i32 s40, s32, 0x2000
	s_add_u32 s16, s6, s40
	s_addc_u32 s17, s7, 0
	s_mul_i32 s40, s0, 0x800000
	s_mul_i32 s41, s28, 0x2000
	s_add_u32 s40, s40, s41
	s_add_u32 s18, s12, s40
	s_addc_u32 s19, s13, 0
	s_barrier
	s_add_u32 m0, s8, 0x0
	s_nop 0
	global_load_lds_dwordx4 v240, s[16:17]
	s_add_u32 m0, s8, 0x400
	s_nop 0
	global_load_lds_dwordx4 v241, s[16:17]
	s_add_u32 m0, s10, 0x2000
	s_nop 0
	global_load_lds_dwordx4 v242, s[18:19]
	s_add_u32 m0, s10, 0x2400
	s_nop 0
	global_load_lds_dwordx4 v243, s[18:19]
	s_add_u32 m0, s10, 0x2800
	s_nop 0
	global_load_lds_dwordx4 v244, s[18:19]
	s_add_u32 m0, s10, 0x2c00
	s_nop 0
	global_load_lds_dwordx4 v245, s[18:19]
	s_add_u32 s16, s16, 64
	s_addc_u32 s17, s17, 0
	s_add_u32 s18, s18, 64
	s_addc_u32 s19, s19, 0
	s_add_u32 m0, s8, 0x6000
	s_nop 0
	global_load_lds_dwordx4 v240, s[16:17]
	s_add_u32 m0, s8, 0x6400
	s_nop 0
	global_load_lds_dwordx4 v241, s[16:17]
	s_add_u32 m0, s10, 0x8000
	s_nop 0
	global_load_lds_dwordx4 v242, s[18:19]
	s_add_u32 m0, s10, 0x8400
	s_nop 0
	global_load_lds_dwordx4 v243, s[18:19]
	s_add_u32 m0, s10, 0x8800
	s_nop 0
	global_load_lds_dwordx4 v244, s[18:19]
	s_add_u32 m0, s10, 0x8c00
	s_nop 0
	global_load_lds_dwordx4 v245, s[18:19]
	s_add_u32 s16, s16, 64
	s_addc_u32 s17, s17, 0
	s_add_u32 s18, s18, 64
	s_addc_u32 s19, s19, 0
	s_add_u32 m0, s8, 0xc000
	s_nop 0
	global_load_lds_dwordx4 v240, s[16:17]
	s_add_u32 m0, s8, 0xc400
	s_nop 0
	global_load_lds_dwordx4 v241, s[16:17]
	s_add_u32 m0, s10, 0xe000
	s_nop 0
	global_load_lds_dwordx4 v242, s[18:19]
	s_add_u32 m0, s10, 0xe400
	s_nop 0
	global_load_lds_dwordx4 v243, s[18:19]
	s_add_u32 m0, s10, 0xe800
	s_nop 0
	global_load_lds_dwordx4 v244, s[18:19]
	s_add_u32 m0, s10, 0xec00
	s_nop 0
	global_load_lds_dwordx4 v245, s[18:19]
	s_add_u32 s16, s16, 64
	s_addc_u32 s17, s17, 0
	s_add_u32 s18, s18, 64
	s_addc_u32 s19, s19, 0
	v_mov_b32_e32 v0, 0
	v_mov_b32_e32 v1, 0
	v_mov_b32_e32 v2, 0
	v_mov_b32_e32 v3, 0
	v_mov_b32_e32 v4, 0
	v_mov_b32_e32 v5, 0
	v_mov_b32_e32 v6, 0
	v_mov_b32_e32 v7, 0
	v_mov_b32_e32 v8, 0
	v_mov_b32_e32 v9, 0
	v_mov_b32_e32 v10, 0
	v_mov_b32_e32 v11, 0
	v_mov_b32_e32 v12, 0
	v_mov_b32_e32 v13, 0
	v_mov_b32_e32 v14, 0
	v_mov_b32_e32 v15, 0
	v_mov_b32_e32 v16, 0
	v_mov_b32_e32 v17, 0
	v_mov_b32_e32 v18, 0
	v_mov_b32_e32 v19, 0
	v_mov_b32_e32 v20, 0
	v_mov_b32_e32 v21, 0
	v_mov_b32_e32 v22, 0
	v_mov_b32_e32 v23, 0
	v_mov_b32_e32 v24, 0
	v_mov_b32_e32 v25, 0
	v_mov_b32_e32 v26, 0
	v_mov_b32_e32 v27, 0
	v_mov_b32_e32 v28, 0
	v_mov_b32_e32 v29, 0
	v_mov_b32_e32 v30, 0
	v_mov_b32_e32 v31, 0
	v_mov_b32_e32 v32, 0
	v_mov_b32_e32 v33, 0
	v_mov_b32_e32 v34, 0
	v_mov_b32_e32 v35, 0
	v_mov_b32_e32 v36, 0
	v_mov_b32_e32 v37, 0
	v_mov_b32_e32 v38, 0
	v_mov_b32_e32 v39, 0
	v_mov_b32_e32 v40, 0
	v_mov_b32_e32 v41, 0
	v_mov_b32_e32 v42, 0
	v_mov_b32_e32 v43, 0
	v_mov_b32_e32 v44, 0
	v_mov_b32_e32 v45, 0
	v_mov_b32_e32 v46, 0
	v_mov_b32_e32 v47, 0
	v_mov_b32_e32 v48, 0
	v_mov_b32_e32 v49, 0
	v_mov_b32_e32 v50, 0
	v_mov_b32_e32 v51, 0
	v_mov_b32_e32 v52, 0
	v_mov_b32_e32 v53, 0
	v_mov_b32_e32 v54, 0
	v_mov_b32_e32 v55, 0
	v_mov_b32_e32 v56, 0
	v_mov_b32_e32 v57, 0
	v_mov_b32_e32 v58, 0
	v_mov_b32_e32 v59, 0
	v_mov_b32_e32 v60, 0
	v_mov_b32_e32 v61, 0
; template <int NI> ...
;     ...
;   G_LOAD(a0, b0, 0);
;   G_LOAD(a1, b1, 32);
;   __syncthreads();
;   G_WRITE(a0, b0, 0);
;   __syncthreads();
;   for (int kt = 0; kt < nk; kt += 2) {
;     G_LOAD(a0, b0, min((kt + 2) * 32, klast));
;     G_COMPUTE(0);
;     G_WRITE(a1, b1, 1);
;     __syncthreads();
;     G_LOAD(a1, b1, min((kt + 3) * 32, klast));
;     G_COMPUTE(1);
;     G_WRITE(a0, b0, 0);
;     __syncthreads();
;   }
	v_mov_b32_e32 v62, 0
	v_mov_b32_e32 v63, 0
	v_mov_b32_e32 v64, 0
	v_mov_b32_e32 v65, 0
	v_mov_b32_e32 v66, 0
	v_mov_b32_e32 v67, 0
	v_mov_b32_e32 v68, 0
	v_mov_b32_e32 v69, 0
	v_mov_b32_e32 v70, 0
	v_mov_b32_e32 v71, 0
	v_mov_b32_e32 v72, 0
	v_mov_b32_e32 v73, 0
	v_mov_b32_e32 v74, 0
	v_mov_b32_e32 v75, 0
	v_mov_b32_e32 v76, 0
	v_mov_b32_e32 v77, 0
	v_mov_b32_e32 v78, 0
	v_mov_b32_e32 v79, 0
	v_mov_b32_e32 v80, 0
	v_mov_b32_e32 v81, 0
	v_mov_b32_e32 v82, 0
	v_mov_b32_e32 v83, 0
	v_mov_b32_e32 v84, 0
	v_mov_b32_e32 v85, 0
	v_mov_b32_e32 v86, 0
	v_mov_b32_e32 v87, 0
	v_mov_b32_e32 v88, 0
	v_mov_b32_e32 v89, 0
	v_mov_b32_e32 v90, 0
	v_mov_b32_e32 v91, 0
	v_mov_b32_e32 v92, 0
	v_mov_b32_e32 v93, 0
	v_mov_b32_e32 v94, 0
	v_mov_b32_e32 v95, 0
	v_mov_b32_e32 v96, 0
	v_mov_b32_e32 v97, 0
	v_mov_b32_e32 v98, 0
	v_mov_b32_e32 v99, 0
	v_mov_b32_e32 v100, 0
	v_mov_b32_e32 v101, 0
	v_mov_b32_e32 v102, 0
	v_mov_b32_e32 v103, 0
	v_mov_b32_e32 v104, 0
	v_mov_b32_e32 v105, 0
	v_mov_b32_e32 v106, 0
	v_mov_b32_e32 v107, 0
	v_mov_b32_e32 v108, 0
	v_mov_b32_e32 v109, 0
	v_mov_b32_e32 v110, 0
	v_mov_b32_e32 v111, 0
	v_mov_b32_e32 v112, 0
	v_mov_b32_e32 v113, 0
	v_mov_b32_e32 v114, 0
	v_mov_b32_e32 v115, 0
	v_mov_b32_e32 v116, 0
	v_mov_b32_e32 v117, 0
	v_mov_b32_e32 v118, 0
	v_mov_b32_e32 v119, 0
	v_mov_b32_e32 v120, 0
	v_mov_b32_e32 v121, 0
	v_mov_b32_e32 v122, 0
	v_mov_b32_e32 v123, 0
	v_mov_b32_e32 v124, 0
	v_mov_b32_e32 v125, 0
	v_mov_b32_e32 v126, 0
	v_mov_b32_e32 v127, 0
	s_waitcnt vmcnt(12)
	s_barrier
	ds_read_b128 v[128:131], v246 offset:0
	ds_read_b128 v[148:151], v247 offset:0
	ds_read_b128 v[152:155], v247 offset:1024
	ds_read_b128 v[132:135], v246 offset:1024
	ds_read_b128 v[156:159], v247 offset:2048
	ds_read_b128 v[160:163], v247 offset:3072
	ds_read_b128 v[136:139], v246 offset:2048
	ds_read_b128 v[168:171], v247 offset:4096
	ds_read_b128 v[172:175], v247 offset:5120
	ds_read_b128 v[140:143], v246 offset:3072
	ds_read_b128 v[176:179], v247 offset:6144
	ds_read_b128 v[180:183], v247 offset:7168
	s_mov_b32 s29, 0
.Lmlp2_kloop:
	s_waitcnt vmcnt(6) lgkmcnt(0)
	s_barrier
	s_add_u32 m0, s8, 0x0
	s_nop 0
	global_load_lds_dwordx4 v240, s[16:17]
	s_add_u32 m0, s8, 0x400
	s_nop 0
	global_load_lds_dwordx4 v241, s[16:17]
	s_add_u32 m0, s10, 0x2000
	s_nop 0
	global_load_lds_dwordx4 v242, s[18:19]
	s_add_u32 m0, s10, 0x2400
	s_nop 0
	global_load_lds_dwordx4 v243, s[18:19]
	s_add_u32 m0, s10, 0x2800
	s_nop 0
	global_load_lds_dwordx4 v244, s[18:19]
	s_add_u32 m0, s10, 0x2c00
	s_nop 0
	global_load_lds_dwordx4 v245, s[18:19]
	s_add_u32 s16, s16, 64
	s_addc_u32 s17, s17, 0
	s_add_u32 s18, s18, 64
	s_addc_u32 s19, s19, 0
	v_mfma_f32_16x16x32_bf16 v[0:3], v[148:151], v[128:131], v[0:3]
	ds_read_b128 v[184:187], v246 offset:24576
	v_mfma_f32_16x16x32_bf16 v[4:7], v[152:155], v[128:131], v[4:7]
	ds_read_b128 v[200:203], v247 offset:24576
	v_mfma_f32_16x16x32_bf16 v[8:11], v[156:159], v[128:131], v[8:11]
	ds_read_b128 v[204:207], v247 offset:25600
	v_mfma_f32_16x16x32_bf16 v[12:15], v[160:163], v[128:131], v[12:15]
	ds_read_b128 v[188:191], v246 offset:25600
	v_mfma_f32_16x16x32_bf16 v[16:19], v[168:171], v[128:131], v[16:19]
	ds_read_b128 v[208:211], v247 offset:26624
	v_mfma_f32_16x16x32_bf16 v[20:23], v[172:175], v[128:131], v[20:23]
	ds_read_b128 v[212:215], v247 offset:27648
	v_mfma_f32_16x16x32_bf16 v[24:27], v[176:179], v[128:131], v[24:27]
	ds_read_b128 v[192:195], v246 offset:26624
	v_mfma_f32_16x16x32_bf16 v[28:31], v[180:183], v[128:131], v[28:31]
	ds_read_b128 v[216:219], v247 offset:28672
	v_mfma_f32_16x16x32_bf16 v[32:35], v[148:151], v[132:135], v[32:35]
	ds_read_b128 v[220:223], v247 offset:29696
	v_mfma_f32_16x16x32_bf16 v[36:39], v[152:155], v[132:135], v[36:39]
	ds_read_b128 v[196:199], v246 offset:27648
	v_mfma_f32_16x16x32_bf16 v[40:43], v[156:159], v[132:135], v[40:43]
	ds_read_b128 v[228:231], v247 offset:30720
	v_mfma_f32_16x16x32_bf16 v[44:47], v[160:163], v[132:135], v[44:47]
	ds_read_b128 v[232:235], v247 offset:31744
	v_mfma_f32_16x16x32_bf16 v[48:51], v[168:171], v[132:135], v[48:51]
	v_mfma_f32_16x16x32_bf16 v[52:55], v[172:175], v[132:135], v[52:55]
	v_mfma_f32_16x16x32_bf16 v[56:59], v[176:179], v[132:135], v[56:59]
	v_mfma_f32_16x16x32_bf16 v[60:63], v[180:183], v[132:135], v[60:63]
	v_mfma_f32_16x16x32_bf16 v[64:67], v[148:151], v[136:139], v[64:67]
	v_mfma_f32_16x16x32_bf16 v[68:71], v[152:155], v[136:139], v[68:71]
	v_mfma_f32_16x16x32_bf16 v[72:75], v[156:159], v[136:139], v[72:75]
	v_mfma_f32_16x16x32_bf16 v[76:79], v[160:163], v[136:139], v[76:79]
	v_mfma_f32_16x16x32_bf16 v[80:83], v[168:171], v[136:139], v[80:83]
	v_mfma_f32_16x16x32_bf16 v[84:87], v[172:175], v[136:139], v[84:87]
	v_mfma_f32_16x16x32_bf16 v[88:91], v[176:179], v[136:139], v[88:91]
	v_mfma_f32_16x16x32_bf16 v[92:95], v[180:183], v[136:139], v[92:95]
	v_mfma_f32_16x16x32_bf16 v[96:99], v[148:151], v[140:143], v[96:99]
	v_mfma_f32_16x16x32_bf16 v[100:103], v[152:155], v[140:143], v[100:103]
	v_mfma_f32_16x16x32_bf16 v[104:107], v[156:159], v[140:143], v[104:107]
	v_mfma_f32_16x16x32_bf16 v[108:111], v[160:163], v[140:143], v[108:111]
	v_mfma_f32_16x16x32_bf16 v[112:115], v[168:171], v[140:143], v[112:115]
	v_mfma_f32_16x16x32_bf16 v[116:119], v[172:175], v[140:143], v[116:119]
	v_mfma_f32_16x16x32_bf16 v[120:123], v[176:179], v[140:143], v[120:123]
	v_mfma_f32_16x16x32_bf16 v[124:127], v[180:183], v[140:143], v[124:127]
	s_waitcnt vmcnt(6) lgkmcnt(0)
	s_barrier
; template <int NI> ...
;     ...
;   G_LOAD(a0, b0, 0);
;   G_LOAD(a1, b1, 32);
;   __syncthreads();
;   G_WRITE(a0, b0, 0);
;   __syncthreads();
;   for (int kt = 0; kt < nk; kt += 2) {
;     G_LOAD(a0, b0, min((kt + 2) * 32, klast));
;     G_COMPUTE(0);
;     G_WRITE(a1, b1, 1);
;     __syncthreads();
;     G_LOAD(a1, b1, min((kt + 3) * 32, klast));
;     G_COMPUTE(1);
;     G_WRITE(a0, b0, 0);
;     __syncthreads();
;   }
	s_add_u32 m0, s8, 0x6000
	s_nop 0
	global_load_lds_dwordx4 v240, s[16:17]
	s_add_u32 m0, s8, 0x6400
	s_nop 0
	global_load_lds_dwordx4 v241, s[16:17]
	s_add_u32 m0, s10, 0x8000
	s_nop 0
	global_load_lds_dwordx4 v242, s[18:19]
	s_add_u32 m0, s10, 0x8400
	s_nop 0
	global_load_lds_dwordx4 v243, s[18:19]
	s_add_u32 m0, s10, 0x8800
	s_nop 0
	global_load_lds_dwordx4 v244, s[18:19]
	s_add_u32 m0, s10, 0x8c00
	s_nop 0
	global_load_lds_dwordx4 v245, s[18:19]
	s_add_u32 s16, s16, 64
	s_addc_u32 s17, s17, 0
	s_add_u32 s18, s18, 64
	s_addc_u32 s19, s19, 0
	v_mfma_f32_16x16x32_bf16 v[0:3], v[200:203], v[184:187], v[0:3]
	ds_read_b128 v[128:131], v246 offset:49152
	v_mfma_f32_16x16x32_bf16 v[4:7], v[204:207], v[184:187], v[4:7]
	ds_read_b128 v[148:151], v247 offset:49152
	v_mfma_f32_16x16x32_bf16 v[8:11], v[208:211], v[184:187], v[8:11]
	ds_read_b128 v[152:155], v247 offset:50176
	v_mfma_f32_16x16x32_bf16 v[12:15], v[212:215], v[184:187], v[12:15]
	ds_read_b128 v[132:135], v246 offset:50176
	v_mfma_f32_16x16x32_bf16 v[16:19], v[216:219], v[184:187], v[16:19]
	ds_read_b128 v[156:159], v247 offset:51200
	v_mfma_f32_16x16x32_bf16 v[20:23], v[220:223], v[184:187], v[20:23]
	ds_read_b128 v[160:163], v247 offset:52224
	v_mfma_f32_16x16x32_bf16 v[24:27], v[228:231], v[184:187], v[24:27]
	ds_read_b128 v[136:139], v246 offset:51200
	v_mfma_f32_16x16x32_bf16 v[28:31], v[232:235], v[184:187], v[28:31]
	ds_read_b128 v[168:171], v247 offset:53248
	v_mfma_f32_16x16x32_bf16 v[32:35], v[200:203], v[188:191], v[32:35]
	ds_read_b128 v[172:175], v247 offset:54272
	v_mfma_f32_16x16x32_bf16 v[36:39], v[204:207], v[188:191], v[36:39]
	ds_read_b128 v[140:143], v246 offset:52224
	v_mfma_f32_16x16x32_bf16 v[40:43], v[208:211], v[188:191], v[40:43]
	ds_read_b128 v[176:179], v247 offset:55296
	v_mfma_f32_16x16x32_bf16 v[44:47], v[212:215], v[188:191], v[44:47]
	ds_read_b128 v[180:183], v247 offset:56320
	v_mfma_f32_16x16x32_bf16 v[48:51], v[216:219], v[188:191], v[48:51]
	v_mfma_f32_16x16x32_bf16 v[52:55], v[220:223], v[188:191], v[52:55]
	v_mfma_f32_16x16x32_bf16 v[56:59], v[228:231], v[188:191], v[56:59]
	v_mfma_f32_16x16x32_bf16 v[60:63], v[232:235], v[188:191], v[60:63]
	v_mfma_f32_16x16x32_bf16 v[64:67], v[200:203], v[192:195], v[64:67]
	v_mfma_f32_16x16x32_bf16 v[68:71], v[204:207], v[192:195], v[68:71]
	v_mfma_f32_16x16x32_bf16 v[72:75], v[208:211], v[192:195], v[72:75]
	v_mfma_f32_16x16x32_bf16 v[76:79], v[212:215], v[192:195], v[76:79]
	v_mfma_f32_16x16x32_bf16 v[80:83], v[216:219], v[192:195], v[80:83]
	v_mfma_f32_16x16x32_bf16 v[84:87], v[220:223], v[192:195], v[84:87]
	v_mfma_f32_16x16x32_bf16 v[88:91], v[228:231], v[192:195], v[88:91]
	v_mfma_f32_16x16x32_bf16 v[92:95], v[232:235], v[192:195], v[92:95]
	v_mfma_f32_16x16x32_bf16 v[96:99], v[200:203], v[196:199], v[96:99]
	v_mfma_f32_16x16x32_bf16 v[100:103], v[204:207], v[196:199], v[100:103]
	v_mfma_f32_16x16x32_bf16 v[104:107], v[208:211], v[196:199], v[104:107]
	v_mfma_f32_16x16x32_bf16 v[108:111], v[212:215], v[196:199], v[108:111]
	v_mfma_f32_16x16x32_bf16 v[112:115], v[216:219], v[196:199], v[112:115]
	v_mfma_f32_16x16x32_bf16 v[116:119], v[220:223], v[196:199], v[116:119]
	v_mfma_f32_16x16x32_bf16 v[120:123], v[228:231], v[196:199], v[120:123]
	v_mfma_f32_16x16x32_bf16 v[124:127], v[232:235], v[196:199], v[124:127]
	s_waitcnt vmcnt(6) lgkmcnt(0)
	s_barrier
	s_add_u32 m0, s8, 0xc000
	s_nop 0
	global_load_lds_dwordx4 v240, s[16:17]
	s_add_u32 m0, s8, 0xc400
	s_nop 0
	global_load_lds_dwordx4 v241, s[16:17]
	s_add_u32 m0, s10, 0xe000
	s_nop 0
	global_load_lds_dwordx4 v242, s[18:19]
	s_add_u32 m0, s10, 0xe400
	s_nop 0
	global_load_lds_dwordx4 v243, s[18:19]
	s_add_u32 m0, s10, 0xe800
	s_nop 0
	global_load_lds_dwordx4 v244, s[18:19]
	s_add_u32 m0, s10, 0xec00
	s_nop 0
	global_load_lds_dwordx4 v245, s[18:19]
	s_add_u32 s16, s16, 64
	s_addc_u32 s17, s17, 0
	s_add_u32 s18, s18, 64
	s_addc_u32 s19, s19, 0
	v_mfma_f32_16x16x32_bf16 v[0:3], v[148:151], v[128:131], v[0:3]
	ds_read_b128 v[184:187], v246 offset:0
	v_mfma_f32_16x16x32_bf16 v[4:7], v[152:155], v[128:131], v[4:7]
	ds_read_b128 v[200:203], v247 offset:0
	v_mfma_f32_16x16x32_bf16 v[8:11], v[156:159], v[128:131], v[8:11]
	ds_read_b128 v[204:207], v247 offset:1024
	v_mfma_f32_16x16x32_bf16 v[12:15], v[160:163], v[128:131], v[12:15]
	ds_read_b128 v[188:191], v246 offset:1024
	v_mfma_f32_16x16x32_bf16 v[16:19], v[168:171], v[128:131], v[16:19]
	ds_read_b128 v[208:211], v247 offset:2048
	v_mfma_f32_16x16x32_bf16 v[20:23], v[172:175], v[128:131], v[20:23]
	ds_read_b128 v[212:215], v247 offset:3072
	v_mfma_f32_16x16x32_bf16 v[24:27], v[176:179], v[128:131], v[24:27]
	ds_read_b128 v[192:195], v246 offset:2048
	v_mfma_f32_16x16x32_bf16 v[28:31], v[180:183], v[128:131], v[28:31]
	ds_read_b128 v[216:219], v247 offset:4096
	v_mfma_f32_16x16x32_bf16 v[32:35], v[148:151], v[132:135], v[32:35]
	ds_read_b128 v[220:223], v247 offset:5120
	v_mfma_f32_16x16x32_bf16 v[36:39], v[152:155], v[132:135], v[36:39]
	ds_read_b128 v[196:199], v246 offset:3072
	v_mfma_f32_16x16x32_bf16 v[40:43], v[156:159], v[132:135], v[40:43]
	ds_read_b128 v[228:231], v247 offset:6144
	v_mfma_f32_16x16x32_bf16 v[44:47], v[160:163], v[132:135], v[44:47]
	ds_read_b128 v[232:235], v247 offset:7168
	v_mfma_f32_16x16x32_bf16 v[48:51], v[168:171], v[132:135], v[48:51]
	v_mfma_f32_16x16x32_bf16 v[52:55], v[172:175], v[132:135], v[52:55]
	v_mfma_f32_16x16x32_bf16 v[56:59], v[176:179], v[132:135], v[56:59]
	v_mfma_f32_16x16x32_bf16 v[60:63], v[180:183], v[132:135], v[60:63]
	v_mfma_f32_16x16x32_bf16 v[64:67], v[148:151], v[136:139], v[64:67]
	v_mfma_f32_16x16x32_bf16 v[68:71], v[152:155], v[136:139], v[68:71]
	v_mfma_f32_16x16x32_bf16 v[72:75], v[156:159], v[136:139], v[72:75]
	v_mfma_f32_16x16x32_bf16 v[76:79], v[160:163], v[136:139], v[76:79]
	v_mfma_f32_16x16x32_bf16 v[80:83], v[168:171], v[136:139], v[80:83]
	v_mfma_f32_16x16x32_bf16 v[84:87], v[172:175], v[136:139], v[84:87]
	v_mfma_f32_16x16x32_bf16 v[88:91], v[176:179], v[136:139], v[88:91]
	v_mfma_f32_16x16x32_bf16 v[92:95], v[180:183], v[136:139], v[92:95]
	v_mfma_f32_16x16x32_bf16 v[96:99], v[148:151], v[140:143], v[96:99]
	v_mfma_f32_16x16x32_bf16 v[100:103], v[152:155], v[140:143], v[100:103]
	v_mfma_f32_16x16x32_bf16 v[104:107], v[156:159], v[140:143], v[104:107]
	v_mfma_f32_16x16x32_bf16 v[108:111], v[160:163], v[140:143], v[108:111]
	v_mfma_f32_16x16x32_bf16 v[112:115], v[168:171], v[140:143], v[112:115]
	v_mfma_f32_16x16x32_bf16 v[116:119], v[172:175], v[140:143], v[116:119]
	v_mfma_f32_16x16x32_bf16 v[120:123], v[176:179], v[140:143], v[120:123]
	v_mfma_f32_16x16x32_bf16 v[124:127], v[180:183], v[140:143], v[124:127]
	s_waitcnt vmcnt(6) lgkmcnt(0)
	s_barrier
; template <int NI> ...
;     ...
;   G_LOAD(a0, b0, 0);
;   G_LOAD(a1, b1, 32);
;   __syncthreads();
;   G_WRITE(a0, b0, 0);
;   __syncthreads();
;   for (int kt = 0; kt < nk; kt += 2) {
;     G_LOAD(a0, b0, min((kt + 2) * 32, klast));
;     G_COMPUTE(0);
;     G_WRITE(a1, b1, 1);
;     __syncthreads();
;     G_LOAD(a1, b1, min((kt + 3) * 32, klast));
;     G_COMPUTE(1);
;     G_WRITE(a0, b0, 0);
;     __syncthreads();
;   }
	s_add_u32 m0, s8, 0x0
	s_nop 0
	global_load_lds_dwordx4 v240, s[16:17]
	s_add_u32 m0, s8, 0x400
	s_nop 0
	global_load_lds_dwordx4 v241, s[16:17]
	s_add_u32 m0, s10, 0x2000
	s_nop 0
	global_load_lds_dwordx4 v242, s[18:19]
	s_add_u32 m0, s10, 0x2400
	s_nop 0
	global_load_lds_dwordx4 v243, s[18:19]
	s_add_u32 m0, s10, 0x2800
	s_nop 0
	global_load_lds_dwordx4 v244, s[18:19]
	s_add_u32 m0, s10, 0x2c00
	s_nop 0
	global_load_lds_dwordx4 v245, s[18:19]
	s_add_u32 s16, s16, 64
	s_addc_u32 s17, s17, 0
	s_add_u32 s18, s18, 64
	s_addc_u32 s19, s19, 0
	v_mfma_f32_16x16x32_bf16 v[0:3], v[200:203], v[184:187], v[0:3]
	ds_read_b128 v[128:131], v246 offset:24576
	v_mfma_f32_16x16x32_bf16 v[4:7], v[204:207], v[184:187], v[4:7]
	ds_read_b128 v[148:151], v247 offset:24576
	v_mfma_f32_16x16x32_bf16 v[8:11], v[208:211], v[184:187], v[8:11]
	ds_read_b128 v[152:155], v247 offset:25600
	v_mfma_f32_16x16x32_bf16 v[12:15], v[212:215], v[184:187], v[12:15]
	ds_read_b128 v[132:135], v246 offset:25600
	v_mfma_f32_16x16x32_bf16 v[16:19], v[216:219], v[184:187], v[16:19]
	ds_read_b128 v[156:159], v247 offset:26624
	v_mfma_f32_16x16x32_bf16 v[20:23], v[220:223], v[184:187], v[20:23]
	ds_read_b128 v[160:163], v247 offset:27648
	v_mfma_f32_16x16x32_bf16 v[24:27], v[228:231], v[184:187], v[24:27]
	ds_read_b128 v[136:139], v246 offset:26624
	v_mfma_f32_16x16x32_bf16 v[28:31], v[232:235], v[184:187], v[28:31]
	ds_read_b128 v[168:171], v247 offset:28672
	v_mfma_f32_16x16x32_bf16 v[32:35], v[200:203], v[188:191], v[32:35]
	ds_read_b128 v[172:175], v247 offset:29696
	v_mfma_f32_16x16x32_bf16 v[36:39], v[204:207], v[188:191], v[36:39]
	ds_read_b128 v[140:143], v246 offset:27648
	v_mfma_f32_16x16x32_bf16 v[40:43], v[208:211], v[188:191], v[40:43]
	ds_read_b128 v[176:179], v247 offset:30720
	v_mfma_f32_16x16x32_bf16 v[44:47], v[212:215], v[188:191], v[44:47]
	ds_read_b128 v[180:183], v247 offset:31744
	v_mfma_f32_16x16x32_bf16 v[48:51], v[216:219], v[188:191], v[48:51]
	v_mfma_f32_16x16x32_bf16 v[52:55], v[220:223], v[188:191], v[52:55]
	v_mfma_f32_16x16x32_bf16 v[56:59], v[228:231], v[188:191], v[56:59]
	v_mfma_f32_16x16x32_bf16 v[60:63], v[232:235], v[188:191], v[60:63]
	v_mfma_f32_16x16x32_bf16 v[64:67], v[200:203], v[192:195], v[64:67]
	v_mfma_f32_16x16x32_bf16 v[68:71], v[204:207], v[192:195], v[68:71]
	v_mfma_f32_16x16x32_bf16 v[72:75], v[208:211], v[192:195], v[72:75]
	v_mfma_f32_16x16x32_bf16 v[76:79], v[212:215], v[192:195], v[76:79]
	v_mfma_f32_16x16x32_bf16 v[80:83], v[216:219], v[192:195], v[80:83]
	v_mfma_f32_16x16x32_bf16 v[84:87], v[220:223], v[192:195], v[84:87]
	v_mfma_f32_16x16x32_bf16 v[88:91], v[228:231], v[192:195], v[88:91]
	v_mfma_f32_16x16x32_bf16 v[92:95], v[232:235], v[192:195], v[92:95]
	v_mfma_f32_16x16x32_bf16 v[96:99], v[200:203], v[196:199], v[96:99]
	v_mfma_f32_16x16x32_bf16 v[100:103], v[204:207], v[196:199], v[100:103]
	v_mfma_f32_16x16x32_bf16 v[104:107], v[208:211], v[196:199], v[104:107]
	v_mfma_f32_16x16x32_bf16 v[108:111], v[212:215], v[196:199], v[108:111]
	v_mfma_f32_16x16x32_bf16 v[112:115], v[216:219], v[196:199], v[112:115]
	v_mfma_f32_16x16x32_bf16 v[116:119], v[220:223], v[196:199], v[116:119]
	v_mfma_f32_16x16x32_bf16 v[120:123], v[228:231], v[196:199], v[120:123]
	v_mfma_f32_16x16x32_bf16 v[124:127], v[232:235], v[196:199], v[124:127]
	s_waitcnt vmcnt(6) lgkmcnt(0)
	s_barrier
	s_add_u32 m0, s8, 0x6000
	s_nop 0
	global_load_lds_dwordx4 v240, s[16:17]
	s_add_u32 m0, s8, 0x6400
	s_nop 0
	global_load_lds_dwordx4 v241, s[16:17]
	s_add_u32 m0, s10, 0x8000
	s_nop 0
	global_load_lds_dwordx4 v242, s[18:19]
	s_add_u32 m0, s10, 0x8400
	s_nop 0
	global_load_lds_dwordx4 v243, s[18:19]
	s_add_u32 m0, s10, 0x8800
	s_nop 0
	global_load_lds_dwordx4 v244, s[18:19]
	s_add_u32 m0, s10, 0x8c00
	s_nop 0
	global_load_lds_dwordx4 v245, s[18:19]
	s_add_u32 s16, s16, 64
	s_addc_u32 s17, s17, 0
	s_add_u32 s18, s18, 64
	s_addc_u32 s19, s19, 0
	v_mfma_f32_16x16x32_bf16 v[0:3], v[148:151], v[128:131], v[0:3]
	ds_read_b128 v[184:187], v246 offset:49152
	v_mfma_f32_16x16x32_bf16 v[4:7], v[152:155], v[128:131], v[4:7]
	ds_read_b128 v[200:203], v247 offset:49152
	v_mfma_f32_16x16x32_bf16 v[8:11], v[156:159], v[128:131], v[8:11]
	ds_read_b128 v[204:207], v247 offset:50176
	v_mfma_f32_16x16x32_bf16 v[12:15], v[160:163], v[128:131], v[12:15]
	ds_read_b128 v[188:191], v246 offset:50176
	v_mfma_f32_16x16x32_bf16 v[16:19], v[168:171], v[128:131], v[16:19]
	ds_read_b128 v[208:211], v247 offset:51200
	v_mfma_f32_16x16x32_bf16 v[20:23], v[172:175], v[128:131], v[20:23]
	ds_read_b128 v[212:215], v247 offset:52224
	v_mfma_f32_16x16x32_bf16 v[24:27], v[176:179], v[128:131], v[24:27]
	ds_read_b128 v[192:195], v246 offset:51200
	v_mfma_f32_16x16x32_bf16 v[28:31], v[180:183], v[128:131], v[28:31]
	ds_read_b128 v[216:219], v247 offset:53248
	v_mfma_f32_16x16x32_bf16 v[32:35], v[148:151], v[132:135], v[32:35]
	ds_read_b128 v[220:223], v247 offset:54272
	v_mfma_f32_16x16x32_bf16 v[36:39], v[152:155], v[132:135], v[36:39]
	ds_read_b128 v[196:199], v246 offset:52224
	v_mfma_f32_16x16x32_bf16 v[40:43], v[156:159], v[132:135], v[40:43]
	ds_read_b128 v[228:231], v247 offset:55296
	v_mfma_f32_16x16x32_bf16 v[44:47], v[160:163], v[132:135], v[44:47]
	ds_read_b128 v[232:235], v247 offset:56320
	v_mfma_f32_16x16x32_bf16 v[48:51], v[168:171], v[132:135], v[48:51]
	v_mfma_f32_16x16x32_bf16 v[52:55], v[172:175], v[132:135], v[52:55]
	v_mfma_f32_16x16x32_bf16 v[56:59], v[176:179], v[132:135], v[56:59]
	v_mfma_f32_16x16x32_bf16 v[60:63], v[180:183], v[132:135], v[60:63]
	v_mfma_f32_16x16x32_bf16 v[64:67], v[148:151], v[136:139], v[64:67]
	v_mfma_f32_16x16x32_bf16 v[68:71], v[152:155], v[136:139], v[68:71]
	v_mfma_f32_16x16x32_bf16 v[72:75], v[156:159], v[136:139], v[72:75]
	v_mfma_f32_16x16x32_bf16 v[76:79], v[160:163], v[136:139], v[76:79]
	v_mfma_f32_16x16x32_bf16 v[80:83], v[168:171], v[136:139], v[80:83]
	v_mfma_f32_16x16x32_bf16 v[84:87], v[172:175], v[136:139], v[84:87]
	v_mfma_f32_16x16x32_bf16 v[88:91], v[176:179], v[136:139], v[88:91]
	v_mfma_f32_16x16x32_bf16 v[92:95], v[180:183], v[136:139], v[92:95]
	v_mfma_f32_16x16x32_bf16 v[96:99], v[148:151], v[140:143], v[96:99]
	v_mfma_f32_16x16x32_bf16 v[100:103], v[152:155], v[140:143], v[100:103]
	v_mfma_f32_16x16x32_bf16 v[104:107], v[156:159], v[140:143], v[104:107]
	v_mfma_f32_16x16x32_bf16 v[108:111], v[160:163], v[140:143], v[108:111]
	v_mfma_f32_16x16x32_bf16 v[112:115], v[168:171], v[140:143], v[112:115]
	v_mfma_f32_16x16x32_bf16 v[116:119], v[172:175], v[140:143], v[116:119]
	v_mfma_f32_16x16x32_bf16 v[120:123], v[176:179], v[140:143], v[120:123]
	v_mfma_f32_16x16x32_bf16 v[124:127], v[180:183], v[140:143], v[124:127]
	s_waitcnt vmcnt(6) lgkmcnt(0)
	s_barrier
; template <int NI> ...
;     ...
;   G_LOAD(a0, b0, 0);
;   G_LOAD(a1, b1, 32);
;   __syncthreads();
;   G_WRITE(a0, b0, 0);
;   __syncthreads();
;   for (int kt = 0; kt < nk; kt += 2) {
;     G_LOAD(a0, b0, min((kt + 2) * 32, klast));
;     G_COMPUTE(0);
;     G_WRITE(a1, b1, 1);
;     __syncthreads();
;     G_LOAD(a1, b1, min((kt + 3) * 32, klast));
;     G_COMPUTE(1);
;     G_WRITE(a0, b0, 0);
;     __syncthreads();
;   }
	s_add_u32 m0, s8, 0xc000
	s_nop 0
	global_load_lds_dwordx4 v240, s[16:17]
	s_add_u32 m0, s8, 0xc400
	s_nop 0
	global_load_lds_dwordx4 v241, s[16:17]
	s_add_u32 m0, s10, 0xe000
	s_nop 0
	global_load_lds_dwordx4 v242, s[18:19]
	s_add_u32 m0, s10, 0xe400
	s_nop 0
	global_load_lds_dwordx4 v243, s[18:19]
	s_add_u32 m0, s10, 0xe800
	s_nop 0
	global_load_lds_dwordx4 v244, s[18:19]
	s_add_u32 m0, s10, 0xec00
	s_nop 0
	global_load_lds_dwordx4 v245, s[18:19]
	s_add_u32 s16, s16, 64
	s_addc_u32 s17, s17, 0
	s_add_u32 s18, s18, 64
	s_addc_u32 s19, s19, 0
	v_mfma_f32_16x16x32_bf16 v[0:3], v[200:203], v[184:187], v[0:3]
	ds_read_b128 v[128:131], v246 offset:0
	v_mfma_f32_16x16x32_bf16 v[4:7], v[204:207], v[184:187], v[4:7]
	ds_read_b128 v[148:151], v247 offset:0
	v_mfma_f32_16x16x32_bf16 v[8:11], v[208:211], v[184:187], v[8:11]
	ds_read_b128 v[152:155], v247 offset:1024
	v_mfma_f32_16x16x32_bf16 v[12:15], v[212:215], v[184:187], v[12:15]
	ds_read_b128 v[132:135], v246 offset:1024
	v_mfma_f32_16x16x32_bf16 v[16:19], v[216:219], v[184:187], v[16:19]
	ds_read_b128 v[156:159], v247 offset:2048
	v_mfma_f32_16x16x32_bf16 v[20:23], v[220:223], v[184:187], v[20:23]
	ds_read_b128 v[160:163], v247 offset:3072
	v_mfma_f32_16x16x32_bf16 v[24:27], v[228:231], v[184:187], v[24:27]
	ds_read_b128 v[136:139], v246 offset:2048
	v_mfma_f32_16x16x32_bf16 v[28:31], v[232:235], v[184:187], v[28:31]
	ds_read_b128 v[168:171], v247 offset:4096
	v_mfma_f32_16x16x32_bf16 v[32:35], v[200:203], v[188:191], v[32:35]
	ds_read_b128 v[172:175], v247 offset:5120
	v_mfma_f32_16x16x32_bf16 v[36:39], v[204:207], v[188:191], v[36:39]
	ds_read_b128 v[140:143], v246 offset:3072
	v_mfma_f32_16x16x32_bf16 v[40:43], v[208:211], v[188:191], v[40:43]
	ds_read_b128 v[176:179], v247 offset:6144
	v_mfma_f32_16x16x32_bf16 v[44:47], v[212:215], v[188:191], v[44:47]
	ds_read_b128 v[180:183], v247 offset:7168
	v_mfma_f32_16x16x32_bf16 v[48:51], v[216:219], v[188:191], v[48:51]
	v_mfma_f32_16x16x32_bf16 v[52:55], v[220:223], v[188:191], v[52:55]
	v_mfma_f32_16x16x32_bf16 v[56:59], v[228:231], v[188:191], v[56:59]
	v_mfma_f32_16x16x32_bf16 v[60:63], v[232:235], v[188:191], v[60:63]
	v_mfma_f32_16x16x32_bf16 v[64:67], v[200:203], v[192:195], v[64:67]
	v_mfma_f32_16x16x32_bf16 v[68:71], v[204:207], v[192:195], v[68:71]
	v_mfma_f32_16x16x32_bf16 v[72:75], v[208:211], v[192:195], v[72:75]
	v_mfma_f32_16x16x32_bf16 v[76:79], v[212:215], v[192:195], v[76:79]
	v_mfma_f32_16x16x32_bf16 v[80:83], v[216:219], v[192:195], v[80:83]
	v_mfma_f32_16x16x32_bf16 v[84:87], v[220:223], v[192:195], v[84:87]
	v_mfma_f32_16x16x32_bf16 v[88:91], v[228:231], v[192:195], v[88:91]
	v_mfma_f32_16x16x32_bf16 v[92:95], v[232:235], v[192:195], v[92:95]
	v_mfma_f32_16x16x32_bf16 v[96:99], v[200:203], v[196:199], v[96:99]
	v_mfma_f32_16x16x32_bf16 v[100:103], v[204:207], v[196:199], v[100:103]
	v_mfma_f32_16x16x32_bf16 v[104:107], v[208:211], v[196:199], v[104:107]
	v_mfma_f32_16x16x32_bf16 v[108:111], v[212:215], v[196:199], v[108:111]
	v_mfma_f32_16x16x32_bf16 v[112:115], v[216:219], v[196:199], v[112:115]
	v_mfma_f32_16x16x32_bf16 v[116:119], v[220:223], v[196:199], v[116:119]
	v_mfma_f32_16x16x32_bf16 v[120:123], v[228:231], v[196:199], v[120:123]
	v_mfma_f32_16x16x32_bf16 v[124:127], v[232:235], v[196:199], v[124:127]
	s_add_u32 s29, s29, 1
	s_cmp_lt_u32 s29, 21
	s_cbranch_scc1 .Lmlp2_kloop
	s_waitcnt vmcnt(6) lgkmcnt(0)
	s_barrier
	s_add_u32 m0, s8, 0x0
	s_nop 0
	global_load_lds_dwordx4 v240, s[16:17]
	s_add_u32 m0, s8, 0x400
	s_nop 0
	global_load_lds_dwordx4 v241, s[16:17]
	s_add_u32 m0, s10, 0x2000
	s_nop 0
	global_load_lds_dwordx4 v242, s[18:19]
	s_add_u32 m0, s10, 0x2400
	s_nop 0
	global_load_lds_dwordx4 v243, s[18:19]
	s_add_u32 m0, s10, 0x2800
	s_nop 0
	global_load_lds_dwordx4 v244, s[18:19]
	s_add_u32 m0, s10, 0x2c00
	s_nop 0
	global_load_lds_dwordx4 v245, s[18:19]
	s_add_u32 s16, s16, 64
	s_addc_u32 s17, s17, 0
	s_add_u32 s18, s18, 64
	s_addc_u32 s19, s19, 0
	v_mfma_f32_16x16x32_bf16 v[0:3], v[148:151], v[128:131], v[0:3]
	ds_read_b128 v[184:187], v246 offset:24576
	v_mfma_f32_16x16x32_bf16 v[4:7], v[152:155], v[128:131], v[4:7]
	ds_read_b128 v[200:203], v247 offset:24576
	v_mfma_f32_16x16x32_bf16 v[8:11], v[156:159], v[128:131], v[8:11]
	ds_read_b128 v[204:207], v247 offset:25600
	v_mfma_f32_16x16x32_bf16 v[12:15], v[160:163], v[128:131], v[12:15]
	ds_read_b128 v[188:191], v246 offset:25600
	v_mfma_f32_16x16x32_bf16 v[16:19], v[168:171], v[128:131], v[16:19]
	ds_read_b128 v[208:211], v247 offset:26624
	v_mfma_f32_16x16x32_bf16 v[20:23], v[172:175], v[128:131], v[20:23]
	ds_read_b128 v[212:215], v247 offset:27648
	v_mfma_f32_16x16x32_bf16 v[24:27], v[176:179], v[128:131], v[24:27]
	ds_read_b128 v[192:195], v246 offset:26624
	v_mfma_f32_16x16x32_bf16 v[28:31], v[180:183], v[128:131], v[28:31]
	ds_read_b128 v[216:219], v247 offset:28672
	v_mfma_f32_16x16x32_bf16 v[32:35], v[148:151], v[132:135], v[32:35]
	ds_read_b128 v[220:223], v247 offset:29696
	v_mfma_f32_16x16x32_bf16 v[36:39], v[152:155], v[132:135], v[36:39]
	ds_read_b128 v[196:199], v246 offset:27648
	v_mfma_f32_16x16x32_bf16 v[40:43], v[156:159], v[132:135], v[40:43]
	ds_read_b128 v[228:231], v247 offset:30720
	v_mfma_f32_16x16x32_bf16 v[44:47], v[160:163], v[132:135], v[44:47]
	ds_read_b128 v[232:235], v247 offset:31744
	v_mfma_f32_16x16x32_bf16 v[48:51], v[168:171], v[132:135], v[48:51]
	v_mfma_f32_16x16x32_bf16 v[52:55], v[172:175], v[132:135], v[52:55]
	v_mfma_f32_16x16x32_bf16 v[56:59], v[176:179], v[132:135], v[56:59]
	v_mfma_f32_16x16x32_bf16 v[60:63], v[180:183], v[132:135], v[60:63]
	v_mfma_f32_16x16x32_bf16 v[64:67], v[148:151], v[136:139], v[64:67]
	v_mfma_f32_16x16x32_bf16 v[68:71], v[152:155], v[136:139], v[68:71]
	v_mfma_f32_16x16x32_bf16 v[72:75], v[156:159], v[136:139], v[72:75]
	v_mfma_f32_16x16x32_bf16 v[76:79], v[160:163], v[136:139], v[76:79]
	v_mfma_f32_16x16x32_bf16 v[80:83], v[168:171], v[136:139], v[80:83]
	v_mfma_f32_16x16x32_bf16 v[84:87], v[172:175], v[136:139], v[84:87]
	v_mfma_f32_16x16x32_bf16 v[88:91], v[176:179], v[136:139], v[88:91]
	v_mfma_f32_16x16x32_bf16 v[92:95], v[180:183], v[136:139], v[92:95]
	v_mfma_f32_16x16x32_bf16 v[96:99], v[148:151], v[140:143], v[96:99]
	v_mfma_f32_16x16x32_bf16 v[100:103], v[152:155], v[140:143], v[100:103]
	v_mfma_f32_16x16x32_bf16 v[104:107], v[156:159], v[140:143], v[104:107]
	v_mfma_f32_16x16x32_bf16 v[108:111], v[160:163], v[140:143], v[108:111]
	v_mfma_f32_16x16x32_bf16 v[112:115], v[168:171], v[140:143], v[112:115]
	v_mfma_f32_16x16x32_bf16 v[116:119], v[172:175], v[140:143], v[116:119]
	v_mfma_f32_16x16x32_bf16 v[120:123], v[176:179], v[140:143], v[120:123]
	v_mfma_f32_16x16x32_bf16 v[124:127], v[180:183], v[140:143], v[124:127]
	s_waitcnt vmcnt(6) lgkmcnt(0)
	s_barrier
; __device__ void phase_proj_res(CParams& p, int l, int tm, int tn, char* smem, const bf16_t* A, int K,
;                                const bf16_t* Bt, int gate_off, float gscale) {
;     ...
;   const float* md = p.mod + ((size_t)l * 3 + modvec_of_tok(row0)) * 6144 + gate_off;
;   EPI_LOOP({
;     float* xp = xrow(p, row0 + rl) + col0 + cl;
;     *xp = *xp + gscale * md[col0 + cl] * acc[mi][ni][j];
	s_add_u32 m0, s8, 0x6000
	s_nop 0
	global_load_lds_dwordx4 v240, s[16:17]
	s_add_u32 m0, s8, 0x6400
	s_nop 0
	global_load_lds_dwordx4 v241, s[16:17]
	s_add_u32 m0, s10, 0x8000
	s_nop 0
	global_load_lds_dwordx4 v242, s[18:19]
	s_add_u32 m0, s10, 0x8400
	s_nop 0
	global_load_lds_dwordx4 v243, s[18:19]
	s_add_u32 m0, s10, 0x8800
	s_nop 0
	global_load_lds_dwordx4 v244, s[18:19]
	s_add_u32 m0, s10, 0x8c00
	s_nop 0
	global_load_lds_dwordx4 v245, s[18:19]
	s_add_u32 s16, s16, 64
	s_addc_u32 s17, s17, 0
	s_add_u32 s18, s18, 64
	s_addc_u32 s19, s19, 0
	v_mfma_f32_16x16x32_bf16 v[0:3], v[200:203], v[184:187], v[0:3]
	ds_read_b128 v[128:131], v246 offset:49152
	v_mfma_f32_16x16x32_bf16 v[4:7], v[204:207], v[184:187], v[4:7]
	ds_read_b128 v[148:151], v247 offset:49152
	v_mfma_f32_16x16x32_bf16 v[8:11], v[208:211], v[184:187], v[8:11]
	ds_read_b128 v[152:155], v247 offset:50176
	v_mfma_f32_16x16x32_bf16 v[12:15], v[212:215], v[184:187], v[12:15]
	ds_read_b128 v[132:135], v246 offset:50176
	v_mfma_f32_16x16x32_bf16 v[16:19], v[216:219], v[184:187], v[16:19]
	ds_read_b128 v[156:159], v247 offset:51200
	v_mfma_f32_16x16x32_bf16 v[20:23], v[220:223], v[184:187], v[20:23]
	ds_read_b128 v[160:163], v247 offset:52224
	v_mfma_f32_16x16x32_bf16 v[24:27], v[228:231], v[184:187], v[24:27]
	ds_read_b128 v[136:139], v246 offset:51200
	v_mfma_f32_16x16x32_bf16 v[28:31], v[232:235], v[184:187], v[28:31]
	ds_read_b128 v[168:171], v247 offset:53248
	v_mfma_f32_16x16x32_bf16 v[32:35], v[200:203], v[188:191], v[32:35]
	ds_read_b128 v[172:175], v247 offset:54272
	v_mfma_f32_16x16x32_bf16 v[36:39], v[204:207], v[188:191], v[36:39]
	ds_read_b128 v[140:143], v246 offset:52224
	v_mfma_f32_16x16x32_bf16 v[40:43], v[208:211], v[188:191], v[40:43]
	ds_read_b128 v[176:179], v247 offset:55296
	v_mfma_f32_16x16x32_bf16 v[44:47], v[212:215], v[188:191], v[44:47]
	ds_read_b128 v[180:183], v247 offset:56320
	v_mfma_f32_16x16x32_bf16 v[48:51], v[216:219], v[188:191], v[48:51]
	v_mfma_f32_16x16x32_bf16 v[52:55], v[220:223], v[188:191], v[52:55]
	v_mfma_f32_16x16x32_bf16 v[56:59], v[228:231], v[188:191], v[56:59]
	v_mfma_f32_16x16x32_bf16 v[60:63], v[232:235], v[188:191], v[60:63]
	v_mfma_f32_16x16x32_bf16 v[64:67], v[200:203], v[192:195], v[64:67]
	v_mfma_f32_16x16x32_bf16 v[68:71], v[204:207], v[192:195], v[68:71]
	v_mfma_f32_16x16x32_bf16 v[72:75], v[208:211], v[192:195], v[72:75]
	v_mfma_f32_16x16x32_bf16 v[76:79], v[212:215], v[192:195], v[76:79]
	v_mfma_f32_16x16x32_bf16 v[80:83], v[216:219], v[192:195], v[80:83]
	v_mfma_f32_16x16x32_bf16 v[84:87], v[220:223], v[192:195], v[84:87]
	v_mfma_f32_16x16x32_bf16 v[88:91], v[228:231], v[192:195], v[88:91]
	v_mfma_f32_16x16x32_bf16 v[92:95], v[232:235], v[192:195], v[92:95]
	v_mfma_f32_16x16x32_bf16 v[96:99], v[200:203], v[196:199], v[96:99]
	v_mfma_f32_16x16x32_bf16 v[100:103], v[204:207], v[196:199], v[100:103]
	v_mfma_f32_16x16x32_bf16 v[104:107], v[208:211], v[196:199], v[104:107]
	v_mfma_f32_16x16x32_bf16 v[108:111], v[212:215], v[196:199], v[108:111]
	v_mfma_f32_16x16x32_bf16 v[112:115], v[216:219], v[196:199], v[112:115]
	v_mfma_f32_16x16x32_bf16 v[116:119], v[220:223], v[196:199], v[116:119]
	v_mfma_f32_16x16x32_bf16 v[120:123], v[228:231], v[196:199], v[120:123]
	v_mfma_f32_16x16x32_bf16 v[124:127], v[232:235], v[196:199], v[124:127]
	s_waitcnt vmcnt(0) lgkmcnt(0)
	s_barrier
	s_nop 15
	s_nop 15
	s_mul_i32 s40, s0, 3
	s_lshr_b32 s41, s32, 13
	s_add_u32 s40, s40, s41
	s_mul_i32 s40, s40, 6144
	s_add_u32 s40, s40, s28
	s_add_u32 s40, s40, 5120
	s_lshl_b32 s40, s40, 2
	s_add_u32 s56, s26, s40
	s_addc_u32 s57, s27, 0
	s_lshl_b32 s40, s32, 12
	s_lshl_b32 s41, s28, 2
	s_add_u32 s40, s40, s41
	s_add_u32 s54, s22, s40
	s_addc_u32 s55, s23, 0
	global_load_dwordx4 v[148:151], v249, s[56:57] offset:0
	global_load_dwordx4 v[152:155], v249, s[56:57] offset:64
	global_load_dwordx4 v[156:159], v249, s[56:57] offset:128
	global_load_dwordx4 v[160:163], v249, s[56:57] offset:192
	global_load_dwordx4 v[168:171], v249, s[56:57] offset:256
	global_load_dwordx4 v[172:175], v249, s[56:57] offset:320
	global_load_dwordx4 v[176:179], v249, s[56:57] offset:384
	global_load_dwordx4 v[180:183], v249, s[56:57] offset:448
	global_load_dwordx4 v[200:203], v248, s[54:55] offset:0
	global_load_dwordx4 v[204:207], v248, s[54:55] offset:64
	global_load_dwordx4 v[208:211], v248, s[54:55] offset:128
	global_load_dwordx4 v[212:215], v248, s[54:55] offset:192
	global_load_dwordx4 v[216:219], v248, s[54:55] offset:256
	global_load_dwordx4 v[220:223], v248, s[54:55] offset:320
	global_load_dwordx4 v[228:231], v248, s[54:55] offset:384
	global_load_dwordx4 v[232:235], v248, s[54:55] offset:448
	s_add_u32 s54, s54, 0x10000
	s_addc_u32 s55, s55, 0
	global_load_dwordx4 v[128:131], v248, s[54:55] offset:0
	global_load_dwordx4 v[132:135], v248, s[54:55] offset:64
	global_load_dwordx4 v[136:139], v248, s[54:55] offset:128
	global_load_dwordx4 v[140:143], v248, s[54:55] offset:192
	global_load_dwordx4 v[184:187], v248, s[54:55] offset:256
	global_load_dwordx4 v[188:191], v248, s[54:55] offset:320
	global_load_dwordx4 v[192:195], v248, s[54:55] offset:384
	global_load_dwordx4 v[196:199], v248, s[54:55] offset:448
	s_sub_u32 s54, s54, 0x10000
	s_subb_u32 s55, s55, 0
	s_waitcnt vmcnt(8)
; __device__ void phase_proj_res(CParams& p, int l, int tm, int tn, char* smem, const bf16_t* A, int K,
;                                const bf16_t* Bt, int gate_off, float gscale) {
;     ...
;   EPI_LOOP({
;     float* xp = xrow(p, row0 + rl) + col0 + cl;
;     *xp = *xp + gscale * md[col0 + cl] * acc[mi][ni][j];
;   })
	v_fmac_f32_e32 v200, v148, v0
	v_fmac_f32_e32 v201, v149, v1
	v_fmac_f32_e32 v202, v150, v2
	v_fmac_f32_e32 v203, v151, v3
	v_fmac_f32_e32 v204, v152, v4
	v_fmac_f32_e32 v205, v153, v5
	v_fmac_f32_e32 v206, v154, v6
	v_fmac_f32_e32 v207, v155, v7
	v_fmac_f32_e32 v208, v156, v8
	v_fmac_f32_e32 v209, v157, v9
	v_fmac_f32_e32 v210, v158, v10
	v_fmac_f32_e32 v211, v159, v11
	v_fmac_f32_e32 v212, v160, v12
	v_fmac_f32_e32 v213, v161, v13
	v_fmac_f32_e32 v214, v162, v14
	v_fmac_f32_e32 v215, v163, v15
	v_fmac_f32_e32 v216, v168, v16
	v_fmac_f32_e32 v217, v169, v17
	v_fmac_f32_e32 v218, v170, v18
	v_fmac_f32_e32 v219, v171, v19
	v_fmac_f32_e32 v220, v172, v20
	v_fmac_f32_e32 v221, v173, v21
	v_fmac_f32_e32 v222, v174, v22
	v_fmac_f32_e32 v223, v175, v23
	v_fmac_f32_e32 v228, v176, v24
	v_fmac_f32_e32 v229, v177, v25
	v_fmac_f32_e32 v230, v178, v26
	v_fmac_f32_e32 v231, v179, v27
	v_fmac_f32_e32 v232, v180, v28
	v_fmac_f32_e32 v233, v181, v29
	v_fmac_f32_e32 v234, v182, v30
	v_fmac_f32_e32 v235, v183, v31
	global_store_dwordx4 v248, v[200:203], s[54:55] offset:0
	global_store_dwordx4 v248, v[204:207], s[54:55] offset:64
	global_store_dwordx4 v248, v[208:211], s[54:55] offset:128
	global_store_dwordx4 v248, v[212:215], s[54:55] offset:192
	global_store_dwordx4 v248, v[216:219], s[54:55] offset:256
	global_store_dwordx4 v248, v[220:223], s[54:55] offset:320
	global_store_dwordx4 v248, v[228:231], s[54:55] offset:384
	global_store_dwordx4 v248, v[232:235], s[54:55] offset:448
	s_add_u32 s54, s54, 0x10000
	s_addc_u32 s55, s55, 0
	s_add_u32 s54, s54, 0x10000
	s_addc_u32 s55, s55, 0
	global_load_dwordx4 v[200:203], v248, s[54:55] offset:0
	global_load_dwordx4 v[204:207], v248, s[54:55] offset:64
	global_load_dwordx4 v[208:211], v248, s[54:55] offset:128
	global_load_dwordx4 v[212:215], v248, s[54:55] offset:192
	global_load_dwordx4 v[216:219], v248, s[54:55] offset:256
	global_load_dwordx4 v[220:223], v248, s[54:55] offset:320
	global_load_dwordx4 v[228:231], v248, s[54:55] offset:384
	global_load_dwordx4 v[232:235], v248, s[54:55] offset:448
	s_sub_u32 s54, s54, 0x10000
	s_subb_u32 s55, s55, 0
	s_waitcnt vmcnt(8)
	v_fmac_f32_e32 v128, v148, v32
	v_fmac_f32_e32 v129, v149, v33
	v_fmac_f32_e32 v130, v150, v34
	v_fmac_f32_e32 v131, v151, v35
	v_fmac_f32_e32 v132, v152, v36
	v_fmac_f32_e32 v133, v153, v37
	v_fmac_f32_e32 v134, v154, v38
	v_fmac_f32_e32 v135, v155, v39
	v_fmac_f32_e32 v136, v156, v40
	v_fmac_f32_e32 v137, v157, v41
	v_fmac_f32_e32 v138, v158, v42
	v_fmac_f32_e32 v139, v159, v43
	v_fmac_f32_e32 v140, v160, v44
	v_fmac_f32_e32 v141, v161, v45
	v_fmac_f32_e32 v142, v162, v46
	v_fmac_f32_e32 v143, v163, v47
	v_fmac_f32_e32 v184, v168, v48
	v_fmac_f32_e32 v185, v169, v49
	v_fmac_f32_e32 v186, v170, v50
	v_fmac_f32_e32 v187, v171, v51
	v_fmac_f32_e32 v188, v172, v52
	v_fmac_f32_e32 v189, v173, v53
	v_fmac_f32_e32 v190, v174, v54
	v_fmac_f32_e32 v191, v175, v55
	v_fmac_f32_e32 v192, v176, v56
	v_fmac_f32_e32 v193, v177, v57
	v_fmac_f32_e32 v194, v178, v58
	v_fmac_f32_e32 v195, v179, v59
	v_fmac_f32_e32 v196, v180, v60
	v_fmac_f32_e32 v197, v181, v61
	v_fmac_f32_e32 v198, v182, v62
	v_fmac_f32_e32 v199, v183, v63
	global_store_dwordx4 v248, v[128:131], s[54:55] offset:0
	global_store_dwordx4 v248, v[132:135], s[54:55] offset:64
	global_store_dwordx4 v248, v[136:139], s[54:55] offset:128
	global_store_dwordx4 v248, v[140:143], s[54:55] offset:192
	global_store_dwordx4 v248, v[184:187], s[54:55] offset:256
	global_store_dwordx4 v248, v[188:191], s[54:55] offset:320
	global_store_dwordx4 v248, v[192:195], s[54:55] offset:384
	global_store_dwordx4 v248, v[196:199], s[54:55] offset:448
	s_add_u32 s54, s54, 0x10000
	s_addc_u32 s55, s55, 0
	s_add_u32 s54, s54, 0x10000
	s_addc_u32 s55, s55, 0
	global_load_dwordx4 v[128:131], v248, s[54:55] offset:0
	global_load_dwordx4 v[132:135], v248, s[54:55] offset:64
	global_load_dwordx4 v[136:139], v248, s[54:55] offset:128
	global_load_dwordx4 v[140:143], v248, s[54:55] offset:192
	global_load_dwordx4 v[184:187], v248, s[54:55] offset:256
	global_load_dwordx4 v[188:191], v248, s[54:55] offset:320
	global_load_dwordx4 v[192:195], v248, s[54:55] offset:384
	global_load_dwordx4 v[196:199], v248, s[54:55] offset:448
	s_sub_u32 s54, s54, 0x10000
	s_subb_u32 s55, s55, 0
	s_waitcnt vmcnt(8)
; __device__ void phase_proj_res(CParams& p, int l, int tm, int tn, char* smem, const bf16_t* A, int K,
;                                const bf16_t* Bt, int gate_off, float gscale) {
;     ...
;   EPI_LOOP({
;     float* xp = xrow(p, row0 + rl) + col0 + cl;
;     *xp = *xp + gscale * md[col0 + cl] * acc[mi][ni][j];
;   })
	v_fmac_f32_e32 v200, v148, v64
	v_fmac_f32_e32 v201, v149, v65
	v_fmac_f32_e32 v202, v150, v66
	v_fmac_f32_e32 v203, v151, v67
	v_fmac_f32_e32 v204, v152, v68
	v_fmac_f32_e32 v205, v153, v69
	v_fmac_f32_e32 v206, v154, v70
	v_fmac_f32_e32 v207, v155, v71
	v_fmac_f32_e32 v208, v156, v72
	v_fmac_f32_e32 v209, v157, v73
	v_fmac_f32_e32 v210, v158, v74
	v_fmac_f32_e32 v211, v159, v75
	v_fmac_f32_e32 v212, v160, v76
	v_fmac_f32_e32 v213, v161, v77
	v_fmac_f32_e32 v214, v162, v78
	v_fmac_f32_e32 v215, v163, v79
	v_fmac_f32_e32 v216, v168, v80
	v_fmac_f32_e32 v217, v169, v81
	v_fmac_f32_e32 v218, v170, v82
	v_fmac_f32_e32 v219, v171, v83
	v_fmac_f32_e32 v220, v172, v84
	v_fmac_f32_e32 v221, v173, v85
	v_fmac_f32_e32 v222, v174, v86
	v_fmac_f32_e32 v223, v175, v87
	v_fmac_f32_e32 v228, v176, v88
	v_fmac_f32_e32 v229, v177, v89
	v_fmac_f32_e32 v230, v178, v90
	v_fmac_f32_e32 v231, v179, v91
	v_fmac_f32_e32 v232, v180, v92
	v_fmac_f32_e32 v233, v181, v93
	v_fmac_f32_e32 v234, v182, v94
	v_fmac_f32_e32 v235, v183, v95
	global_store_dwordx4 v248, v[200:203], s[54:55] offset:0
	global_store_dwordx4 v248, v[204:207], s[54:55] offset:64
	global_store_dwordx4 v248, v[208:211], s[54:55] offset:128
	global_store_dwordx4 v248, v[212:215], s[54:55] offset:192
	global_store_dwordx4 v248, v[216:219], s[54:55] offset:256
	global_store_dwordx4 v248, v[220:223], s[54:55] offset:320
	global_store_dwordx4 v248, v[228:231], s[54:55] offset:384
	global_store_dwordx4 v248, v[232:235], s[54:55] offset:448
	s_add_u32 s54, s54, 0x10000
	s_addc_u32 s55, s55, 0
	s_waitcnt vmcnt(0)
	v_fmac_f32_e32 v128, v148, v96
	v_fmac_f32_e32 v129, v149, v97
	v_fmac_f32_e32 v130, v150, v98
	v_fmac_f32_e32 v131, v151, v99
	v_fmac_f32_e32 v132, v152, v100
	v_fmac_f32_e32 v133, v153, v101
	v_fmac_f32_e32 v134, v154, v102
	v_fmac_f32_e32 v135, v155, v103
	v_fmac_f32_e32 v136, v156, v104
	v_fmac_f32_e32 v137, v157, v105
	v_fmac_f32_e32 v138, v158, v106
	v_fmac_f32_e32 v139, v159, v107
	v_fmac_f32_e32 v140, v160, v108
	v_fmac_f32_e32 v141, v161, v109
	v_fmac_f32_e32 v142, v162, v110
	v_fmac_f32_e32 v143, v163, v111
	v_fmac_f32_e32 v184, v168, v112
	v_fmac_f32_e32 v185, v169, v113
	v_fmac_f32_e32 v186, v170, v114
	v_fmac_f32_e32 v187, v171, v115
	v_fmac_f32_e32 v188, v172, v116
	v_fmac_f32_e32 v189, v173, v117
	v_fmac_f32_e32 v190, v174, v118
	v_fmac_f32_e32 v191, v175, v119
	v_fmac_f32_e32 v192, v176, v120
	v_fmac_f32_e32 v193, v177, v121
	v_fmac_f32_e32 v194, v178, v122
	v_fmac_f32_e32 v195, v179, v123
	v_fmac_f32_e32 v196, v180, v124
	v_fmac_f32_e32 v197, v181, v125
	v_fmac_f32_e32 v198, v182, v126
	v_fmac_f32_e32 v199, v183, v127
	global_store_dwordx4 v248, v[128:131], s[54:55] offset:0
	global_store_dwordx4 v248, v[132:135], s[54:55] offset:64
	global_store_dwordx4 v248, v[136:139], s[54:55] offset:128
	global_store_dwordx4 v248, v[140:143], s[54:55] offset:192
	global_store_dwordx4 v248, v[184:187], s[54:55] offset:256
	global_store_dwordx4 v248, v[188:191], s[54:55] offset:320
	global_store_dwordx4 v248, v[192:195], s[54:55] offset:384
	global_store_dwordx4 v248, v[196:199], s[54:55] offset:448
	s_waitcnt vmcnt(0) lgkmcnt(0)
	s_barrier
	ds_write_b128 v145, v[236:239] offset:40960
	s_waitcnt lgkmcnt(0)
	s_barrier
	s_mov_b64 s[50:51], 0
